# full-line (8 rows x 128B) LDS-DMA stage image in all 8 GEMM loops
# baseline (speedup 1.0000x reference)
.LBB0_140:
	s_or_b64 exec, exec, s[0:1]
	s_add_u32 s96, s92, 0xfd00000
	s_addc_u32 s97, s93, 0
	s_add_u32 s80, s92, 0xbd00000
	s_addc_u32 s81, s93, 0
	v_lshlrev_b32_e32 v0, 6, v222
	v_lshlrev_b32_e32 v239, 2, v222
	s_ashr_i32 s77, s2, 31
	v_readfirstlane_b32 s3, v222
	v_and_b32_e32 v163, 15, v222
	v_and_b32_e32 v155, 0x3c0, v0
	v_and_b32_e32 v152, 32, v239
	s_cmpk_gt_i32 s2, 0x5ff
	v_bfe_u32 v157, v222, 2, 2
	v_bfe_u32 v218, v222, 2, 4
	v_lshrrev_b32_e32 v238, 5, v222
	v_lshrrev_b32_e32 v158, 1, v222
	v_lshlrev_b32_e32 v156, 4, v222
	v_and_b32_e32 v159, 32, v222
	v_and_b32_e32 v224, 64, v222
	v_lshrrev_b32_e32 v153, 3, v222
	s_cbranch_scc1 .LBB0_152
	v_and_b32_e32 v0, 4, v238
	s_waitcnt vmcnt(4)
	v_and_b32_e32 v10, 24, v158
	v_add_u32_e32 v8, 0x2000, v156
	v_or3_b32 v0, v0, v157, v10
	v_lshrrev_b32_e32 v1, 7, v8
	s_movk_i32 s0, 0xe0
	v_and_or_b32 v2, v1, s0, v0
	s_movk_i32 s0, 0xf0
	v_bitop3_b32 v9, v156, v159, 48 bitop3:0x6c
	v_and_or_b32 v1, v1, s0, v218
	s_movk_i32 s0, 0x60
	s_add_u32 s22, s92, 0x100000
	v_or_b32_e32 v3, v9, v224
	v_and_or_b32 v0, v153, s0, v0
	s_movk_i32 s0, 0x70
	s_addc_u32 s23, s93, 0
	v_lshl_or_b32 v132, v0, 12, v3
	v_and_or_b32 v0, v153, s0, v218
	s_lshr_b32 s0, s77, 29
	s_add_i32 s0, s2, s0
	s_lshr_b32 s6, s3, 6
	s_ashr_i32 s1, s0, 3
	s_and_b32 s0, s0, -8
	s_lshr_b32 s5, s3, 8
	s_lshl_b32 s24, s6, 10
	s_sub_i32 s0, s2, s0
	s_cmp_lt_i32 s0, 0
	s_movk_i32 s25, 0xc1
	s_cselect_b32 s4, s25, 0xc0
	s_mul_i32 s0, s4, s0
	s_add_i32 s0, s0, s1
	s_mul_hi_i32 s1, s0, 0x2aaaaaab
	s_lshr_b32 s4, s1, 31
	s_ashr_i32 s1, s1, 4
	s_add_i32 s1, s1, s4
	s_lshl_b32 s7, s1, 2
	s_mulk_i32 s1, 0x60
	s_sub_i32 s0, s0, s1
	s_bfe_i32 s1, s0, 0x80000
	s_bfe_u32 s1, s1, 0x2000d
	s_add_i32 s1, s0, s1
	s_bfe_i32 s4, s1, 0x80000
	s_and_b32 s1, s1, 0xfc
	s_sub_i32 s0, s0, s1
	s_sext_i32_i16 s4, s4
	s_sext_i32_i8 s0, s0
	s_lshr_b32 s4, s4, 2
	s_add_i32 s0, s7, s0
	s_ashr_i32 s1, s0, 31
	s_bfe_i64 s[10:11], s[4:5], 0x100000
	s_lshl_b64 s[8:9], s[0:1], 20
	s_lshl_b64 s[10:11], s[10:11], 20
	s_add_u32 s18, s22, s10
	s_addc_u32 s19, s23, s11
	s_add_i32 s1, s24, 0
	s_add_i32 m0, s1, 0x10000
	v_lshl_or_b32 v128, v2, 12, v3
	v_and_b32_e32 v144, 63, v222
	v_lshrrev_b32_e32 v145, 3, v144
	v_lshrrev_b32_e32 v146, 6, v222
	v_lshl_add_u32 v147, v146, 3, v145
	v_and_b32_e32 v148, 7, v144
	v_and_b32_e32 v149, 6, v145
	v_xor_b32_e32 v148, v148, v149
	v_lshlrev_b32_e32 v148, 4, v148
	v_mul_u32_u24_e32 v149, 0x1000, v147
	v_add_u32_e32 v149, v149, v148
	v_mov_b32_e32 v134, v149
	v_add_u32_e32 v130, 0x40000, v149
	v_mov_b32_e32 v136, v149
	v_add_u32_e32 v138, 0x40000, v149
	v_add_u32_e32 v130, 0x40000, v149
	v_add_u32_e32 v138, 0x40000, v149
	v_and_b32_e32 v149, 31, v147
	v_and_b32_e32 v150, 12, v149
	v_lshlrev_b32_e32 v150, 1, v150
	v_lshrrev_b32_e32 v151, 4, v149
	v_lshlrev_b32_e32 v151, 2, v151
	v_and_b32_e32 v149, 3, v149
	v_or3_b32 v149, v150, v151, v149
	v_and_b32_e32 v150, 0x60, v147
	v_add_u32_e32 v149, v149, v150
	v_mul_u32_u24_e32 v149, 0x1000, v149
	v_add_u32_e32 v149, v149, v148
	v_mov_b32_e32 v132, v149
	v_add_u32_e32 v128, 0x40000, v149
	v_add_u32_e32 v128, 0x40000, v149
	v_and_b32_e32 v149, 15, v144
	v_lshrrev_b32_e32 v150, 4, v144
	v_and_b32_e32 v151, 6, v149
	v_xor_b32_e32 v150, v150, v151
	v_lshlrev_b32_e32 v150, 4, v150
	v_lshl_or_b32 v150, v149, 7, v150
	v_lshrrev_b32_e32 v151, 2, v146
	v_lshl_add_u32 v151, v151, 13, v150
	v_add_u32_e32 v166, 0x0, v151
	v_and_b32_e32 v149, 3, v146
	v_lshl_add_u32 v149, v149, 12, v150
	v_add_u32_e32 v161, 0x0, v149
	v_add_u32_e32 v165, 0x10000, v149
	v_add_u32_e32 v167, 0x14000, v149
	global_load_lds_dwordx4 v132, s[18:19]
	s_add_i32 m0, s1, 0x12000
	s_add_u32 s16, s80, s8
	global_load_lds_dwordx4 v128, s[18:19]
	s_addc_u32 s17, s81, s9
	s_mov_b32 m0, s1
	s_add_i32 s26, s1, 0x2000
	global_load_lds_dwordx4 v134, s[16:17]
	s_mov_b32 m0, s26
	s_add_u32 s8, s18, 0x80000
	global_load_lds_dwordx4 v130, s[16:17]
	s_addc_u32 s9, s19, 0
	s_add_i32 m0, s1, 0x14000
	v_mov_b32_e32 v133, 0
	global_load_lds_dwordx4 v132, s[8:9]
	s_add_i32 m0, s1, 0x16000
	v_mov_b32_e32 v129, v133
	global_load_lds_dwordx4 v128, s[8:9]
	s_add_u32 s8, s16, 0x80000
	s_addc_u32 s9, s17, 0
	s_add_i32 s27, s1, 0x4000
	s_mov_b32 m0, s27
	s_add_i32 s28, s1, 0x6000
	global_load_lds_dwordx4 v134, s[8:9]
	s_mov_b32 m0, s28
	v_mov_b32_e32 v135, v133
	global_load_lds_dwordx4 v130, s[8:9]
	v_mov_b32_e32 v131, v133
	s_mov_b32 s29, 0
	v_lshl_add_u64 v[6:7], s[18:19], 0, v[132:133]
	v_lshl_add_u64 v[4:5], s[18:19], 0, v[128:129]
	v_lshl_add_u64 v[2:3], s[16:17], 0, v[134:135]
	s_cmp_lg_u32 s5, 1
	v_lshl_add_u64 v[0:1], s[16:17], 0, v[130:131]
	s_cbranch_scc1 .LBB0_143
	s_barrier
.LBB0_143:
	s_lshl_b32 s6, s6, 5
	s_and_b32 s11, s6, 0x60
	s_mov_b64 s[6:7], 0x80
	s_add_i32 m0, s1, 0x18000
	v_lshl_add_u64 v[6:7], v[6:7], 0, s[6:7]
	s_lshl_b32 s10, s5, 13
	s_lshl_b32 s12, s11, 7
	s_waitcnt vmcnt(4)
	s_barrier
	global_load_lds_dwordx4 v[6:7], off
	v_lshl_add_u64 v[4:5], v[4:5], 0, s[6:7]
	s_add_i32 m0, s1, 0x1a000
	s_add_i32 s30, s1, 0x8000
	s_add_i32 s31, s1, 0xa000
	global_load_lds_dwordx4 v[4:5], off
	v_lshl_add_u64 v[2:3], v[2:3], 0, s[6:7]
	s_mov_b32 m0, s30
	s_add_u32 s8, s18, 0x80080
	global_load_lds_dwordx4 v[2:3], off
	v_lshl_add_u64 v[0:1], v[0:1], 0, s[6:7]
	s_mov_b32 m0, s31
	s_addc_u32 s9, s19, 0
	global_load_lds_dwordx4 v[0:1], off
	s_add_i32 m0, s1, 0x1c000
	v_lshl_add_u64 v[0:1], s[8:9], 0, v[132:133]
	global_load_lds_dwordx4 v[0:1], off
	v_lshl_add_u64 v[0:1], s[8:9], 0, v[128:129]
	s_add_i32 m0, s1, 0x1e000
	v_lshlrev_b32_e32 v2, 2, v163
	global_load_lds_dwordx4 v[0:1], off
	v_lshlrev_b32_e32 v0, 1, v10
	v_lshl_or_b32 v1, v163, 6, v0
	v_or_b32_e32 v0, v0, v155
	v_and_b32_e32 v2, 32, v2
	v_lshlrev_b32_e32 v0, 9, v222
	v_bitop3_b32 v1, v1, s10, v2 bitop3:0xde
	v_and_b32_e32 v0, 0x70000, v0
	v_lshlrev_b32_e32 v2, 12, v218
	v_or3_b32 v0, v9, v0, v2
	v_lshlrev_b32_e32 v0, 5, v8
	s_waitcnt vmcnt(6)
	v_and_b32_e32 v0, 0xf0000, v0
	v_or3_b32 v0, v9, v0, v2
	s_add_i32 s35, 0, 0x10000
	s_add_i32 s38, 0, 0x14000
	s_sext_i32_i8 s40, s4
	v_lshl_or_b32 v160, s5, 6, v163
	s_ashr_i32 s33, s94, 31
	s_mov_b32 s34, s94
	v_or_b32_e32 v164, s11, v10
	v_mov_b32_e32 v137, v133
	v_mov_b32_e32 v139, v133
	v_mov_b64_e32 v[140:141], 0x600
	v_mov_b64_e32 v[142:143], 0x5ff
	v_mov_b32_e32 v168, 0x3727c5ac
	s_movk_i32 s39, 0x3000
	s_barrier

.LBB0_147:
	ds_read_b128 v[144:147], v165
	v_xor_b32_e32 v177, 64, v165
	ds_read_b128 v[148:151], v177
	ds_read_b128 v[170:173], v165 offset:2048
	ds_read_b128 v[174:177], v177 offset:2048
	s_add_u32 s18, s16, 0xfff80080
	s_addc_u32 s19, s17, -1
	s_cmp_eq_u32 s47, 28
	s_cselect_b32 s21, s11, s19
	s_cselect_b32 s20, s41, s18
	s_cselect_b32 s19, s9, s46
	s_cselect_b32 s18, s44, s45
	v_lshl_add_u64 v[210:211], s[16:17], 0, v[136:137]
	s_add_i32 m0, s1, 0xc000
	ds_read_b128 v[178:181], v166
	v_xor_b32_e32 v209, 64, v166
	ds_read_b128 v[182:185], v209
	ds_read_b128 v[186:189], v166 offset:2048
	ds_read_b128 v[190:193], v209 offset:2048
	ds_read_b128 v[194:197], v166 offset:4096
	ds_read_b128 v[198:201], v209 offset:4096
	ds_read_b128 v[202:205], v166 offset:6144
	ds_read_b128 v[206:209], v209 offset:6144
	global_load_lds_dwordx4 v[210:211], off
	v_lshl_add_u64 v[210:211], s[16:17], 0, v[138:139]
	s_add_i32 m0, s1, 0xe000
	s_nop 0
	global_load_lds_dwordx4 v[210:211], off
	s_waitcnt lgkmcnt(8)
	s_barrier
	s_waitcnt lgkmcnt(0)
	s_setprio 1
	s_waitcnt lgkmcnt(0)
	v_mfma_f32_16x16x32_bf16 v[124:127], v[144:147], v[178:181], v[124:127]
	v_mfma_f32_16x16x32_bf16 v[120:123], v[170:173], v[178:181], v[120:123]
	v_mfma_f32_16x16x32_bf16 v[108:111], v[144:147], v[186:189], v[108:111]
	v_mfma_f32_16x16x32_bf16 v[104:107], v[170:173], v[186:189], v[104:107]
	v_mfma_f32_16x16x32_bf16 v[92:95], v[144:147], v[194:197], v[92:95]
	v_mfma_f32_16x16x32_bf16 v[88:91], v[170:173], v[194:197], v[88:91]
	v_mfma_f32_16x16x32_bf16 v[76:79], v[144:147], v[202:205], v[76:79]
	v_mfma_f32_16x16x32_bf16 v[72:75], v[170:173], v[202:205], v[72:75]
	v_mfma_f32_16x16x32_bf16 v[124:127], v[148:151], v[182:185], v[124:127]
	v_mfma_f32_16x16x32_bf16 v[120:123], v[174:177], v[182:185], v[120:123]
	v_mfma_f32_16x16x32_bf16 v[108:111], v[148:151], v[190:193], v[108:111]
	v_mfma_f32_16x16x32_bf16 v[104:107], v[174:177], v[190:193], v[104:107]
	v_mfma_f32_16x16x32_bf16 v[92:95], v[148:151], v[198:201], v[92:95]
	v_mfma_f32_16x16x32_bf16 v[88:91], v[174:177], v[198:201], v[88:91]
	v_mfma_f32_16x16x32_bf16 v[76:79], v[148:151], v[206:209], v[76:79]
	v_mfma_f32_16x16x32_bf16 v[72:75], v[174:177], v[206:209], v[72:75]
	s_setprio 0
	s_barrier
	s_add_i32 s48, s35, s24
	v_lshl_add_u64 v[220:221], s[18:19], 0, v[132:133]
	s_mov_b32 m0, s48
	ds_read_b128 v[210:213], v167
	v_xor_b32_e32 v233, 64, v167
	ds_read_b128 v[214:217], v233
	ds_read_b128 v[226:229], v167 offset:2048
	ds_read_b128 v[230:233], v233 offset:2048
	global_load_lds_dwordx4 v[220:221], off
	v_lshl_add_u64 v[234:235], s[18:19], 0, v[128:129]
	s_add_i32 m0, s48, 0x2000
	s_nop 0
	global_load_lds_dwordx4 v[234:235], off
	s_barrier
	s_waitcnt lgkmcnt(0)
	s_setprio 1
	s_waitcnt lgkmcnt(0)
	v_mfma_f32_16x16x32_bf16 v[116:119], v[210:213], v[178:181], v[116:119]
	v_mfma_f32_16x16x32_bf16 v[112:115], v[226:229], v[178:181], v[112:115]
	v_mfma_f32_16x16x32_bf16 v[100:103], v[210:213], v[186:189], v[100:103]
	v_mfma_f32_16x16x32_bf16 v[96:99], v[226:229], v[186:189], v[96:99]
	v_mfma_f32_16x16x32_bf16 v[84:87], v[210:213], v[194:197], v[84:87]
	v_mfma_f32_16x16x32_bf16 v[80:83], v[226:229], v[194:197], v[80:83]
	v_mfma_f32_16x16x32_bf16 v[68:71], v[210:213], v[202:205], v[68:71]
	v_mfma_f32_16x16x32_bf16 v[64:67], v[226:229], v[202:205], v[64:67]
	v_mfma_f32_16x16x32_bf16 v[116:119], v[214:217], v[182:185], v[116:119]
	v_mfma_f32_16x16x32_bf16 v[112:115], v[230:233], v[182:185], v[112:115]
	v_mfma_f32_16x16x32_bf16 v[100:103], v[214:217], v[190:193], v[100:103]
	v_mfma_f32_16x16x32_bf16 v[96:99], v[230:233], v[190:193], v[96:99]
	v_mfma_f32_16x16x32_bf16 v[84:87], v[214:217], v[198:201], v[84:87]
	v_mfma_f32_16x16x32_bf16 v[80:83], v[230:233], v[198:201], v[80:83]
	v_mfma_f32_16x16x32_bf16 v[68:71], v[214:217], v[206:209], v[68:71]
	v_mfma_f32_16x16x32_bf16 v[64:67], v[230:233], v[206:209], v[64:67]
	s_setprio 0
	s_mov_b32 m0, s1
	v_lshl_add_u64 v[236:237], s[20:21], 0, v[134:135]
	s_barrier
	ds_read_b128 v[178:181], v166 offset:16384
	v_xor_b32_e32 v209, 64, v166
	ds_read_b128 v[182:185], v209 offset:16384
	ds_read_b128 v[186:189], v166 offset:18432
	ds_read_b128 v[190:193], v209 offset:18432
	ds_read_b128 v[194:197], v166 offset:20480
	ds_read_b128 v[198:201], v209 offset:20480
	ds_read_b128 v[202:205], v166 offset:22528
	ds_read_b128 v[206:209], v209 offset:22528
	global_load_lds_dwordx4 v[236:237], off
	v_lshl_add_u64 v[240:241], s[20:21], 0, v[130:131]
	s_mov_b32 m0, s26
	s_nop 0
	global_load_lds_dwordx4 v[240:241], off
	s_barrier
	s_waitcnt lgkmcnt(0)
	s_setprio 1
	s_waitcnt lgkmcnt(0)
	v_mfma_f32_16x16x32_bf16 v[60:63], v[144:147], v[178:181], v[60:63]
	v_mfma_f32_16x16x32_bf16 v[56:59], v[170:173], v[178:181], v[56:59]
	v_mfma_f32_16x16x32_bf16 v[44:47], v[144:147], v[186:189], v[44:47]
	v_mfma_f32_16x16x32_bf16 v[40:43], v[170:173], v[186:189], v[40:43]
	v_mfma_f32_16x16x32_bf16 v[28:31], v[144:147], v[194:197], v[28:31]
	v_mfma_f32_16x16x32_bf16 v[24:27], v[170:173], v[194:197], v[24:27]
	v_mfma_f32_16x16x32_bf16 v[12:15], v[144:147], v[202:205], v[12:15]
	v_mfma_f32_16x16x32_bf16 v[8:11], v[170:173], v[202:205], v[8:11]
	v_mfma_f32_16x16x32_bf16 v[60:63], v[148:151], v[182:185], v[60:63]
	v_mfma_f32_16x16x32_bf16 v[56:59], v[174:177], v[182:185], v[56:59]
	v_mfma_f32_16x16x32_bf16 v[44:47], v[148:151], v[190:193], v[44:47]
	v_mfma_f32_16x16x32_bf16 v[40:43], v[174:177], v[190:193], v[40:43]
	v_mfma_f32_16x16x32_bf16 v[28:31], v[148:151], v[198:201], v[28:31]
	v_mfma_f32_16x16x32_bf16 v[24:27], v[174:177], v[198:201], v[24:27]
	v_mfma_f32_16x16x32_bf16 v[12:15], v[148:151], v[206:209], v[12:15]
	v_mfma_f32_16x16x32_bf16 v[8:11], v[174:177], v[206:209], v[8:11]
	s_setprio 0
	s_barrier
	s_add_u32 s48, s18, 0x80000
	s_addc_u32 s49, s19, 0
	s_add_i32 s52, s38, s24
	v_lshl_add_u64 v[144:145], s[48:49], 0, v[132:133]
	s_mov_b32 m0, s52
	s_nop 0
	global_load_lds_dwordx4 v[144:145], off
	v_lshl_add_u64 v[144:145], s[48:49], 0, v[128:129]
	s_add_i32 m0, s52, 0x2000
	s_nop 0
	global_load_lds_dwordx4 v[144:145], off
	s_waitcnt vmcnt(6)
	s_barrier
	s_setprio 1
	v_mfma_f32_16x16x32_bf16 v[52:55], v[210:213], v[178:181], v[52:55]
	v_mfma_f32_16x16x32_bf16 v[48:51], v[226:229], v[178:181], v[48:51]
	v_mfma_f32_16x16x32_bf16 v[36:39], v[210:213], v[186:189], v[36:39]
	v_mfma_f32_16x16x32_bf16 v[32:35], v[226:229], v[186:189], v[32:35]
	v_mfma_f32_16x16x32_bf16 v[20:23], v[210:213], v[194:197], v[20:23]
	v_mfma_f32_16x16x32_bf16 v[16:19], v[226:229], v[194:197], v[16:19]
	v_mfma_f32_16x16x32_bf16 v[4:7], v[210:213], v[202:205], v[4:7]
	v_mfma_f32_16x16x32_bf16 v[0:3], v[226:229], v[202:205], v[0:3]
	v_mfma_f32_16x16x32_bf16 v[52:55], v[214:217], v[182:185], v[52:55]
	v_mfma_f32_16x16x32_bf16 v[48:51], v[230:233], v[182:185], v[48:51]
	v_mfma_f32_16x16x32_bf16 v[36:39], v[214:217], v[190:193], v[36:39]
	v_mfma_f32_16x16x32_bf16 v[32:35], v[230:233], v[190:193], v[32:35]
	v_mfma_f32_16x16x32_bf16 v[20:23], v[214:217], v[198:201], v[20:23]
	v_mfma_f32_16x16x32_bf16 v[16:19], v[230:233], v[198:201], v[16:19]
	v_mfma_f32_16x16x32_bf16 v[4:7], v[214:217], v[206:209], v[4:7]
	v_mfma_f32_16x16x32_bf16 v[0:3], v[230:233], v[206:209], v[0:3]
	s_setprio 0
	s_add_i32 s48, 0, 0x18000
	v_add_u32_e32 v169, s48, v161
	s_barrier
	ds_read_b128 v[144:147], v169
	v_xor_b32_e32 v177, 64, v169
	ds_read_b128 v[148:151], v177
	ds_read_b128 v[170:173], v169 offset:2048
	ds_read_b128 v[174:177], v177 offset:2048
	s_add_u32 s20, s20, 0x80000
	s_addc_u32 s21, s21, 0
	s_mov_b32 m0, s27
	v_lshl_add_u64 v[210:211], s[20:21], 0, v[134:135]
	ds_read_b128 v[178:181], v166 offset:32768
	v_xor_b32_e32 v209, 64, v166
	ds_read_b128 v[182:185], v209 offset:32768
	ds_read_b128 v[186:189], v166 offset:34816
	ds_read_b128 v[190:193], v209 offset:34816
	ds_read_b128 v[194:197], v166 offset:36864
	ds_read_b128 v[198:201], v209 offset:36864
	ds_read_b128 v[202:205], v166 offset:38912
	ds_read_b128 v[206:209], v209 offset:38912
	global_load_lds_dwordx4 v[210:211], off
	v_lshl_add_u64 v[210:211], s[20:21], 0, v[130:131]
	s_mov_b32 m0, s28
	s_nop 0
	global_load_lds_dwordx4 v[210:211], off
	s_waitcnt lgkmcnt(8)
	s_barrier
	s_waitcnt lgkmcnt(0)
	s_setprio 1
	s_waitcnt lgkmcnt(0)
	v_mfma_f32_16x16x32_bf16 v[124:127], v[144:147], v[178:181], v[124:127]
	v_mfma_f32_16x16x32_bf16 v[120:123], v[170:173], v[178:181], v[120:123]
	v_mfma_f32_16x16x32_bf16 v[108:111], v[144:147], v[186:189], v[108:111]
	v_mfma_f32_16x16x32_bf16 v[104:107], v[170:173], v[186:189], v[104:107]
	v_mfma_f32_16x16x32_bf16 v[92:95], v[144:147], v[194:197], v[92:95]
	v_mfma_f32_16x16x32_bf16 v[88:91], v[170:173], v[194:197], v[88:91]
	v_mfma_f32_16x16x32_bf16 v[76:79], v[144:147], v[202:205], v[76:79]
	v_mfma_f32_16x16x32_bf16 v[72:75], v[170:173], v[202:205], v[72:75]
	v_mfma_f32_16x16x32_bf16 v[124:127], v[148:151], v[182:185], v[124:127]
	v_mfma_f32_16x16x32_bf16 v[120:123], v[174:177], v[182:185], v[120:123]
	v_mfma_f32_16x16x32_bf16 v[108:111], v[148:151], v[190:193], v[108:111]
	v_mfma_f32_16x16x32_bf16 v[104:107], v[174:177], v[190:193], v[104:107]
	v_mfma_f32_16x16x32_bf16 v[92:95], v[148:151], v[198:201], v[92:95]
	v_mfma_f32_16x16x32_bf16 v[88:91], v[174:177], v[198:201], v[88:91]
	v_mfma_f32_16x16x32_bf16 v[76:79], v[148:151], v[206:209], v[76:79]
	v_mfma_f32_16x16x32_bf16 v[72:75], v[174:177], v[206:209], v[72:75]
	s_setprio 0
	s_barrier
	s_add_i32 s20, 0, 0x1c000
	s_add_i32 s21, s48, s24
	v_add_u32_e32 v169, s20, v161
	v_lshl_add_u64 v[220:221], v[220:221], 0, s[6:7]
	s_mov_b32 m0, s21
	ds_read_b128 v[210:213], v169
	v_xor_b32_e32 v233, 64, v169
	ds_read_b128 v[214:217], v233
	ds_read_b128 v[226:229], v169 offset:2048
	ds_read_b128 v[230:233], v233 offset:2048
	global_load_lds_dwordx4 v[220:221], off
	v_lshl_add_u64 v[220:221], v[234:235], 0, s[6:7]
	s_add_i32 m0, s21, 0x2000
	s_nop 0
	global_load_lds_dwordx4 v[220:221], off
	s_barrier
	s_waitcnt lgkmcnt(0)
	s_setprio 1
	s_waitcnt lgkmcnt(0)
	v_mfma_f32_16x16x32_bf16 v[116:119], v[210:213], v[178:181], v[116:119]
	v_mfma_f32_16x16x32_bf16 v[112:115], v[226:229], v[178:181], v[112:115]
	v_mfma_f32_16x16x32_bf16 v[100:103], v[210:213], v[186:189], v[100:103]
	v_mfma_f32_16x16x32_bf16 v[96:99], v[226:229], v[186:189], v[96:99]
	v_mfma_f32_16x16x32_bf16 v[84:87], v[210:213], v[194:197], v[84:87]
	v_mfma_f32_16x16x32_bf16 v[80:83], v[226:229], v[194:197], v[80:83]
	v_mfma_f32_16x16x32_bf16 v[68:71], v[210:213], v[202:205], v[68:71]
	v_mfma_f32_16x16x32_bf16 v[64:67], v[226:229], v[202:205], v[64:67]
	v_mfma_f32_16x16x32_bf16 v[116:119], v[214:217], v[182:185], v[116:119]
	v_mfma_f32_16x16x32_bf16 v[112:115], v[230:233], v[182:185], v[112:115]
	v_mfma_f32_16x16x32_bf16 v[100:103], v[214:217], v[190:193], v[100:103]
	v_mfma_f32_16x16x32_bf16 v[96:99], v[230:233], v[190:193], v[96:99]
	v_mfma_f32_16x16x32_bf16 v[84:87], v[214:217], v[198:201], v[84:87]
	v_mfma_f32_16x16x32_bf16 v[80:83], v[230:233], v[198:201], v[80:83]
	v_mfma_f32_16x16x32_bf16 v[68:71], v[214:217], v[206:209], v[68:71]
	v_mfma_f32_16x16x32_bf16 v[64:67], v[230:233], v[206:209], v[64:67]
	s_setprio 0
	s_mov_b32 m0, s30
	v_lshl_add_u64 v[220:221], v[236:237], 0, s[6:7]
	s_barrier
	ds_read_b128 v[178:181], v166 offset:49152
	v_xor_b32_e32 v209, 64, v166
	ds_read_b128 v[182:185], v209 offset:49152
	ds_read_b128 v[186:189], v166 offset:51200
	ds_read_b128 v[190:193], v209 offset:51200
	ds_read_b128 v[194:197], v166 offset:53248
	ds_read_b128 v[198:201], v209 offset:53248
	ds_read_b128 v[202:205], v166 offset:55296
	ds_read_b128 v[206:209], v209 offset:55296
	global_load_lds_dwordx4 v[220:221], off
	v_lshl_add_u64 v[220:221], v[240:241], 0, s[6:7]
	s_mov_b32 m0, s31
	s_nop 0
	global_load_lds_dwordx4 v[220:221], off
	s_barrier
	s_waitcnt lgkmcnt(0)
	s_setprio 1
	s_waitcnt lgkmcnt(0)
	v_mfma_f32_16x16x32_bf16 v[60:63], v[144:147], v[178:181], v[60:63]
	v_mfma_f32_16x16x32_bf16 v[56:59], v[170:173], v[178:181], v[56:59]
	v_mfma_f32_16x16x32_bf16 v[44:47], v[144:147], v[186:189], v[44:47]
	v_mfma_f32_16x16x32_bf16 v[40:43], v[170:173], v[186:189], v[40:43]
	v_mfma_f32_16x16x32_bf16 v[28:31], v[144:147], v[194:197], v[28:31]
	v_mfma_f32_16x16x32_bf16 v[24:27], v[170:173], v[194:197], v[24:27]
	v_mfma_f32_16x16x32_bf16 v[12:15], v[144:147], v[202:205], v[12:15]
	v_mfma_f32_16x16x32_bf16 v[8:11], v[170:173], v[202:205], v[8:11]
	v_mfma_f32_16x16x32_bf16 v[60:63], v[148:151], v[182:185], v[60:63]
	v_mfma_f32_16x16x32_bf16 v[56:59], v[174:177], v[182:185], v[56:59]
	v_mfma_f32_16x16x32_bf16 v[44:47], v[148:151], v[190:193], v[44:47]
	v_mfma_f32_16x16x32_bf16 v[40:43], v[174:177], v[190:193], v[40:43]
	v_mfma_f32_16x16x32_bf16 v[28:31], v[148:151], v[198:201], v[28:31]
	v_mfma_f32_16x16x32_bf16 v[24:27], v[174:177], v[198:201], v[24:27]
	v_mfma_f32_16x16x32_bf16 v[12:15], v[148:151], v[206:209], v[12:15]
	v_mfma_f32_16x16x32_bf16 v[8:11], v[174:177], v[206:209], v[8:11]
	s_setprio 0
	s_barrier
	s_add_u32 s18, s18, 0x80080
	s_addc_u32 s19, s19, 0
	s_add_i32 s20, s20, s24
	v_lshl_add_u64 v[144:145], s[18:19], 0, v[132:133]
	s_mov_b32 m0, s20
	s_nop 0
	global_load_lds_dwordx4 v[144:145], off
	v_lshl_add_u64 v[144:145], s[18:19], 0, v[128:129]
	s_add_i32 m0, s20, 0x2000
	s_nop 0
	global_load_lds_dwordx4 v[144:145], off
	s_waitcnt vmcnt(6)
	s_barrier
	s_setprio 1
	v_mfma_f32_16x16x32_bf16 v[52:55], v[210:213], v[178:181], v[52:55]
	v_mfma_f32_16x16x32_bf16 v[48:51], v[226:229], v[178:181], v[48:51]
	v_mfma_f32_16x16x32_bf16 v[36:39], v[210:213], v[186:189], v[36:39]
	v_mfma_f32_16x16x32_bf16 v[32:35], v[226:229], v[186:189], v[32:35]
	v_mfma_f32_16x16x32_bf16 v[20:23], v[210:213], v[194:197], v[20:23]
	v_mfma_f32_16x16x32_bf16 v[16:19], v[226:229], v[194:197], v[16:19]
	v_mfma_f32_16x16x32_bf16 v[4:7], v[210:213], v[202:205], v[4:7]
	v_mfma_f32_16x16x32_bf16 v[0:3], v[226:229], v[202:205], v[0:3]
	v_mfma_f32_16x16x32_bf16 v[52:55], v[214:217], v[182:185], v[52:55]
	v_mfma_f32_16x16x32_bf16 v[48:51], v[230:233], v[182:185], v[48:51]
	v_mfma_f32_16x16x32_bf16 v[36:39], v[214:217], v[190:193], v[36:39]
	v_mfma_f32_16x16x32_bf16 v[32:35], v[230:233], v[190:193], v[32:35]
	v_mfma_f32_16x16x32_bf16 v[20:23], v[214:217], v[198:201], v[20:23]
	v_mfma_f32_16x16x32_bf16 v[16:19], v[230:233], v[198:201], v[16:19]
	v_mfma_f32_16x16x32_bf16 v[4:7], v[214:217], v[206:209], v[4:7]
	v_mfma_f32_16x16x32_bf16 v[0:3], v[230:233], v[206:209], v[0:3]
	s_setprio 0
	s_add_i32 s47, s47, 2
	s_add_u32 s16, s16, 0x100
	s_addc_u32 s17, s17, 0
	s_add_u32 s45, s45, 0x100
	s_addc_u32 s46, s46, 0
	s_cmp_gt_u32 s47, 29
	s_barrier
	s_cbranch_scc0 .LBB0_147
	v_lshl_add_u32 v144, s0, 8, v160
	v_ashrrev_i32_e32 v145, 31, v144
	v_lshl_add_u64 v[150:151], v[144:145], 2, s[92:93]
	global_load_dword v145, v[150:151], off
	v_lshl_or_b32 v148, s40, 8, v164
	v_mov_b64_e32 v[146:147], s[96:97]
	v_ashrrev_i32_e32 v149, 31, v148
	v_mad_i64_i32 v[172:173], s[16:17], v144, s39, v[146:147]
	v_lshlrev_b64 v[148:149], 1, v[148:149]
	v_lshl_add_u64 v[172:173], v[172:173], 0, v[148:149]
	s_and_b64 vcc, exec, s[4:5]
	s_mov_b32 s40, s8
	s_mov_b32 s0, s10
	s_mov_b64 s[18:19], s[14:15]
	s_waitcnt vmcnt(0)
	v_fmamk_f32 v145, v145, 0x3a000000, v168
	v_rsq_f32_e32 v170, v145
	s_nop 0
	v_pk_mul_f32 v[126:127], v[126:127], v[170:171] op_sel_hi:[1,0]
	v_pk_mul_f32 v[124:125], v[124:125], v[170:171] op_sel_hi:[1,0]
	v_pk_mul_f32 v[122:123], v[122:123], v[170:171] op_sel_hi:[1,0]
	v_pk_mul_f32 v[120:121], v[120:121], v[170:171] op_sel_hi:[1,0]
	v_pk_mul_f32 v[118:119], v[118:119], v[170:171] op_sel_hi:[1,0]
	v_pk_mul_f32 v[116:117], v[116:117], v[170:171] op_sel_hi:[1,0]
	v_pk_mul_f32 v[174:175], v[114:115], v[170:171] op_sel_hi:[1,0]
	v_pk_mul_f32 v[170:171], v[112:113], v[170:171] op_sel_hi:[1,0]
	v_cvt_pk_bf16_f32 v112, v124, v125
	v_cvt_pk_bf16_f32 v113, v126, v127
	v_cvt_pk_bf16_f32 v114, v120, v121
	v_cvt_pk_bf16_f32 v115, v122, v123
	global_store_dwordx4 v[172:173], v[112:115], off
	s_nop 1
	v_cvt_pk_bf16_f32 v112, v116, v117
	v_cvt_pk_bf16_f32 v113, v118, v119
	v_cvt_pk_bf16_f32 v114, v170, v171
	v_cvt_pk_bf16_f32 v115, v174, v175
	global_store_dwordx4 v[172:173], v[112:115], off offset:256
	global_load_dword v112, v[150:151], off offset:64
	s_nop 0
	v_or_b32_e32 v113, 16, v144
	v_mad_i64_i32 v[114:115], s[16:17], v113, s39, v[146:147]
	v_lshl_add_u64 v[114:115], v[114:115], 0, v[148:149]
	s_waitcnt vmcnt(0)
	v_fmamk_f32 v112, v112, 0x3a000000, v168
	v_rsq_f32_e32 v112, v112
	s_nop 0
	v_pk_mul_f32 v[110:111], v[110:111], v[112:113] op_sel_hi:[1,0]
	v_pk_mul_f32 v[108:109], v[108:109], v[112:113] op_sel_hi:[1,0]
	v_pk_mul_f32 v[106:107], v[106:107], v[112:113] op_sel_hi:[1,0]
	v_pk_mul_f32 v[104:105], v[104:105], v[112:113] op_sel_hi:[1,0]
	v_pk_mul_f32 v[102:103], v[102:103], v[112:113] op_sel_hi:[1,0]
	v_pk_mul_f32 v[100:101], v[100:101], v[112:113] op_sel_hi:[1,0]
	v_pk_mul_f32 v[116:117], v[98:99], v[112:113] op_sel_hi:[1,0]
	v_pk_mul_f32 v[112:113], v[96:97], v[112:113] op_sel_hi:[1,0]
	v_cvt_pk_bf16_f32 v96, v108, v109
	v_cvt_pk_bf16_f32 v97, v110, v111
	v_cvt_pk_bf16_f32 v98, v104, v105
	v_cvt_pk_bf16_f32 v99, v106, v107
	global_store_dwordx4 v[114:115], v[96:99], off
	s_nop 1
	v_cvt_pk_bf16_f32 v96, v100, v101
	v_cvt_pk_bf16_f32 v97, v102, v103
	v_cvt_pk_bf16_f32 v98, v112, v113
	v_cvt_pk_bf16_f32 v99, v116, v117
	global_store_dwordx4 v[114:115], v[96:99], off offset:256
	global_load_dword v96, v[150:151], off offset:128
	s_nop 0
	v_or_b32_e32 v97, 32, v144
	v_mad_i64_i32 v[98:99], s[16:17], v97, s39, v[146:147]
	v_lshl_add_u64 v[98:99], v[98:99], 0, v[148:149]
	s_waitcnt vmcnt(0)
	v_fmamk_f32 v96, v96, 0x3a000000, v168
	v_rsq_f32_e32 v96, v96
	s_nop 0
	v_pk_mul_f32 v[94:95], v[94:95], v[96:97] op_sel_hi:[1,0]
	v_pk_mul_f32 v[92:93], v[92:93], v[96:97] op_sel_hi:[1,0]
	v_pk_mul_f32 v[90:91], v[90:91], v[96:97] op_sel_hi:[1,0]
	v_pk_mul_f32 v[88:89], v[88:89], v[96:97] op_sel_hi:[1,0]
	v_pk_mul_f32 v[86:87], v[86:87], v[96:97] op_sel_hi:[1,0]
	v_pk_mul_f32 v[84:85], v[84:85], v[96:97] op_sel_hi:[1,0]
	v_pk_mul_f32 v[100:101], v[82:83], v[96:97] op_sel_hi:[1,0]
	v_pk_mul_f32 v[96:97], v[80:81], v[96:97] op_sel_hi:[1,0]
	v_cvt_pk_bf16_f32 v80, v92, v93
	v_cvt_pk_bf16_f32 v81, v94, v95
	v_cvt_pk_bf16_f32 v82, v88, v89
	v_cvt_pk_bf16_f32 v83, v90, v91
	global_store_dwordx4 v[98:99], v[80:83], off
	s_nop 1
	v_cvt_pk_bf16_f32 v80, v84, v85
	v_cvt_pk_bf16_f32 v81, v86, v87
	v_cvt_pk_bf16_f32 v82, v96, v97
	v_cvt_pk_bf16_f32 v83, v100, v101
	global_store_dwordx4 v[98:99], v[80:83], off offset:256
	global_load_dword v80, v[150:151], off offset:192
	s_nop 0
	v_or_b32_e32 v81, 48, v144
	v_mad_i64_i32 v[82:83], s[16:17], v81, s39, v[146:147]
	v_lshl_add_u64 v[82:83], v[82:83], 0, v[148:149]
	s_waitcnt vmcnt(0)
	v_fmamk_f32 v80, v80, 0x3a000000, v168
	v_rsq_f32_e32 v80, v80
	s_nop 0
	v_pk_mul_f32 v[78:79], v[78:79], v[80:81] op_sel_hi:[1,0]
	v_pk_mul_f32 v[76:77], v[76:77], v[80:81] op_sel_hi:[1,0]
	v_pk_mul_f32 v[74:75], v[74:75], v[80:81] op_sel_hi:[1,0]
	v_pk_mul_f32 v[72:73], v[72:73], v[80:81] op_sel_hi:[1,0]
	v_pk_mul_f32 v[70:71], v[70:71], v[80:81] op_sel_hi:[1,0]
	v_pk_mul_f32 v[68:69], v[68:69], v[80:81] op_sel_hi:[1,0]
	v_pk_mul_f32 v[84:85], v[66:67], v[80:81] op_sel_hi:[1,0]
	v_pk_mul_f32 v[80:81], v[64:65], v[80:81] op_sel_hi:[1,0]
	v_cvt_pk_bf16_f32 v64, v76, v77
	v_cvt_pk_bf16_f32 v65, v78, v79
	v_cvt_pk_bf16_f32 v66, v72, v73
	v_cvt_pk_bf16_f32 v67, v74, v75
	global_store_dwordx4 v[82:83], v[64:67], off
	s_nop 1
	v_cvt_pk_bf16_f32 v64, v68, v69
	v_cvt_pk_bf16_f32 v65, v70, v71
	v_cvt_pk_bf16_f32 v66, v80, v81
	v_cvt_pk_bf16_f32 v67, v84, v85
	global_store_dwordx4 v[82:83], v[64:67], off offset:256
	global_load_dword v64, v[150:151], off offset:512
	s_nop 0
	v_add_u32_e32 v65, 0x80, v144
	v_mad_i64_i32 v[66:67], s[16:17], v65, s39, v[146:147]
	v_lshl_add_u64 v[66:67], v[66:67], 0, v[148:149]
	s_waitcnt vmcnt(0)
	v_fmamk_f32 v64, v64, 0x3a000000, v168
	v_rsq_f32_e32 v64, v64
	s_nop 0
	v_pk_mul_f32 v[62:63], v[62:63], v[64:65] op_sel_hi:[1,0]
	v_pk_mul_f32 v[60:61], v[60:61], v[64:65] op_sel_hi:[1,0]
	v_pk_mul_f32 v[58:59], v[58:59], v[64:65] op_sel_hi:[1,0]
	v_pk_mul_f32 v[56:57], v[56:57], v[64:65] op_sel_hi:[1,0]
	v_pk_mul_f32 v[54:55], v[54:55], v[64:65] op_sel_hi:[1,0]
	v_pk_mul_f32 v[52:53], v[52:53], v[64:65] op_sel_hi:[1,0]
	v_pk_mul_f32 v[68:69], v[50:51], v[64:65] op_sel_hi:[1,0]
	v_pk_mul_f32 v[64:65], v[48:49], v[64:65] op_sel_hi:[1,0]
	v_cvt_pk_bf16_f32 v48, v60, v61
	v_cvt_pk_bf16_f32 v49, v62, v63
	v_cvt_pk_bf16_f32 v50, v56, v57
	v_cvt_pk_bf16_f32 v51, v58, v59
	global_store_dwordx4 v[66:67], v[48:51], off
	s_nop 1
	v_cvt_pk_bf16_f32 v48, v52, v53
	v_cvt_pk_bf16_f32 v49, v54, v55
	v_cvt_pk_bf16_f32 v50, v64, v65
	v_cvt_pk_bf16_f32 v51, v68, v69
	global_store_dwordx4 v[66:67], v[48:51], off offset:256
	global_load_dword v48, v[150:151], off offset:576
	s_nop 0
	v_add_u32_e32 v49, 0x90, v144
	v_mad_i64_i32 v[50:51], s[16:17], v49, s39, v[146:147]
	v_lshl_add_u64 v[50:51], v[50:51], 0, v[148:149]
	s_waitcnt vmcnt(0)
	v_fmamk_f32 v48, v48, 0x3a000000, v168
	v_rsq_f32_e32 v48, v48
	s_nop 0
	v_pk_mul_f32 v[46:47], v[46:47], v[48:49] op_sel_hi:[1,0]
	v_pk_mul_f32 v[44:45], v[44:45], v[48:49] op_sel_hi:[1,0]
	v_pk_mul_f32 v[42:43], v[42:43], v[48:49] op_sel_hi:[1,0]
	v_pk_mul_f32 v[40:41], v[40:41], v[48:49] op_sel_hi:[1,0]
	v_pk_mul_f32 v[38:39], v[38:39], v[48:49] op_sel_hi:[1,0]
	v_pk_mul_f32 v[36:37], v[36:37], v[48:49] op_sel_hi:[1,0]
	v_pk_mul_f32 v[52:53], v[34:35], v[48:49] op_sel_hi:[1,0]
	v_pk_mul_f32 v[48:49], v[32:33], v[48:49] op_sel_hi:[1,0]
	v_cvt_pk_bf16_f32 v32, v44, v45
	v_cvt_pk_bf16_f32 v33, v46, v47
	v_cvt_pk_bf16_f32 v34, v40, v41
	v_cvt_pk_bf16_f32 v35, v42, v43
	global_store_dwordx4 v[50:51], v[32:35], off
	s_nop 1
	v_cvt_pk_bf16_f32 v32, v36, v37
	v_cvt_pk_bf16_f32 v33, v38, v39
	v_cvt_pk_bf16_f32 v34, v48, v49
	v_cvt_pk_bf16_f32 v35, v52, v53
	global_store_dwordx4 v[50:51], v[32:35], off offset:256
	global_load_dword v32, v[150:151], off offset:640
	s_nop 0
	v_add_u32_e32 v33, 0xa0, v144
	v_mad_i64_i32 v[34:35], s[16:17], v33, s39, v[146:147]
	v_lshl_add_u64 v[34:35], v[34:35], 0, v[148:149]
	s_mov_b64 s[16:17], s[12:13]
	s_waitcnt vmcnt(0)
	v_fmamk_f32 v32, v32, 0x3a000000, v168
	v_rsq_f32_e32 v32, v32
	s_nop 0
	v_pk_mul_f32 v[30:31], v[30:31], v[32:33] op_sel_hi:[1,0]
	v_pk_mul_f32 v[28:29], v[28:29], v[32:33] op_sel_hi:[1,0]
	v_pk_mul_f32 v[26:27], v[26:27], v[32:33] op_sel_hi:[1,0]
	v_pk_mul_f32 v[24:25], v[24:25], v[32:33] op_sel_hi:[1,0]
	v_pk_mul_f32 v[22:23], v[22:23], v[32:33] op_sel_hi:[1,0]
	v_pk_mul_f32 v[20:21], v[20:21], v[32:33] op_sel_hi:[1,0]
	v_pk_mul_f32 v[36:37], v[18:19], v[32:33] op_sel_hi:[1,0]
	v_pk_mul_f32 v[32:33], v[16:17], v[32:33] op_sel_hi:[1,0]
	v_cvt_pk_bf16_f32 v16, v28, v29
	v_cvt_pk_bf16_f32 v17, v30, v31
	v_cvt_pk_bf16_f32 v18, v24, v25
	v_cvt_pk_bf16_f32 v19, v26, v27
	global_store_dwordx4 v[34:35], v[16:19], off
	s_nop 1
	v_cvt_pk_bf16_f32 v16, v20, v21
	v_cvt_pk_bf16_f32 v17, v22, v23
	v_cvt_pk_bf16_f32 v18, v32, v33
	v_cvt_pk_bf16_f32 v19, v36, v37
	global_store_dwordx4 v[34:35], v[16:19], off offset:256
	global_load_dword v16, v[150:151], off offset:704
	s_nop 0
	v_add_u32_e32 v17, 0xb0, v144
	v_mad_i64_i32 v[18:19], s[4:5], v17, s39, v[146:147]
	v_lshl_add_u64 v[18:19], v[18:19], 0, v[148:149]
	s_waitcnt vmcnt(0)
	v_fmamk_f32 v16, v16, 0x3a000000, v168
	v_rsq_f32_e32 v16, v16
	s_nop 0
	v_pk_mul_f32 v[14:15], v[14:15], v[16:17] op_sel_hi:[1,0]
	v_pk_mul_f32 v[12:13], v[12:13], v[16:17] op_sel_hi:[1,0]
	v_pk_mul_f32 v[10:11], v[10:11], v[16:17] op_sel_hi:[1,0]
	v_pk_mul_f32 v[8:9], v[8:9], v[16:17] op_sel_hi:[1,0]
	v_pk_mul_f32 v[6:7], v[6:7], v[16:17] op_sel_hi:[1,0]
	v_pk_mul_f32 v[4:5], v[4:5], v[16:17] op_sel_hi:[1,0]
	v_pk_mul_f32 v[20:21], v[2:3], v[16:17] op_sel_hi:[1,0]
	v_pk_mul_f32 v[16:17], v[0:1], v[16:17] op_sel_hi:[1,0]
	v_cvt_pk_bf16_f32 v0, v12, v13
	v_cvt_pk_bf16_f32 v1, v14, v15
	v_cvt_pk_bf16_f32 v2, v8, v9
	v_cvt_pk_bf16_f32 v3, v10, v11
	global_store_dwordx4 v[18:19], v[0:3], off
	s_nop 1
	v_cvt_pk_bf16_f32 v0, v4, v5
	v_cvt_pk_bf16_f32 v1, v6, v7
	v_cvt_pk_bf16_f32 v2, v16, v17
	v_cvt_pk_bf16_f32 v3, v20, v21
	global_store_dwordx4 v[18:19], v[0:3], off offset:256
	s_cbranch_vccz .LBB0_144
	s_waitcnt vmcnt(0)
	s_cmpk_gt_u32 s3, 0xff
	s_cbranch_scc1 .LBB0_151
	s_barrier

.LBB0_269:
	v_and_b32_e32 v0, 24, v158
	v_and_b32_e32 v1, 4, v238
	s_movk_i32 s1, 0x70
	v_or3_b32 v0, v1, v157, v0
	v_and_or_b32 v236, v153, s1, v218
	s_movk_i32 s1, 0x60
	v_add_u32_e32 v233, 0x2000, v156
	v_and_or_b32 v232, v153, s1, v0
	v_lshrrev_b32_e32 v144, 7, v233
	s_movk_i32 s1, 0xf0
	v_and_or_b32 v237, v144, s1, v218
	s_movk_i32 s1, 0xe0
	v_and_or_b32 v240, v144, s1, v0
	v_cndmask_b32_e64 v0, 0, 1, s[4:5]
	v_bitop3_b32 v226, v156, v159, 48 bitop3:0x6c
	v_bfe_u32 v225, v222, 4, 2
	v_cmp_ne_u32_e64 s[6:7], 1, v0
	v_or_b32_e32 v219, v226, v224
	v_lshlrev_b32_e32 v227, 4, v225
	s_add_u32 s12, s92, 0x10000
	v_writelane_b32 v255, s6, 8
	v_lshl_or_b32 v164, v232, 12, v219
	v_lshl_or_b32 v166, v240, 12, v219
	s_addc_u32 s13, s93, 0
	v_writelane_b32 v255, s7, 9
	s_andn2_b64 vcc, exec, s[4:5]
	v_bitop3_b32 v228, v227, v152, v155 bitop3:0x36
	s_cbranch_vccnz .LBB0_303
	s_add_u32 s22, s92, 0x1900000
	s_addc_u32 s23, s93, 0
	s_lshr_b32 s5, s3, 6
	s_ashr_i32 s1, s0, 31
	s_lshr_b32 s4, s3, 8
	s_lshl_b32 s24, s5, 10
	s_lshl_b64 s[6:7], s[0:1], 20
	s_add_u32 s18, s22, s6
	s_addc_u32 s19, s23, s7
	s_add_i32 s25, s24, 0
	s_add_i32 m0, s25, 0x10000
	s_mul_i32 s9, s42, 0x300000
	v_and_b32_e32 v140, 63, v222
	v_lshrrev_b32_e32 v141, 3, v140
	v_lshrrev_b32_e32 v142, 6, v222
	v_lshl_add_u32 v143, v142, 3, v141
	v_and_b32_e32 v150, 7, v140
	v_and_b32_e32 v151, 6, v141
	v_xor_b32_e32 v150, v150, v151
	v_lshlrev_b32_e32 v150, 4, v150
	v_mul_u32_u24_e32 v151, 0x3000, v143
	v_add_u32_e32 v151, v151, v150
	v_mov_b32_e32 v132, v151
	v_mov_b32_e32 v128, v151
	v_add_u32_e32 v134, 0xc0000, v151
	v_add_u32_e32 v130, 0xc0000, v151
	v_add_u32_e32 v134, 0xc0000, v151
	v_add_u32_e32 v130, 0xc0000, v151
	v_and_b32_e32 v151, 31, v143
	v_and_b32_e32 v154, 12, v151
	v_lshlrev_b32_e32 v154, 1, v154
	v_lshrrev_b32_e32 v155, 4, v151
	v_lshlrev_b32_e32 v155, 2, v155
	v_and_b32_e32 v151, 3, v151
	v_or3_b32 v151, v154, v155, v151
	v_and_b32_e32 v154, 0x60, v143
	v_add_u32_e32 v151, v151, v154
	v_mul_u32_u24_e32 v151, 0x1000, v151
	v_add_u32_e32 v151, v151, v150
	v_mov_b32_e32 v164, v151
	v_add_u32_e32 v166, 0x40000, v151
	v_add_u32_e32 v166, 0x40000, v151
	v_and_b32_e32 v151, 15, v140
	v_lshrrev_b32_e32 v154, 4, v140
	v_and_b32_e32 v155, 6, v151
	v_xor_b32_e32 v154, v154, v155
	v_lshlrev_b32_e32 v154, 4, v154
	v_lshl_or_b32 v154, v151, 7, v154
	v_lshrrev_b32_e32 v155, 2, v142
	v_lshl_add_u32 v155, v155, 13, v154
	v_add_u32_e32 v147, 0x0, v155
	v_and_b32_e32 v151, 3, v142
	v_lshl_add_u32 v151, v151, 12, v154
	v_add_u32_e32 v145, 0x0, v151
	v_add_u32_e32 v146, 0x10000, v151
	v_add_u32_e32 v148, 0x14000, v151
	global_load_lds_dwordx4 v164, s[18:19]
	s_add_i32 m0, s25, 0x12000
	v_mul_u32_u24_e32 v9, 0x3000, v236
	s_mul_hi_i32 s8, s42, 0x300000
	s_add_u32 s20, s96, s9
	v_mul_u32_u24_e32 v8, 0x3000, v237
	global_load_lds_dwordx4 v166, s[18:19]
	s_addc_u32 s21, s97, s8
	s_mov_b32 m0, s25
	s_add_i32 s26, s25, 0x2000
	global_load_lds_dwordx4 v128, s[20:21]
	s_mov_b32 m0, s26
	s_add_u32 s6, s18, 0x80000
	global_load_lds_dwordx4 v130, s[20:21]
	s_addc_u32 s7, s19, 0
	s_add_i32 m0, s25, 0x14000
	v_mov_b32_e32 v165, 0
	global_load_lds_dwordx4 v164, s[6:7]
	s_add_i32 m0, s25, 0x16000
	v_mov_b32_e32 v167, v165
	global_load_lds_dwordx4 v166, s[6:7]
	s_add_u32 s6, s20, 0x180000
	s_addc_u32 s7, s21, 0
	s_add_i32 s27, s25, 0x4000
	s_mov_b32 m0, s27
	s_add_i32 s28, s25, 0x6000
	global_load_lds_dwordx4 v128, s[6:7]
	s_mov_b32 m0, s28
	v_mov_b32_e32 v129, v165
	global_load_lds_dwordx4 v130, s[6:7]
	v_mov_b32_e32 v131, v165
	s_mov_b32 s29, 0
	v_lshl_add_u64 v[6:7], s[18:19], 0, v[164:165]
	v_lshl_add_u64 v[4:5], s[18:19], 0, v[166:167]
	v_lshl_add_u64 v[2:3], s[20:21], 0, v[128:129]
	s_cmp_lg_u32 s4, 1
	v_lshl_add_u64 v[0:1], s[20:21], 0, v[130:131]
	s_cbranch_scc1 .LBB0_272
	s_barrier
.LBB0_272:
	s_mov_b64 s[8:9], 0x80
	s_lshl_b32 s30, s4, 6
	s_lshl_b32 s1, s4, 13
	s_lshl_b32 s4, s5, 5
	s_add_i32 m0, s25, 0x18000
	v_lshl_add_u64 v[6:7], v[6:7], 0, s[8:9]
	s_and_b32 s31, s4, 0x60
	s_waitcnt vmcnt(4)
	s_barrier
	global_load_lds_dwordx4 v[6:7], off
	v_lshl_add_u64 v[4:5], v[4:5], 0, s[8:9]
	s_add_i32 m0, s25, 0x1a000
	s_add_i32 s33, s25, 0x8000
	s_add_i32 s34, s25, 0xa000
	global_load_lds_dwordx4 v[4:5], off
	v_lshl_add_u64 v[2:3], v[2:3], 0, s[8:9]
	s_mov_b32 m0, s33
	s_add_u32 s4, s18, 0x80080
	global_load_lds_dwordx4 v[2:3], off
	v_lshl_add_u64 v[0:1], v[0:1], 0, s[8:9]
	s_mov_b32 m0, s34
	s_addc_u32 s5, s19, 0
	global_load_lds_dwordx4 v[0:1], off
	s_add_i32 m0, s25, 0x1c000
	v_lshl_add_u64 v[0:1], s[4:5], 0, v[164:165]
	global_load_lds_dwordx4 v[0:1], off
	v_lshl_add_u64 v[0:1], s[4:5], 0, v[166:167]
	s_add_i32 m0, s25, 0x1e000
	global_load_lds_dwordx4 v[0:1], off
	v_lshlrev_b32_e32 v1, 2, v163
	v_lshl_or_b32 v0, v163, 6, v227
	v_and_b32_e32 v1, 32, v1
	v_bitop3_b32 v0, v0, s1, v1 bitop3:0xde
	s_waitcnt vmcnt(6)
	s_add_i32 s39, 0, 0x10000
	s_add_i32 s40, 0, 0x14000
	v_mbcnt_lo_u32_b32 v0, -1, 0
	s_ashr_i32 s35, s94, 31
	s_mov_b32 s38, s94
	v_mov_b32_e32 v133, v165
	v_mov_b32_e32 v135, v165
	v_mov_b64_e32 v[136:137], 0x200
	v_mov_b64_e32 v[138:139], 0x1ff
	v_mbcnt_hi_u32_b32 v149, -1, v0
	s_barrier
	s_branch .LBB0_274

.LBB0_283:
	ds_read_b128 v[140:143], v146
	v_xor_b32_e32 v171, 64, v146
	ds_read_b128 v[154:157], v171
	ds_read_b128 v[158:161], v146 offset:2048
	ds_read_b128 v[168:171], v171 offset:2048
	s_add_u32 s18, s6, 0xffe80080
	s_addc_u32 s19, s7, -1
	s_cmp_eq_u32 s45, 28
	s_cselect_b32 s21, s15, s19
	s_cselect_b32 s20, s14, s18
	s_cselect_b32 s19, s1, s44
	s_cselect_b32 s18, s11, s43
	v_lshl_add_u64 v[150:151], s[6:7], 0, v[132:133]
	s_add_i32 m0, s25, 0xc000
	ds_read_b128 v[172:175], v147
	v_xor_b32_e32 v203, 64, v147
	ds_read_b128 v[176:179], v203
	ds_read_b128 v[180:183], v147 offset:2048
	ds_read_b128 v[184:187], v203 offset:2048
	ds_read_b128 v[188:191], v147 offset:4096
	ds_read_b128 v[192:195], v203 offset:4096
	ds_read_b128 v[196:199], v147 offset:6144
	ds_read_b128 v[200:203], v203 offset:6144
	global_load_lds_dwordx4 v[150:151], off
	v_lshl_add_u64 v[150:151], s[6:7], 0, v[134:135]
	s_add_i32 m0, s25, 0xe000
	s_nop 0
	global_load_lds_dwordx4 v[150:151], off
	s_waitcnt lgkmcnt(8)
	s_barrier
	s_waitcnt lgkmcnt(0)
	s_setprio 1
	s_waitcnt lgkmcnt(0)
	v_mfma_f32_16x16x32_bf16 v[124:127], v[140:143], v[172:175], v[124:127]
	v_mfma_f32_16x16x32_bf16 v[120:123], v[158:161], v[172:175], v[120:123]
	v_mfma_f32_16x16x32_bf16 v[108:111], v[140:143], v[180:183], v[108:111]
	v_mfma_f32_16x16x32_bf16 v[104:107], v[158:161], v[180:183], v[104:107]
	v_mfma_f32_16x16x32_bf16 v[92:95], v[140:143], v[188:191], v[92:95]
	v_mfma_f32_16x16x32_bf16 v[88:91], v[158:161], v[188:191], v[88:91]
	v_mfma_f32_16x16x32_bf16 v[76:79], v[140:143], v[196:199], v[76:79]
	v_mfma_f32_16x16x32_bf16 v[72:75], v[158:161], v[196:199], v[72:75]
	v_mfma_f32_16x16x32_bf16 v[124:127], v[154:157], v[176:179], v[124:127]
	v_mfma_f32_16x16x32_bf16 v[120:123], v[168:171], v[176:179], v[120:123]
	v_mfma_f32_16x16x32_bf16 v[108:111], v[154:157], v[184:187], v[108:111]
	v_mfma_f32_16x16x32_bf16 v[104:107], v[168:171], v[184:187], v[104:107]
	v_mfma_f32_16x16x32_bf16 v[92:95], v[154:157], v[192:195], v[92:95]
	v_mfma_f32_16x16x32_bf16 v[88:91], v[168:171], v[192:195], v[88:91]
	v_mfma_f32_16x16x32_bf16 v[76:79], v[154:157], v[200:203], v[76:79]
	v_mfma_f32_16x16x32_bf16 v[72:75], v[168:171], v[200:203], v[72:75]
	s_setprio 0
	s_barrier
	s_add_i32 s46, s39, s24
	v_lshl_add_u64 v[150:151], s[18:19], 0, v[164:165]
	s_mov_b32 m0, s46
	ds_read_b128 v[204:207], v148
	v_xor_b32_e32 v245, 64, v148
	ds_read_b128 v[208:211], v245
	ds_read_b128 v[212:215], v148 offset:2048
	ds_read_b128 v[242:245], v245 offset:2048
	global_load_lds_dwordx4 v[150:151], off
	v_lshl_add_u64 v[216:217], s[18:19], 0, v[166:167]
	s_add_i32 m0, s46, 0x2000
	s_nop 0
	global_load_lds_dwordx4 v[216:217], off
	s_barrier
	s_waitcnt lgkmcnt(0)
	s_setprio 1
	s_waitcnt lgkmcnt(0)
	v_mfma_f32_16x16x32_bf16 v[116:119], v[204:207], v[172:175], v[116:119]
	v_mfma_f32_16x16x32_bf16 v[112:115], v[212:215], v[172:175], v[112:115]
	v_mfma_f32_16x16x32_bf16 v[100:103], v[204:207], v[180:183], v[100:103]
	v_mfma_f32_16x16x32_bf16 v[96:99], v[212:215], v[180:183], v[96:99]
	v_mfma_f32_16x16x32_bf16 v[84:87], v[204:207], v[188:191], v[84:87]
	v_mfma_f32_16x16x32_bf16 v[80:83], v[212:215], v[188:191], v[80:83]
	v_mfma_f32_16x16x32_bf16 v[68:71], v[204:207], v[196:199], v[68:71]
	v_mfma_f32_16x16x32_bf16 v[64:67], v[212:215], v[196:199], v[64:67]
	v_mfma_f32_16x16x32_bf16 v[116:119], v[208:211], v[176:179], v[116:119]
	v_mfma_f32_16x16x32_bf16 v[112:115], v[242:245], v[176:179], v[112:115]
	v_mfma_f32_16x16x32_bf16 v[100:103], v[208:211], v[184:187], v[100:103]
	v_mfma_f32_16x16x32_bf16 v[96:99], v[242:245], v[184:187], v[96:99]
	v_mfma_f32_16x16x32_bf16 v[84:87], v[208:211], v[192:195], v[84:87]
	v_mfma_f32_16x16x32_bf16 v[80:83], v[242:245], v[192:195], v[80:83]
	v_mfma_f32_16x16x32_bf16 v[68:71], v[208:211], v[200:203], v[68:71]
	v_mfma_f32_16x16x32_bf16 v[64:67], v[242:245], v[200:203], v[64:67]
	s_setprio 0
	s_mov_b32 m0, s25
	v_lshl_add_u64 v[220:221], s[20:21], 0, v[128:129]
	s_barrier
	ds_read_b128 v[172:175], v147 offset:16384
	v_xor_b32_e32 v203, 64, v147
	ds_read_b128 v[176:179], v203 offset:16384
	ds_read_b128 v[180:183], v147 offset:18432
	ds_read_b128 v[184:187], v203 offset:18432
	ds_read_b128 v[188:191], v147 offset:20480
	ds_read_b128 v[192:195], v203 offset:20480
	ds_read_b128 v[196:199], v147 offset:22528
	ds_read_b128 v[200:203], v203 offset:22528
	global_load_lds_dwordx4 v[220:221], off
	v_lshl_add_u64 v[230:231], s[20:21], 0, v[130:131]
	s_mov_b32 m0, s26
	s_nop 0
	global_load_lds_dwordx4 v[230:231], off
	s_barrier
	s_waitcnt lgkmcnt(0)
	s_setprio 1
	s_waitcnt lgkmcnt(0)
	v_mfma_f32_16x16x32_bf16 v[60:63], v[140:143], v[172:175], v[60:63]
	v_mfma_f32_16x16x32_bf16 v[56:59], v[158:161], v[172:175], v[56:59]
	v_mfma_f32_16x16x32_bf16 v[44:47], v[140:143], v[180:183], v[44:47]
	v_mfma_f32_16x16x32_bf16 v[40:43], v[158:161], v[180:183], v[40:43]
	v_mfma_f32_16x16x32_bf16 v[28:31], v[140:143], v[188:191], v[28:31]
	v_mfma_f32_16x16x32_bf16 v[24:27], v[158:161], v[188:191], v[24:27]
	v_mfma_f32_16x16x32_bf16 v[12:15], v[140:143], v[196:199], v[12:15]
	v_mfma_f32_16x16x32_bf16 v[8:11], v[158:161], v[196:199], v[8:11]
	v_mfma_f32_16x16x32_bf16 v[60:63], v[154:157], v[176:179], v[60:63]
	v_mfma_f32_16x16x32_bf16 v[56:59], v[168:171], v[176:179], v[56:59]
	v_mfma_f32_16x16x32_bf16 v[44:47], v[154:157], v[184:187], v[44:47]
	v_mfma_f32_16x16x32_bf16 v[40:43], v[168:171], v[184:187], v[40:43]
	v_mfma_f32_16x16x32_bf16 v[28:31], v[154:157], v[192:195], v[28:31]
	v_mfma_f32_16x16x32_bf16 v[24:27], v[168:171], v[192:195], v[24:27]
	v_mfma_f32_16x16x32_bf16 v[12:15], v[154:157], v[200:203], v[12:15]
	v_mfma_f32_16x16x32_bf16 v[8:11], v[168:171], v[200:203], v[8:11]
	s_setprio 0
	s_barrier
	s_add_u32 s46, s18, 0x80000
	s_addc_u32 s47, s19, 0
	s_add_i32 s48, s40, s24
	v_lshl_add_u64 v[140:141], s[46:47], 0, v[164:165]
	s_mov_b32 m0, s48
	s_nop 0
	global_load_lds_dwordx4 v[140:141], off
	v_lshl_add_u64 v[140:141], s[46:47], 0, v[166:167]
	s_add_i32 m0, s48, 0x2000
	s_nop 0
	global_load_lds_dwordx4 v[140:141], off
	s_waitcnt vmcnt(6)
	s_barrier
	s_setprio 1
	v_mfma_f32_16x16x32_bf16 v[52:55], v[204:207], v[172:175], v[52:55]
	v_mfma_f32_16x16x32_bf16 v[48:51], v[212:215], v[172:175], v[48:51]
	v_mfma_f32_16x16x32_bf16 v[36:39], v[204:207], v[180:183], v[36:39]
	v_mfma_f32_16x16x32_bf16 v[32:35], v[212:215], v[180:183], v[32:35]
	v_mfma_f32_16x16x32_bf16 v[20:23], v[204:207], v[188:191], v[20:23]
	v_mfma_f32_16x16x32_bf16 v[16:19], v[212:215], v[188:191], v[16:19]
	v_mfma_f32_16x16x32_bf16 v[4:7], v[204:207], v[196:199], v[4:7]
	v_mfma_f32_16x16x32_bf16 v[0:3], v[212:215], v[196:199], v[0:3]
	v_mfma_f32_16x16x32_bf16 v[52:55], v[208:211], v[176:179], v[52:55]
	v_mfma_f32_16x16x32_bf16 v[48:51], v[242:245], v[176:179], v[48:51]
	v_mfma_f32_16x16x32_bf16 v[36:39], v[208:211], v[184:187], v[36:39]
	v_mfma_f32_16x16x32_bf16 v[32:35], v[242:245], v[184:187], v[32:35]
	v_mfma_f32_16x16x32_bf16 v[20:23], v[208:211], v[192:195], v[20:23]
	v_mfma_f32_16x16x32_bf16 v[16:19], v[242:245], v[192:195], v[16:19]
	v_mfma_f32_16x16x32_bf16 v[4:7], v[208:211], v[200:203], v[4:7]
	v_mfma_f32_16x16x32_bf16 v[0:3], v[242:245], v[200:203], v[0:3]
	s_setprio 0
	s_add_i32 s46, 0, 0x18000
	v_add_u32_e32 v168, s46, v145
	s_barrier
	ds_read_b128 v[140:143], v168
	v_xor_b32_e32 v171, 64, v168
	ds_read_b128 v[154:157], v171
	ds_read_b128 v[158:161], v168 offset:2048
	ds_read_b128 v[168:171], v171 offset:2048
	s_add_u32 s20, s20, 0x180000
	s_addc_u32 s21, s21, 0
	s_mov_b32 m0, s27
	v_lshl_add_u64 v[204:205], s[20:21], 0, v[128:129]
	ds_read_b128 v[172:175], v147 offset:32768
	v_xor_b32_e32 v203, 64, v147
	ds_read_b128 v[176:179], v203 offset:32768
	ds_read_b128 v[180:183], v147 offset:34816
	ds_read_b128 v[184:187], v203 offset:34816
	ds_read_b128 v[188:191], v147 offset:36864
	ds_read_b128 v[192:195], v203 offset:36864
	ds_read_b128 v[196:199], v147 offset:38912
	ds_read_b128 v[200:203], v203 offset:38912
	global_load_lds_dwordx4 v[204:205], off
	v_lshl_add_u64 v[204:205], s[20:21], 0, v[130:131]
	s_mov_b32 m0, s28
	s_nop 0
	global_load_lds_dwordx4 v[204:205], off
	s_waitcnt lgkmcnt(8)
	s_barrier
	s_waitcnt lgkmcnt(0)
	s_setprio 1
	s_waitcnt lgkmcnt(0)
	v_mfma_f32_16x16x32_bf16 v[124:127], v[140:143], v[172:175], v[124:127]
	v_mfma_f32_16x16x32_bf16 v[120:123], v[158:161], v[172:175], v[120:123]
	v_mfma_f32_16x16x32_bf16 v[108:111], v[140:143], v[180:183], v[108:111]
	v_mfma_f32_16x16x32_bf16 v[104:107], v[158:161], v[180:183], v[104:107]
	v_mfma_f32_16x16x32_bf16 v[92:95], v[140:143], v[188:191], v[92:95]
	v_mfma_f32_16x16x32_bf16 v[88:91], v[158:161], v[188:191], v[88:91]
	v_mfma_f32_16x16x32_bf16 v[76:79], v[140:143], v[196:199], v[76:79]
	v_mfma_f32_16x16x32_bf16 v[72:75], v[158:161], v[196:199], v[72:75]
	v_mfma_f32_16x16x32_bf16 v[124:127], v[154:157], v[176:179], v[124:127]
	v_mfma_f32_16x16x32_bf16 v[120:123], v[168:171], v[176:179], v[120:123]
	v_mfma_f32_16x16x32_bf16 v[108:111], v[154:157], v[184:187], v[108:111]
	v_mfma_f32_16x16x32_bf16 v[104:107], v[168:171], v[184:187], v[104:107]
	v_mfma_f32_16x16x32_bf16 v[92:95], v[154:157], v[192:195], v[92:95]
	v_mfma_f32_16x16x32_bf16 v[88:91], v[168:171], v[192:195], v[88:91]
	v_mfma_f32_16x16x32_bf16 v[76:79], v[154:157], v[200:203], v[76:79]
	v_mfma_f32_16x16x32_bf16 v[72:75], v[168:171], v[200:203], v[72:75]
	s_setprio 0
	s_barrier
	s_add_i32 s20, 0, 0x1c000
	s_add_i32 s21, s46, s24
	v_add_u32_e32 v223, s20, v145
	v_lshl_add_u64 v[150:151], v[150:151], 0, s[8:9]
	s_mov_b32 m0, s21
	ds_read_b128 v[204:207], v223
	v_xor_b32_e32 v245, 64, v223
	ds_read_b128 v[208:211], v245
	ds_read_b128 v[212:215], v223 offset:2048
	ds_read_b128 v[242:245], v245 offset:2048
	global_load_lds_dwordx4 v[150:151], off
	v_lshl_add_u64 v[150:151], v[216:217], 0, s[8:9]
	s_add_i32 m0, s21, 0x2000
	s_nop 0
	global_load_lds_dwordx4 v[150:151], off
	s_barrier
	s_waitcnt lgkmcnt(0)
	s_setprio 1
	s_waitcnt lgkmcnt(0)
	v_mfma_f32_16x16x32_bf16 v[116:119], v[204:207], v[172:175], v[116:119]
	v_mfma_f32_16x16x32_bf16 v[112:115], v[212:215], v[172:175], v[112:115]
	v_mfma_f32_16x16x32_bf16 v[100:103], v[204:207], v[180:183], v[100:103]
	v_mfma_f32_16x16x32_bf16 v[96:99], v[212:215], v[180:183], v[96:99]
	v_mfma_f32_16x16x32_bf16 v[84:87], v[204:207], v[188:191], v[84:87]
	v_mfma_f32_16x16x32_bf16 v[80:83], v[212:215], v[188:191], v[80:83]
	v_mfma_f32_16x16x32_bf16 v[68:71], v[204:207], v[196:199], v[68:71]
	v_mfma_f32_16x16x32_bf16 v[64:67], v[212:215], v[196:199], v[64:67]
	v_mfma_f32_16x16x32_bf16 v[116:119], v[208:211], v[176:179], v[116:119]
	v_mfma_f32_16x16x32_bf16 v[112:115], v[242:245], v[176:179], v[112:115]
	v_mfma_f32_16x16x32_bf16 v[100:103], v[208:211], v[184:187], v[100:103]
	v_mfma_f32_16x16x32_bf16 v[96:99], v[242:245], v[184:187], v[96:99]
	v_mfma_f32_16x16x32_bf16 v[84:87], v[208:211], v[192:195], v[84:87]
	v_mfma_f32_16x16x32_bf16 v[80:83], v[242:245], v[192:195], v[80:83]
	v_mfma_f32_16x16x32_bf16 v[68:71], v[208:211], v[200:203], v[68:71]
	v_mfma_f32_16x16x32_bf16 v[64:67], v[242:245], v[200:203], v[64:67]
	s_setprio 0
	s_mov_b32 m0, s33
	v_lshl_add_u64 v[150:151], v[220:221], 0, s[8:9]
	s_barrier
	ds_read_b128 v[172:175], v147 offset:49152
	v_xor_b32_e32 v203, 64, v147
	ds_read_b128 v[176:179], v203 offset:49152
	ds_read_b128 v[180:183], v147 offset:51200
	ds_read_b128 v[184:187], v203 offset:51200
	ds_read_b128 v[188:191], v147 offset:53248
	ds_read_b128 v[192:195], v203 offset:53248
	ds_read_b128 v[196:199], v147 offset:55296
	ds_read_b128 v[200:203], v203 offset:55296
	global_load_lds_dwordx4 v[150:151], off
	v_lshl_add_u64 v[150:151], v[230:231], 0, s[8:9]
	s_mov_b32 m0, s34
	s_nop 0
	global_load_lds_dwordx4 v[150:151], off
	s_barrier
	s_waitcnt lgkmcnt(0)
	s_setprio 1
	s_waitcnt lgkmcnt(0)
	v_mfma_f32_16x16x32_bf16 v[60:63], v[140:143], v[172:175], v[60:63]
	v_mfma_f32_16x16x32_bf16 v[56:59], v[158:161], v[172:175], v[56:59]
	v_mfma_f32_16x16x32_bf16 v[44:47], v[140:143], v[180:183], v[44:47]
	v_mfma_f32_16x16x32_bf16 v[40:43], v[158:161], v[180:183], v[40:43]
	v_mfma_f32_16x16x32_bf16 v[28:31], v[140:143], v[188:191], v[28:31]
	v_mfma_f32_16x16x32_bf16 v[24:27], v[158:161], v[188:191], v[24:27]
	v_mfma_f32_16x16x32_bf16 v[12:15], v[140:143], v[196:199], v[12:15]
	v_mfma_f32_16x16x32_bf16 v[8:11], v[158:161], v[196:199], v[8:11]
	v_mfma_f32_16x16x32_bf16 v[60:63], v[154:157], v[176:179], v[60:63]
	v_mfma_f32_16x16x32_bf16 v[56:59], v[168:171], v[176:179], v[56:59]
	v_mfma_f32_16x16x32_bf16 v[44:47], v[154:157], v[184:187], v[44:47]
	v_mfma_f32_16x16x32_bf16 v[40:43], v[168:171], v[184:187], v[40:43]
	v_mfma_f32_16x16x32_bf16 v[28:31], v[154:157], v[192:195], v[28:31]
	v_mfma_f32_16x16x32_bf16 v[24:27], v[168:171], v[192:195], v[24:27]
	v_mfma_f32_16x16x32_bf16 v[12:15], v[154:157], v[200:203], v[12:15]
	v_mfma_f32_16x16x32_bf16 v[8:11], v[168:171], v[200:203], v[8:11]
	s_setprio 0
	s_barrier
	s_add_u32 s18, s18, 0x80080
	s_addc_u32 s19, s19, 0
	s_add_i32 s20, s20, s24
	v_lshl_add_u64 v[140:141], s[18:19], 0, v[164:165]
	s_mov_b32 m0, s20
	s_nop 0
	global_load_lds_dwordx4 v[140:141], off
	v_lshl_add_u64 v[140:141], s[18:19], 0, v[166:167]
	s_add_i32 m0, s20, 0x2000
	s_nop 0
	global_load_lds_dwordx4 v[140:141], off
	s_waitcnt vmcnt(6)
	s_barrier
	s_setprio 1
	v_mfma_f32_16x16x32_bf16 v[52:55], v[204:207], v[172:175], v[52:55]
	v_mfma_f32_16x16x32_bf16 v[48:51], v[212:215], v[172:175], v[48:51]
	v_mfma_f32_16x16x32_bf16 v[36:39], v[204:207], v[180:183], v[36:39]
	v_mfma_f32_16x16x32_bf16 v[32:35], v[212:215], v[180:183], v[32:35]
	v_mfma_f32_16x16x32_bf16 v[20:23], v[204:207], v[188:191], v[20:23]
	v_mfma_f32_16x16x32_bf16 v[16:19], v[212:215], v[188:191], v[16:19]
	v_mfma_f32_16x16x32_bf16 v[4:7], v[204:207], v[196:199], v[4:7]
	v_mfma_f32_16x16x32_bf16 v[0:3], v[212:215], v[196:199], v[0:3]
	v_mfma_f32_16x16x32_bf16 v[52:55], v[208:211], v[176:179], v[52:55]
	v_mfma_f32_16x16x32_bf16 v[48:51], v[242:245], v[176:179], v[48:51]
	v_mfma_f32_16x16x32_bf16 v[36:39], v[208:211], v[184:187], v[36:39]
	v_mfma_f32_16x16x32_bf16 v[32:35], v[242:245], v[184:187], v[32:35]
	v_mfma_f32_16x16x32_bf16 v[20:23], v[208:211], v[192:195], v[20:23]
	v_mfma_f32_16x16x32_bf16 v[16:19], v[242:245], v[192:195], v[16:19]
	v_mfma_f32_16x16x32_bf16 v[4:7], v[208:211], v[200:203], v[4:7]
	v_mfma_f32_16x16x32_bf16 v[0:3], v[242:245], v[200:203], v[0:3]
	s_setprio 0
	s_add_i32 s45, s45, 2
	s_add_u32 s6, s6, 0x100
	s_addc_u32 s7, s7, 0
	s_add_u32 s43, s43, 0x100
	s_addc_u32 s44, s44, 0
	s_cmp_gt_u32 s45, 29
	s_barrier
	s_cbranch_scc0 .LBB0_283
	s_lshl_b32 s1, s42, 8
	v_mov_b32_e32 v140, v163
	v_mov_b32_e32 v172, v225
	s_add_i32 s1, s1, s30
	s_lshl_b32 s0, s0, 8
	s_or_b32 s0, s0, s31
	v_add_u32_e32 v142, s1, v140
	v_lshl_add_u32 v140, v172, 3, s0
	v_ashrrev_i32_e32 v143, 31, v142
	v_ashrrev_i32_e32 v141, 31, v140
	v_lshlrev_b64 v[150:151], 11, v[142:143]
	v_lshl_add_u64 v[150:151], v[150:151], 0, v[140:141]
	v_lshl_add_u64 v[168:169], v[150:151], 2, s[36:37]
	global_load_dwordx4 v[154:157], v[168:169], off
	global_load_dwordx4 v[158:161], v[168:169], off offset:16
	v_lshl_add_u64 v[150:151], v[150:151], 1, s[80:81]
	s_waitcnt vmcnt(0)
	v_pk_add_f32 v[126:127], v[126:127], v[156:157]
	v_pk_add_f32 v[170:171], v[124:125], v[154:155]
	v_pk_add_f32 v[160:161], v[122:123], v[160:161]
	v_pk_add_f32 v[158:159], v[120:121], v[158:159]
	v_cvt_pk_bf16_f32 v120, v170, v171
	v_cvt_pk_bf16_f32 v121, v126, v127
	s_nop 0
	v_cvt_pk_bf16_f32 v122, v158, v159
	v_cvt_pk_bf16_f32 v123, v160, v161
	global_store_dwordx4 v[150:151], v[120:123], off
	global_load_dwordx4 v[122:125], v[168:169], off offset:512
	s_nop 0
	global_load_dwordx4 v[154:157], v[168:169], off offset:528
	v_mul_f32_e32 v158, v158, v158
	v_mul_f32_e32 v159, v159, v159
	v_mul_f32_e32 v160, v160, v160
	v_fmac_f32_e32 v158, v170, v170
	v_fmac_f32_e32 v159, v171, v171
	v_mul_f32_e32 v161, v161, v161
	v_fmac_f32_e32 v160, v126, v126
	v_add_f32_e32 v126, v158, v159
	v_fmac_f32_e32 v161, v127, v127
	v_add_f32_e32 v126, v160, v126
	v_and_b32_e32 v121, 64, v149
	v_add_f32_e32 v126, v161, v126
	v_xor_b32_e32 v120, 16, v149
	v_add_u32_e32 v121, 64, v121
	v_cmp_lt_i32_e32 vcc, v120, v121
	v_xor_b32_e32 v168, 32, v149
	v_cmp_lt_i32_e64 s[6:7], v168, v121
	v_cndmask_b32_e32 v120, v149, v120, vcc
	v_lshlrev_b32_e32 v120, 2, v120
	v_cmp_eq_u32_e32 vcc, 0, v172
	s_waitcnt vmcnt(0)
	v_pk_add_f32 v[118:119], v[118:119], v[124:125]
	v_pk_add_f32 v[124:125], v[112:113], v[154:155]
	v_pk_add_f32 v[116:117], v[116:117], v[122:123]
	v_mul_f32_e32 v112, v124, v124
	v_pk_add_f32 v[122:123], v[114:115], v[156:157]
	v_mul_f32_e32 v113, v125, v125
	v_fmac_f32_e32 v112, v116, v116
	v_mul_f32_e32 v114, v122, v122
	v_fmac_f32_e32 v113, v117, v117
	v_add_f32_e32 v112, v126, v112
	v_mul_f32_e32 v115, v123, v123
	v_fmac_f32_e32 v114, v118, v118
	v_add_f32_e32 v112, v113, v112
	v_fmac_f32_e32 v115, v119, v119
	v_add_f32_e32 v112, v114, v112
	v_add_f32_e32 v112, v115, v112
	ds_bpermute_b32 v113, v120, v112
	v_cndmask_b32_e64 v114, v149, v168, s[6:7]
	v_lshlrev_b32_e32 v114, 2, v114
	v_cvt_pk_bf16_f32 v116, v116, v117
	v_cvt_pk_bf16_f32 v117, v118, v119
	s_waitcnt lgkmcnt(0)
	v_add_f32_e32 v112, v112, v113
	ds_bpermute_b32 v113, v114, v112
	v_cvt_pk_bf16_f32 v118, v124, v125
	v_cvt_pk_bf16_f32 v119, v122, v123
	global_store_dwordx4 v[150:151], v[116:119], off offset:256
	s_and_saveexec_b64 s[0:1], vcc
	s_cbranch_execz .LBB0_286
	v_lshl_add_u64 v[116:117], v[142:143], 2, s[12:13]
	s_waitcnt lgkmcnt(0)
	v_add_f32_e32 v112, v112, v113
	global_atomic_add_f32 v[116:117], v112, off

.LBB0_355:
	s_or_b64 exec, exec, s[0:1]
	s_add_u32 s70, s92, 0x1bd00000
	s_addc_u32 s71, s93, 0
	s_cmpk_lt_i32 s2, 0xb00
	s_cselect_b64 s[0:1], -1, 0
	s_waitcnt lgkmcnt(0)
	v_lshlrev_b32_e32 v0, 6, v163
	v_writelane_b32 v255, s0, 10
	v_readfirstlane_b32 s3, v222
	v_bitop3_b32 v230, v227, v152, v0 bitop3:0x36
	v_writelane_b32 v255, s1, 11
	s_cmpk_gt_i32 s2, 0xaff
	v_and_b32_e32 v220, 48, v144
	v_lshlrev_b32_e32 v223, 1, v144
	v_and_b32_e32 v221, 48, v153
	v_lshlrev_b32_e32 v254, 1, v153
	s_barrier
	s_cbranch_scc1 .LBB0_377
	s_add_u32 s40, s92, 0x2100000
	s_addc_u32 s41, s93, 0
	s_lshr_b32 s0, s77, 29
	s_add_i32 s0, s2, s0
	s_lshr_b32 s10, s3, 6
	s_ashr_i32 s1, s0, 3
	s_and_b32 s0, s0, -8
	s_lshr_b32 s5, s3, 8
	s_lshl_b32 s42, s10, 10
	s_sub_i32 s0, s2, s0
	s_cmp_lt_i32 s0, 0
	s_movk_i32 s43, 0x161
	s_cselect_b32 s4, s43, 0x160
	s_mul_i32 s0, s4, s0
	s_add_i32 s0, s0, s1
	s_mul_hi_i32 s1, s0, 0x2e8ba2e9
	s_lshr_b32 s4, s1, 31
	s_ashr_i32 s1, s1, 5
	s_add_i32 s1, s1, s4
	s_lshl_b32 s6, s1, 2
	s_mulk_i32 s1, 0xb0
	s_sub_i32 s0, s0, s1
	s_sext_i32_i16 s1, s0
	s_bfe_u32 s1, s1, 0x2001d
	s_add_i32 s1, s0, s1
	s_sext_i32_i16 s4, s1
	s_and_b32 s1, s1, 0xfffc
	s_sub_i32 s0, s0, s1
	s_sext_i32_i16 s0, s0
	s_lshr_b32 s4, s4, 2
	s_add_i32 s0, s6, s0
	s_ashr_i32 s1, s0, 31
	s_bfe_i64 s[8:9], s[4:5], 0x100000
	s_lshl_b64 s[6:7], s[0:1], 20
	s_lshl_b64 s[8:9], s[8:9], 19
	s_add_u32 s8, s40, s8
	s_addc_u32 s9, s41, s9
	s_add_i32 s44, s42, 0
	v_and_b32_e32 v8, 0x180, v223
	s_add_i32 m0, s44, 0x10000
	v_or3_b32 v0, v220, v8, v218
	v_and_b32_e32 v9, 0x80, v254
	v_and_b32_e32 v183, 63, v222
	v_lshrrev_b32_e32 v184, 3, v183
	v_lshrrev_b32_e32 v185, 6, v222
	v_lshl_add_u32 v186, v185, 3, v184
	v_and_b32_e32 v187, 7, v183
	v_and_b32_e32 v188, 6, v184
	v_xor_b32_e32 v187, v187, v188
	v_lshlrev_b32_e32 v187, 4, v187
	v_mul_u32_u24_e32 v188, 0x1000, v186
	v_add_u32_e32 v188, v188, v187
	v_add_u32_e32 v168, 0x80000, v188
	v_mov_b32_e32 v170, v188
	v_add_u32_e32 v172, 0x40080, v188
	v_add_u32_e32 v174, 0xc0080, v188
	v_add_u32_e32 v168, 0x80000, v188
	v_add_u32_e32 v174, 0xc0080, v188
	v_and_b32_e32 v188, 31, v186
	v_and_b32_e32 v189, 12, v188
	v_lshlrev_b32_e32 v189, 1, v189
	v_lshrrev_b32_e32 v190, 4, v188
	v_lshlrev_b32_e32 v190, 2, v190
	v_and_b32_e32 v188, 3, v188
	v_or3_b32 v188, v189, v190, v188
	v_and_b32_e32 v189, 0x60, v186
	v_add_u32_e32 v188, v188, v189
	v_mul_u32_u24_e32 v188, 0x1000, v188
	v_add_u32_e32 v188, v188, v187
	v_mov_b32_e32 v164, v188
	v_add_u32_e32 v166, 0x40000, v188
	v_add_u32_e32 v166, 0x40000, v188
	v_and_b32_e32 v188, 15, v183
	v_lshrrev_b32_e32 v189, 4, v183
	v_and_b32_e32 v190, 6, v188
	v_xor_b32_e32 v189, v189, v190
	v_lshlrev_b32_e32 v189, 4, v189
	v_lshl_or_b32 v189, v188, 7, v189
	v_lshrrev_b32_e32 v190, 2, v185
	v_lshl_add_u32 v190, v190, 13, v189
	v_add_u32_e32 v241, 0x0, v190
	v_and_b32_e32 v188, 3, v185
	v_lshl_add_u32 v188, v188, 12, v189
	v_add_u32_e32 v229, 0x0, v188
	v_add_u32_e32 v231, 0x10000, v188
	v_add_u32_e32 v242, 0x14000, v188
	v_mov_b32_e32 v173, 0x0
	v_mov_b32_e32 v175, 0x0
	global_load_lds_dwordx4 v164, s[8:9]
	s_add_i32 m0, s44, 0x12000
	v_or3_b32 v0, v221, v9, v218
	s_add_u32 s6, s80, s6
	global_load_lds_dwordx4 v166, s[8:9]
	s_addc_u32 s7, s81, s7
	s_mov_b32 m0, s44
	s_add_i32 s45, s44, 0x2000
	global_load_lds_dwordx4 v170, s[6:7]
	s_mov_b32 m0, s45
	s_add_u32 s14, s8, 0x1600000
	global_load_lds_dwordx4 v168, s[6:7]
	s_addc_u32 s15, s9, 0
	s_add_i32 m0, s44, 0x14000
	v_mov_b32_e32 v165, 0
	global_load_lds_dwordx4 v164, s[14:15]
	s_add_i32 m0, s44, 0x16000
	v_mov_b32_e32 v167, v165
	global_load_lds_dwordx4 v166, s[14:15]
	s_add_u32 s14, s6, 0x40000
	s_addc_u32 s15, s7, 0
	s_add_i32 s46, s44, 0x4000
	s_mov_b32 m0, s46
	s_add_i32 s47, s44, 0x6000
	global_load_lds_dwordx4 v170, s[14:15]
	s_mov_b32 m0, s47
	v_mov_b32_e32 v171, v165
	global_load_lds_dwordx4 v168, s[14:15]
	v_mov_b32_e32 v169, v165
	s_mov_b32 s48, 0
	v_lshl_add_u64 v[6:7], s[8:9], 0, v[164:165]
	v_lshl_add_u64 v[4:5], s[8:9], 0, v[166:167]
	v_lshl_add_u64 v[2:3], s[6:7], 0, v[170:171]
	s_cmp_lg_u32 s5, 1
	v_lshl_add_u64 v[0:1], s[6:7], 0, v[168:169]
	s_cbranch_scc1 .LBB0_358
	s_barrier
.LBB0_358:
	s_mov_b64 s[14:15], 0x80
	s_lshl_b32 s1, s10, 5
	s_add_i32 m0, s44, 0x18000
	v_lshl_add_u64 v[6:7], v[6:7], 0, s[14:15]
	s_and_b32 s49, s1, 0x60
	s_waitcnt vmcnt(4)
	s_barrier
	global_load_lds_dwordx4 v[6:7], off
	v_lshl_add_u64 v[4:5], v[4:5], 0, s[14:15]
	s_add_i32 m0, s44, 0x1a000
	s_add_i32 s52, s44, 0x8000
	s_add_i32 s53, s44, 0xa000
	global_load_lds_dwordx4 v[4:5], off
	v_lshl_add_u64 v[2:3], v[2:3], 0, s[14:15]
	s_mov_b32 m0, s52
	s_add_u32 s10, s8, 0x1600080
	global_load_lds_dwordx4 v[2:3], off
	v_lshl_add_u64 v[0:1], v[0:1], 0, s[14:15]
	s_mov_b32 m0, s53
	s_addc_u32 s11, s9, 0
	global_load_lds_dwordx4 v[0:1], off
	s_add_i32 m0, s44, 0x1c000
	v_lshl_add_u64 v[0:1], s[10:11], 0, v[164:165]
	global_load_lds_dwordx4 v[0:1], off
	v_lshl_add_u64 v[0:1], s[10:11], 0, v[166:167]
	s_add_i32 m0, s44, 0x1e000
	s_ashr_i32 s54, s94, 31
	global_load_lds_dwordx4 v[0:1], off
	s_lshl_b32 s56, s5, 7
	s_lshl_b32 s57, s5, 2
	s_add_u32 s16, s82, 0xb000
	s_addc_u32 s17, s83, 0
	s_add_u32 s18, s82, 0x16000
	s_addc_u32 s19, s83, 0
	s_add_u32 s20, s82, 0x5800
	s_addc_u32 s21, s83, 0
	s_add_u32 s22, s82, 0x10800
	v_add3_u32 v0, v9, v221, v218
	s_addc_u32 s23, s83, 0
	v_lshl_or_b32 v0, v0, 12, v226
	s_sext_i32_i16 s1, s4
	v_lshl_or_b32 v2, s5, 13, v230
	s_add_u32 s24, s82, 0x1b800
	v_add_u32_e32 v0, v0, v224
	v_mov_b32_e32 v1, v165
	s_mov_b64 s[4:5], 0x40080
	s_addc_u32 s25, s83, 0
	v_add3_u32 v0, v8, v220, v218
	s_waitcnt vmcnt(6)
	s_add_u32 s26, s84, 0x5800
	v_lshl_or_b32 v0, v0, 12, v226
	s_addc_u32 s27, s85, 0
	v_add_u32_e32 v0, v0, v224
	s_add_i32 s58, 0, 0x10000
	s_add_i32 s59, 0, 0x14000
	s_mov_b32 s55, s94
	v_mov_b64_e32 v[176:177], 0xb00
	v_mov_b64_e32 v[178:179], 0xaff
	v_mov_b32_e32 v243, 0x3727c5ac
	s_mov_b32 s60, 0xb000
	s_movk_i32 s61, 0x2c00
	s_barrier
	s_branch .LBB0_360

.LBB0_363:
	ds_read_b128 v[76:79], v231
	v_xor_b32_e32 v91, 64, v231
	ds_read_b128 v[80:83], v91
	ds_read_b128 v[84:87], v231 offset:2048
	ds_read_b128 v[88:91], v91 offset:2048
	s_add_u32 s8, s6, 0x100
	s_addc_u32 s9, s7, 0
	s_cmp_eq_u32 s65, 28
	s_cselect_b32 s39, s31, s9
	s_cselect_b32 s38, s33, s8
	s_cselect_b32 s11, s29, s64
	s_cselect_b32 s10, s62, s63
	v_lshl_add_u64 v[108:109], s[6:7], 0, v[172:173]
	s_add_i32 m0, s44, 0xc000
	ds_read_b128 v[92:95], v241
	v_xor_b32_e32 v195, 64, v241
	ds_read_b128 v[96:99], v195
	ds_read_b128 v[100:103], v241 offset:2048
	ds_read_b128 v[104:107], v195 offset:2048
	ds_read_b128 v[180:183], v241 offset:4096
	ds_read_b128 v[184:187], v195 offset:4096
	ds_read_b128 v[188:191], v241 offset:6144
	ds_read_b128 v[192:195], v195 offset:6144
	global_load_lds_dwordx4 v[108:109], off
	v_lshl_add_u64 v[108:109], s[6:7], 0, v[174:175]
	s_add_i32 m0, s44, 0xe000
	s_nop 0
	global_load_lds_dwordx4 v[108:109], off
	s_waitcnt lgkmcnt(8)
	s_barrier
	s_waitcnt lgkmcnt(0)
	s_setprio 1
	s_waitcnt lgkmcnt(0)
	v_mfma_f32_16x16x32_bf16 v[158:161], v[76:79], v[92:95], v[158:161]
	v_mfma_f32_16x16x32_bf16 v[60:63], v[84:87], v[92:95], v[60:63]
	v_mfma_f32_16x16x32_bf16 v[150:153], v[76:79], v[100:103], v[150:153]
	v_mfma_f32_16x16x32_bf16 v[52:55], v[84:87], v[100:103], v[52:55]
	v_mfma_f32_16x16x32_bf16 v[146:149], v[76:79], v[180:183], v[146:149]
	v_mfma_f32_16x16x32_bf16 v[48:51], v[84:87], v[180:183], v[48:51]
	v_mfma_f32_16x16x32_bf16 v[138:141], v[76:79], v[188:191], v[138:141]
	v_mfma_f32_16x16x32_bf16 v[40:43], v[84:87], v[188:191], v[40:43]
	v_mfma_f32_16x16x32_bf16 v[158:161], v[80:83], v[96:99], v[158:161]
	v_mfma_f32_16x16x32_bf16 v[60:63], v[88:91], v[96:99], v[60:63]
	v_mfma_f32_16x16x32_bf16 v[150:153], v[80:83], v[104:107], v[150:153]
	v_mfma_f32_16x16x32_bf16 v[52:55], v[88:91], v[104:107], v[52:55]
	v_mfma_f32_16x16x32_bf16 v[146:149], v[80:83], v[184:187], v[146:149]
	v_mfma_f32_16x16x32_bf16 v[48:51], v[88:91], v[184:187], v[48:51]
	v_mfma_f32_16x16x32_bf16 v[138:141], v[80:83], v[192:195], v[138:141]
	v_mfma_f32_16x16x32_bf16 v[40:43], v[88:91], v[192:195], v[40:43]
	s_setprio 0
	s_barrier
	s_add_i32 s6, s58, s42
	v_lshl_add_u64 v[216:217], s[10:11], 0, v[164:165]
	s_mov_b32 m0, s6
	ds_read_b128 v[196:199], v242
	v_xor_b32_e32 v211, 64, v242
	ds_read_b128 v[200:203], v211
	ds_read_b128 v[204:207], v242 offset:2048
	ds_read_b128 v[208:211], v211 offset:2048
	global_load_lds_dwordx4 v[216:217], off
	v_lshl_add_u64 v[244:245], s[10:11], 0, v[166:167]
	s_add_i32 m0, s6, 0x2000
	s_nop 0
	global_load_lds_dwordx4 v[244:245], off
	s_barrier
	s_waitcnt lgkmcnt(0)
	s_setprio 1
	s_waitcnt lgkmcnt(0)
	v_mfma_f32_16x16x32_bf16 v[154:157], v[196:199], v[92:95], v[154:157]
	v_mfma_f32_16x16x32_bf16 v[56:59], v[204:207], v[92:95], v[56:59]
	v_mfma_f32_16x16x32_bf16 v[44:47], v[204:207], v[100:103], v[44:47]
	v_mfma_f32_16x16x32_bf16 v[36:39], v[204:207], v[180:183], v[36:39]
	v_mfma_f32_16x16x32_bf16 v[32:35], v[204:207], v[188:191], v[32:35]
	v_mfma_f32_16x16x32_bf16 v[154:157], v[200:203], v[96:99], v[154:157]
	v_mfma_f32_16x16x32_bf16 v[56:59], v[208:211], v[96:99], v[56:59]
	v_mfma_f32_16x16x32_bf16 v[92:95], v[196:199], v[100:103], v[142:145]
	v_mfma_f32_16x16x32_bf16 v[44:47], v[208:211], v[104:107], v[44:47]
	v_mfma_f32_16x16x32_bf16 v[96:99], v[196:199], v[180:183], v[134:137]
	v_mfma_f32_16x16x32_bf16 v[36:39], v[208:211], v[184:187], v[36:39]
	v_mfma_f32_16x16x32_bf16 v[100:103], v[196:199], v[188:191], v[130:133]
	v_mfma_f32_16x16x32_bf16 v[32:35], v[208:211], v[192:195], v[32:35]
	v_mfma_f32_16x16x32_bf16 v[92:95], v[200:203], v[104:107], v[92:95]
	v_mfma_f32_16x16x32_bf16 v[96:99], v[200:203], v[184:187], v[96:99]
	v_mfma_f32_16x16x32_bf16 v[100:103], v[200:203], v[192:195], v[100:103]
	s_setprio 0
	s_mov_b32 m0, s44
	v_lshl_add_u64 v[246:247], s[38:39], 0, v[170:171]
	s_barrier
	ds_read_b128 v[104:107], v241 offset:16384
	v_xor_b32_e32 v195, 64, v241
	ds_read_b128 v[130:133], v195 offset:16384
	ds_read_b128 v[134:137], v241 offset:18432
	ds_read_b128 v[142:145], v195 offset:18432
	ds_read_b128 v[180:183], v241 offset:20480
	ds_read_b128 v[184:187], v195 offset:20480
	ds_read_b128 v[188:191], v241 offset:22528
	ds_read_b128 v[192:195], v195 offset:22528
	global_load_lds_dwordx4 v[246:247], off
	v_lshl_add_u64 v[248:249], s[38:39], 0, v[168:169]
	s_mov_b32 m0, s45
	s_nop 0
	global_load_lds_dwordx4 v[248:249], off
	s_barrier
	s_waitcnt lgkmcnt(0)
	s_setprio 1
	s_waitcnt lgkmcnt(0)
	v_mfma_f32_16x16x32_bf16 v[126:129], v[76:79], v[104:107], v[126:129]
	v_mfma_f32_16x16x32_bf16 v[28:31], v[84:87], v[104:107], v[28:31]
	v_mfma_f32_16x16x32_bf16 v[122:125], v[76:79], v[134:137], v[122:125]
	v_mfma_f32_16x16x32_bf16 v[24:27], v[84:87], v[134:137], v[24:27]
	v_mfma_f32_16x16x32_bf16 v[114:117], v[76:79], v[180:183], v[114:117]
	v_mfma_f32_16x16x32_bf16 v[20:23], v[84:87], v[180:183], v[20:23]
	v_mfma_f32_16x16x32_bf16 v[72:75], v[76:79], v[188:191], v[72:75]
	v_mfma_f32_16x16x32_bf16 v[4:7], v[84:87], v[188:191], v[4:7]
	v_mfma_f32_16x16x32_bf16 v[126:129], v[80:83], v[130:133], v[126:129]
	v_mfma_f32_16x16x32_bf16 v[28:31], v[88:91], v[130:133], v[28:31]
	v_mfma_f32_16x16x32_bf16 v[122:125], v[80:83], v[142:145], v[122:125]
	v_mfma_f32_16x16x32_bf16 v[24:27], v[88:91], v[142:145], v[24:27]
	v_mfma_f32_16x16x32_bf16 v[114:117], v[80:83], v[184:187], v[114:117]
	v_mfma_f32_16x16x32_bf16 v[20:23], v[88:91], v[184:187], v[20:23]
	v_mfma_f32_16x16x32_bf16 v[72:75], v[80:83], v[192:195], v[72:75]
	v_mfma_f32_16x16x32_bf16 v[4:7], v[88:91], v[192:195], v[4:7]
	s_setprio 0
	s_barrier
	s_add_u32 s6, s10, 0x1600000
	s_addc_u32 s7, s11, 0
	s_add_i32 s66, s59, s42
	v_lshl_add_u64 v[76:77], s[6:7], 0, v[164:165]
	s_mov_b32 m0, s66
	s_nop 0
	global_load_lds_dwordx4 v[76:77], off
	v_lshl_add_u64 v[76:77], s[6:7], 0, v[166:167]
	s_add_i32 m0, s66, 0x2000
	s_nop 0
	global_load_lds_dwordx4 v[76:77], off
	s_waitcnt vmcnt(6)
	s_barrier
	s_setprio 1
	v_mfma_f32_16x16x32_bf16 v[16:19], v[204:207], v[104:107], v[16:19]
	v_mfma_f32_16x16x32_bf16 v[12:15], v[204:207], v[134:137], v[12:15]
	v_mfma_f32_16x16x32_bf16 v[68:71], v[196:199], v[180:183], v[68:71]
	v_mfma_f32_16x16x32_bf16 v[8:11], v[204:207], v[180:183], v[8:11]
	v_mfma_f32_16x16x32_bf16 v[64:67], v[196:199], v[188:191], v[64:67]
	v_mfma_f32_16x16x32_bf16 v[0:3], v[204:207], v[188:191], v[0:3]
	v_mfma_f32_16x16x32_bf16 v[76:79], v[196:199], v[104:107], v[118:121]
	v_mfma_f32_16x16x32_bf16 v[16:19], v[208:211], v[130:133], v[16:19]
	v_mfma_f32_16x16x32_bf16 v[80:83], v[196:199], v[134:137], v[110:113]
	v_mfma_f32_16x16x32_bf16 v[12:15], v[208:211], v[142:145], v[12:15]
	v_mfma_f32_16x16x32_bf16 v[68:71], v[200:203], v[184:187], v[68:71]
	v_mfma_f32_16x16x32_bf16 v[8:11], v[208:211], v[184:187], v[8:11]
	v_mfma_f32_16x16x32_bf16 v[64:67], v[200:203], v[192:195], v[64:67]
	v_mfma_f32_16x16x32_bf16 v[0:3], v[208:211], v[192:195], v[0:3]
	v_mfma_f32_16x16x32_bf16 v[76:79], v[200:203], v[130:133], v[76:79]
	v_mfma_f32_16x16x32_bf16 v[80:83], v[200:203], v[142:145], v[80:83]
	s_setprio 0
	s_add_i32 s66, 0, 0x18000
	v_add_u32_e32 v108, s66, v229
	s_barrier
	ds_read_b128 v[84:87], v108
	v_xor_b32_e32 v111, 64, v108
	ds_read_b128 v[88:91], v111
	ds_read_b128 v[104:107], v108 offset:2048
	ds_read_b128 v[108:111], v111 offset:2048
	s_add_u32 s6, s38, 0x40000
	s_addc_u32 s7, s39, 0
	s_mov_b32 m0, s46
	v_lshl_add_u64 v[112:113], s[6:7], 0, v[170:171]
	ds_read_b128 v[118:121], v241 offset:32768
	v_xor_b32_e32 v199, 64, v241
	ds_read_b128 v[130:133], v199 offset:32768
	ds_read_b128 v[134:137], v241 offset:34816
	ds_read_b128 v[180:183], v199 offset:34816
	ds_read_b128 v[184:187], v241 offset:36864
	ds_read_b128 v[188:191], v199 offset:36864
	ds_read_b128 v[192:195], v241 offset:38912
	ds_read_b128 v[196:199], v199 offset:38912
	global_load_lds_dwordx4 v[112:113], off
	v_lshl_add_u64 v[112:113], s[6:7], 0, v[168:169]
	s_mov_b32 m0, s47
	s_nop 0
	global_load_lds_dwordx4 v[112:113], off
	s_waitcnt lgkmcnt(8)
	s_barrier
	s_waitcnt lgkmcnt(0)
	s_setprio 1
	s_waitcnt lgkmcnt(0)
	v_mfma_f32_16x16x32_bf16 v[142:145], v[84:87], v[118:121], v[158:161]
	v_mfma_f32_16x16x32_bf16 v[158:161], v[88:91], v[130:133], v[142:145]
	v_mfma_f32_16x16x32_bf16 v[142:145], v[84:87], v[134:137], v[150:153]
	v_mfma_f32_16x16x32_bf16 v[60:63], v[104:107], v[118:121], v[60:63]
	v_mfma_f32_16x16x32_bf16 v[150:153], v[88:91], v[180:183], v[142:145]
	v_mfma_f32_16x16x32_bf16 v[52:55], v[104:107], v[134:137], v[52:55]
	v_mfma_f32_16x16x32_bf16 v[142:145], v[84:87], v[184:187], v[146:149]
	v_mfma_f32_16x16x32_bf16 v[48:51], v[104:107], v[184:187], v[48:51]
	v_mfma_f32_16x16x32_bf16 v[138:141], v[84:87], v[192:195], v[138:141]
	v_mfma_f32_16x16x32_bf16 v[40:43], v[104:107], v[192:195], v[40:43]
	v_mfma_f32_16x16x32_bf16 v[60:63], v[108:111], v[130:133], v[60:63]
	v_mfma_f32_16x16x32_bf16 v[52:55], v[108:111], v[180:183], v[52:55]
	v_mfma_f32_16x16x32_bf16 v[146:149], v[88:91], v[188:191], v[142:145]
	v_mfma_f32_16x16x32_bf16 v[48:51], v[108:111], v[188:191], v[48:51]
	v_mfma_f32_16x16x32_bf16 v[138:141], v[88:91], v[196:199], v[138:141]
	v_mfma_f32_16x16x32_bf16 v[40:43], v[108:111], v[196:199], v[40:43]
	s_setprio 0
	s_barrier
	s_add_i32 s38, 0, 0x1c000
	v_add_u32_e32 v112, s38, v229
	s_add_i32 s6, s66, s42
	ds_read_b128 v[200:203], v112
	v_xor_b32_e32 v215, 64, v112
	ds_read_b128 v[204:207], v215
	ds_read_b128 v[208:211], v112 offset:2048
	ds_read_b128 v[212:215], v215 offset:2048
	v_lshl_add_u64 v[112:113], v[216:217], 0, s[14:15]
	s_mov_b32 m0, s6
	s_nop 0
	global_load_lds_dwordx4 v[112:113], off
	v_lshl_add_u64 v[112:113], v[244:245], 0, s[14:15]
	s_add_i32 m0, s6, 0x2000
	s_nop 0
	global_load_lds_dwordx4 v[112:113], off
	s_barrier
	s_waitcnt lgkmcnt(0)
	s_setprio 1
	s_waitcnt lgkmcnt(0)
	v_mfma_f32_16x16x32_bf16 v[142:145], v[200:203], v[118:121], v[154:157]
	v_mfma_f32_16x16x32_bf16 v[92:95], v[200:203], v[134:137], v[92:95]
	v_mfma_f32_16x16x32_bf16 v[154:157], v[204:207], v[130:133], v[142:145]
	v_mfma_f32_16x16x32_bf16 v[142:145], v[204:207], v[180:183], v[92:95]
	v_mfma_f32_16x16x32_bf16 v[92:95], v[200:203], v[184:187], v[96:99]
	v_mfma_f32_16x16x32_bf16 v[56:59], v[208:211], v[118:121], v[56:59]
	v_mfma_f32_16x16x32_bf16 v[44:47], v[208:211], v[134:137], v[44:47]
	v_mfma_f32_16x16x32_bf16 v[134:137], v[204:207], v[188:191], v[92:95]
	v_mfma_f32_16x16x32_bf16 v[36:39], v[208:211], v[184:187], v[36:39]
	v_mfma_f32_16x16x32_bf16 v[92:95], v[200:203], v[192:195], v[100:103]
	v_mfma_f32_16x16x32_bf16 v[32:35], v[208:211], v[192:195], v[32:35]
	v_mfma_f32_16x16x32_bf16 v[56:59], v[212:215], v[130:133], v[56:59]
	v_mfma_f32_16x16x32_bf16 v[44:47], v[212:215], v[180:183], v[44:47]
	v_mfma_f32_16x16x32_bf16 v[36:39], v[212:215], v[188:191], v[36:39]
	v_mfma_f32_16x16x32_bf16 v[130:133], v[204:207], v[196:199], v[92:95]
	v_mfma_f32_16x16x32_bf16 v[32:35], v[212:215], v[196:199], v[32:35]
	s_setprio 0
	s_mov_b32 m0, s52
	v_lshl_add_u64 v[112:113], v[246:247], 0, s[14:15]
	s_barrier
	ds_read_b128 v[92:95], v241 offset:49152
	v_xor_b32_e32 v199, 64, v241
	ds_read_b128 v[96:99], v199 offset:49152
	ds_read_b128 v[100:103], v241 offset:51200
	ds_read_b128 v[180:183], v199 offset:51200
	ds_read_b128 v[184:187], v241 offset:53248
	ds_read_b128 v[188:191], v199 offset:53248
	ds_read_b128 v[192:195], v241 offset:55296
	ds_read_b128 v[196:199], v199 offset:55296
	global_load_lds_dwordx4 v[112:113], off
	v_lshl_add_u64 v[112:113], v[248:249], 0, s[14:15]
	s_mov_b32 m0, s53
	s_nop 0
	global_load_lds_dwordx4 v[112:113], off
	s_barrier
	s_waitcnt lgkmcnt(0)
	s_setprio 1
	s_waitcnt lgkmcnt(0)
	v_mfma_f32_16x16x32_bf16 v[118:121], v[84:87], v[92:95], v[126:129]
	v_mfma_f32_16x16x32_bf16 v[126:129], v[88:91], v[96:99], v[118:121]
	v_mfma_f32_16x16x32_bf16 v[28:31], v[104:107], v[92:95], v[28:31]
	v_mfma_f32_16x16x32_bf16 v[118:121], v[84:87], v[100:103], v[122:125]
	v_mfma_f32_16x16x32_bf16 v[24:27], v[104:107], v[100:103], v[24:27]
	v_mfma_f32_16x16x32_bf16 v[112:115], v[84:87], v[184:187], v[114:117]
	v_mfma_f32_16x16x32_bf16 v[20:23], v[104:107], v[184:187], v[20:23]
	v_mfma_f32_16x16x32_bf16 v[72:75], v[84:87], v[192:195], v[72:75]
	v_mfma_f32_16x16x32_bf16 v[4:7], v[104:107], v[192:195], v[4:7]
	v_mfma_f32_16x16x32_bf16 v[28:31], v[108:111], v[96:99], v[28:31]
	v_mfma_f32_16x16x32_bf16 v[122:125], v[88:91], v[180:183], v[118:121]
	v_mfma_f32_16x16x32_bf16 v[24:27], v[108:111], v[180:183], v[24:27]
	v_mfma_f32_16x16x32_bf16 v[114:117], v[88:91], v[188:191], v[112:115]
	v_mfma_f32_16x16x32_bf16 v[20:23], v[108:111], v[188:191], v[20:23]
	v_mfma_f32_16x16x32_bf16 v[72:75], v[88:91], v[196:199], v[72:75]
	v_mfma_f32_16x16x32_bf16 v[4:7], v[108:111], v[196:199], v[4:7]
	s_setprio 0
	s_barrier
	s_add_u32 s6, s10, 0x1600080
	s_addc_u32 s7, s11, 0
	s_add_i32 s10, s38, s42
	v_lshl_add_u64 v[84:85], s[6:7], 0, v[164:165]
	s_mov_b32 m0, s10
	s_nop 0
	global_load_lds_dwordx4 v[84:85], off
	v_lshl_add_u64 v[84:85], s[6:7], 0, v[166:167]
	s_add_i32 m0, s10, 0x2000
	s_nop 0
	global_load_lds_dwordx4 v[84:85], off
	s_waitcnt vmcnt(6)
	s_barrier
	s_setprio 1
	v_mfma_f32_16x16x32_bf16 v[76:79], v[200:203], v[92:95], v[76:79]
	v_mfma_f32_16x16x32_bf16 v[118:121], v[204:207], v[96:99], v[76:79]
	v_mfma_f32_16x16x32_bf16 v[16:19], v[208:211], v[92:95], v[16:19]
	v_mfma_f32_16x16x32_bf16 v[76:79], v[200:203], v[100:103], v[80:83]
	v_mfma_f32_16x16x32_bf16 v[12:15], v[208:211], v[100:103], v[12:15]
	v_mfma_f32_16x16x32_bf16 v[68:71], v[200:203], v[184:187], v[68:71]
	v_mfma_f32_16x16x32_bf16 v[8:11], v[208:211], v[184:187], v[8:11]
	v_mfma_f32_16x16x32_bf16 v[64:67], v[200:203], v[192:195], v[64:67]
	v_mfma_f32_16x16x32_bf16 v[0:3], v[208:211], v[192:195], v[0:3]
	v_mfma_f32_16x16x32_bf16 v[16:19], v[212:215], v[96:99], v[16:19]
	v_mfma_f32_16x16x32_bf16 v[110:113], v[204:207], v[180:183], v[76:79]
	v_mfma_f32_16x16x32_bf16 v[12:15], v[212:215], v[180:183], v[12:15]
	v_mfma_f32_16x16x32_bf16 v[68:71], v[204:207], v[188:191], v[68:71]
	v_mfma_f32_16x16x32_bf16 v[8:11], v[212:215], v[188:191], v[8:11]
	v_mfma_f32_16x16x32_bf16 v[64:67], v[204:207], v[196:199], v[64:67]
	v_mfma_f32_16x16x32_bf16 v[0:3], v[212:215], v[196:199], v[0:3]
	s_setprio 0
	s_add_i32 s65, s65, 2
	s_add_u32 s63, s63, 0x100
	s_addc_u32 s64, s64, 0
	s_cmp_gt_u32 s65, 29
	s_mov_b64 s[6:7], s[8:9]
	s_barrier
	s_cbranch_scc0 .LBB0_363
	s_lshl_b32 s6, s0, 8
	s_lshl_b32 s1, s1, 7
	v_mov_b32_e32 v185, v163
	v_mov_b32_e32 v80, v225
	s_add_i32 s6, s6, s56
	s_or_b32 s1, s1, s49
	s_lshl_b32 s0, s0, 3
	v_add_u32_e32 v182, s6, v185
	v_lshl_add_u32 v180, v80, 3, s1
	v_ashrrev_i32_e32 v183, 31, v182
	v_ashrrev_i32_e32 v181, 31, v180
	v_lshl_add_u64 v[78:79], v[182:183], 2, s[12:13]
	v_lshlrev_b64 v[90:91], 2, v[180:181]
	global_load_dword v188, v[78:79], off
	global_load_dword v184, v[78:79], off offset:64
	global_load_dword v186, v[78:79], off offset:128
	global_load_dword v196, v[78:79], off offset:192
	global_load_dword v195, v[78:79], off offset:256
	global_load_dword v77, v[78:79], off offset:320
	global_load_dword v76, v[78:79], off offset:384
	global_load_dword v183, v[78:79], off offset:448
	v_lshl_add_u64 v[190:191], s[82:83], 0, v[90:91]
	v_lshl_add_u64 v[78:79], s[16:17], 0, v[90:91]
	v_lshl_add_u64 v[80:81], s[18:19], 0, v[90:91]
	global_load_dwordx4 v[94:97], v[190:191], off
	global_load_dwordx4 v[102:105], v[78:79], off
	global_load_dwordx4 v[98:101], v[80:81], off
	v_lshl_add_u64 v[192:193], s[84:85], 0, v[90:91]
	v_lshl_add_u64 v[78:79], s[20:21], 0, v[90:91]
	v_lshl_add_u64 v[80:81], s[22:23], 0, v[90:91]
	v_lshl_add_u64 v[82:83], s[24:25], 0, v[90:91]
	v_lshl_add_u64 v[90:91], s[26:27], 0, v[90:91]
	global_load_dwordx4 v[106:109], v[192:193], off
	global_load_dwordx4 v[86:89], v[78:79], off
	s_nop 0
	global_load_dwordx4 v[78:81], v[80:81], off
	s_add_i32 s0, s0, s57
	global_load_dwordx4 v[82:85], v[82:83], off
	v_add_u32_e32 v187, s0, v185
	global_load_dwordx4 v[90:93], v[90:91], off
	v_cmp_gt_i32_e64 s[10:11], 2, v185
	s_waitcnt vmcnt(0)
	v_fmamk_f32 v188, v188, 0x3a000000, v243
	v_rsq_f32_e32 v194, v188
	v_mad_i64_i32 v[188:189], s[0:1], v187, s60, 0
	v_lshl_add_u64 v[188:189], s[70:71], 0, v[188:189]
	v_pk_mul_f32 v[160:161], v[160:161], v[194:195] op_sel_hi:[1,0]
	v_pk_mul_f32 v[158:159], v[158:159], v[194:195] op_sel_hi:[1,0]
	v_pk_mul_f32 v[156:157], v[156:157], v[194:195] op_sel_hi:[1,0]
	v_pk_mul_f32 v[154:155], v[154:155], v[194:195] op_sel_hi:[1,0]
	v_lshl_add_u64 v[188:189], v[180:181], 2, v[188:189]
	s_and_saveexec_b64 s[0:1], s[10:11]
	s_cbranch_execz .LBB0_366
	v_add_co_u32_e32 v198, vcc, 0x5000, v188
	global_store_dwordx4 v[188:189], v[158:161], off
	s_nop 0
	v_addc_co_u32_e32 v199, vcc, 0, v189, vcc
	global_store_dwordx4 v[198:199], v[154:157], off offset:2048

.LBB0_492:
	v_lshrrev_b32_e32 v0, 1, v219
	v_mul_u32_u24_e32 v231, 0x1600, v236
	v_or_b32_e32 v1, v0, v231
	v_lshlrev_b32_e32 v168, 1, v1
	v_mul_u32_u24_e32 v1, 0x1600, v232
	v_or_b32_e32 v1, v1, v0
	v_mul_u32_u24_e32 v232, 0x1600, v237
	v_lshlrev_b32_e32 v170, 1, v1
	v_or_b32_e32 v1, v232, v0
	v_lshlrev_b32_e32 v172, 1, v1
	v_mul_u32_u24_e32 v1, 0x1600, v240
	v_readlane_b32 s0, v255, 8
	v_or_b32_e32 v0, v1, v0
	s_add_u32 s14, s92, 0x20000
	v_readlane_b32 s1, v255, 9
	s_addc_u32 s15, s93, 0
	s_and_b64 vcc, exec, s[0:1]
	v_lshlrev_b32_e32 v174, 1, v0
	s_cbranch_vccnz .LBB0_528
	s_add_u32 s18, s92, 0x4d00000
	s_addc_u32 s19, s93, 0
	s_lshr_b32 s4, s3, 6
	s_lshr_b32 s5, s3, 8
	s_lshl_b32 s20, s4, 10
	s_mul_i32 s7, s37, 0x2c0000
	s_mul_hi_i32 s6, s37, 0x2c0000
	s_add_u32 s16, s18, s7
	s_addc_u32 s17, s19, s6
	s_add_i32 s21, s20, 0
	s_add_i32 m0, s21, 0x10000
	s_mul_i32 s0, s38, 0x2c0000
	v_and_b32_e32 v136, 63, v222
	v_lshrrev_b32_e32 v137, 3, v136
	v_lshrrev_b32_e32 v138, 6, v222
	v_lshl_add_u32 v139, v138, 3, v137
	v_and_b32_e32 v146, 7, v136
	v_and_b32_e32 v147, 6, v137
	v_xor_b32_e32 v146, v146, v147
	v_lshlrev_b32_e32 v146, 4, v146
	v_mul_u32_u24_e32 v147, 0x2c00, v139
	v_add_u32_e32 v147, v147, v146
	v_mov_b32_e32 v128, v147
	v_add_u32_e32 v130, 0xb0000, v147
	v_mov_b32_e32 v168, v147
	v_add_u32_e32 v172, 0xb0000, v147
	v_add_u32_e32 v130, 0xb0000, v147
	v_add_u32_e32 v172, 0xb0000, v147
	v_and_b32_e32 v147, 31, v139
	v_and_b32_e32 v148, 12, v147
	v_lshlrev_b32_e32 v148, 1, v148
	v_lshrrev_b32_e32 v149, 4, v147
	v_lshlrev_b32_e32 v149, 2, v149
	v_and_b32_e32 v147, 3, v147
	v_or3_b32 v147, v148, v149, v147
	v_and_b32_e32 v148, 0x60, v139
	v_add_u32_e32 v147, v147, v148
	v_mul_u32_u24_e32 v147, 0x2c00, v147
	v_add_u32_e32 v147, v147, v146
	v_mov_b32_e32 v170, v147
	v_add_u32_e32 v174, 0xb0000, v147
	v_add_u32_e32 v174, 0xb0000, v147
	v_and_b32_e32 v147, 15, v136
	v_lshrrev_b32_e32 v148, 4, v136
	v_and_b32_e32 v149, 6, v147
	v_xor_b32_e32 v148, v148, v149
	v_lshlrev_b32_e32 v148, 4, v148
	v_lshl_or_b32 v148, v147, 7, v148
	v_lshrrev_b32_e32 v149, 2, v138
	v_lshl_add_u32 v149, v149, 13, v148
	v_add_u32_e32 v142, 0x0, v149
	v_and_b32_e32 v147, 3, v138
	v_lshl_add_u32 v147, v147, 12, v148
	v_add_u32_e32 v140, 0x0, v147
	v_add_u32_e32 v141, 0x10000, v147
	v_add_u32_e32 v143, 0x14000, v147
	v_add_u32_e32 v145, 0x0, v147
	global_load_lds_dwordx4 v170, s[16:17]
	s_add_i32 m0, s21, 0x12000
	s_mul_hi_i32 s1, s38, 0x2c0000
	s_add_u32 s0, s96, s0
	global_load_lds_dwordx4 v174, s[16:17]
	s_addc_u32 s1, s97, s1
	s_mov_b32 m0, s21
	s_add_i32 s22, s21, 0x2000
	global_load_lds_dwordx4 v168, s[0:1]
	s_mov_b32 m0, s22
	s_add_u32 s6, s16, 0x160000
	global_load_lds_dwordx4 v172, s[0:1]
	s_addc_u32 s7, s17, 0
	s_add_i32 m0, s21, 0x14000
	v_mov_b32_e32 v171, 0
	global_load_lds_dwordx4 v170, s[6:7]
	s_add_i32 m0, s21, 0x16000
	v_mov_b32_e32 v175, v171
	global_load_lds_dwordx4 v174, s[6:7]
	s_add_u32 s6, s0, 0x160000
	s_addc_u32 s7, s1, 0
	s_add_i32 s23, s21, 0x4000
	s_mov_b32 m0, s23
	s_add_i32 s24, s21, 0x6000
	global_load_lds_dwordx4 v168, s[6:7]
	s_mov_b32 m0, s24
	v_mov_b32_e32 v169, v171
	global_load_lds_dwordx4 v172, s[6:7]
	v_mov_b32_e32 v173, v171
	s_mov_b32 s25, 0
	v_lshl_add_u64 v[6:7], s[16:17], 0, v[170:171]
	v_lshl_add_u64 v[4:5], s[16:17], 0, v[174:175]
	v_lshl_add_u64 v[2:3], s[0:1], 0, v[168:169]
	s_cmp_lg_u32 s5, 1
	v_lshl_add_u64 v[0:1], s[0:1], 0, v[172:173]
	s_cbranch_scc1 .LBB0_495
	s_barrier
.LBB0_495:
	s_lshl_b32 s4, s4, 5
	s_lshl_b32 s26, s5, 6
	s_lshl_b32 s8, s5, 13
	s_and_b32 s27, s4, 0x60
	s_mov_b64 s[4:5], 0x80
	s_add_i32 m0, s21, 0x18000
	v_lshl_add_u64 v[6:7], v[6:7], 0, s[4:5]
	s_waitcnt vmcnt(4)
	s_barrier
	global_load_lds_dwordx4 v[6:7], off
	v_lshl_add_u64 v[4:5], v[4:5], 0, s[4:5]
	s_add_i32 m0, s21, 0x1a000
	s_add_i32 s28, s21, 0x8000
	s_add_i32 s29, s21, 0xa000
	global_load_lds_dwordx4 v[4:5], off
	v_lshl_add_u64 v[2:3], v[2:3], 0, s[4:5]
	s_mov_b32 m0, s28
	s_add_u32 s6, s16, 0x160080
	global_load_lds_dwordx4 v[2:3], off
	v_lshl_add_u64 v[0:1], v[0:1], 0, s[4:5]
	s_mov_b32 m0, s29
	s_addc_u32 s7, s17, 0
	global_load_lds_dwordx4 v[0:1], off
	s_add_i32 m0, s21, 0x1c000
	v_lshl_add_u64 v[0:1], s[6:7], 0, v[170:171]
	global_load_lds_dwordx4 v[0:1], off
	v_lshl_add_u64 v[0:1], s[6:7], 0, v[174:175]
	s_add_i32 m0, s21, 0x1e000
	global_load_lds_dwordx4 v[0:1], off
	v_lshlrev_b32_e32 v1, 2, v163
	v_lshl_or_b32 v0, v163, 6, v227
	v_and_b32_e32 v1, 32, v1
	v_bitop3_b32 v0, v0, s8, v1 bitop3:0xde
	s_waitcnt vmcnt(6)
	v_add_u16_e32 v1, v226, v224
	v_lshrrev_b16_e32 v1, 1, v1
	s_add_i32 s33, 0, 0x10000
	s_add_i32 s34, 0, 0x14000
	v_mbcnt_lo_u32_b32 v0, -1, 0
	s_ashr_i32 s30, s94, 31
	s_mov_b32 s31, s94
	v_mov_b32_e32 v129, v171
	v_mov_b32_e32 v131, v171
	v_mov_b64_e32 v[132:133], 0x200
	v_mov_b64_e32 v[134:135], 0x1ff
	v_mbcnt_hi_u32_b32 v144, -1, v0
	s_barrier
	s_branch .LBB0_497

.LBB0_508:
	ds_read_b128 v[136:139], v141
	v_xor_b32_e32 v157, 64, v141
	ds_read_b128 v[146:149], v157
	ds_read_b128 v[150:153], v141 offset:2048
	ds_read_b128 v[154:157], v157 offset:2048
	s_add_u32 s8, s0, 0xffea0080
	s_addc_u32 s9, s1, -1
	s_cmpk_eq_i32 s41, 0x54
	s_cselect_b32 s17, s13, s9
	s_cselect_b32 s16, s12, s8
	s_cselect_b32 s9, s11, s40
	s_cselect_b32 s8, s10, s39
	v_lshl_add_u64 v[204:205], s[0:1], 0, v[128:129]
	s_add_i32 m0, s21, 0xc000
	ds_read_b128 v[158:161], v142
	v_xor_b32_e32 v203, 64, v142
	ds_read_b128 v[176:179], v203
	ds_read_b128 v[180:183], v142 offset:2048
	ds_read_b128 v[184:187], v203 offset:2048
	ds_read_b128 v[188:191], v142 offset:4096
	ds_read_b128 v[192:195], v203 offset:4096
	ds_read_b128 v[196:199], v142 offset:6144
	ds_read_b128 v[200:203], v203 offset:6144
	global_load_lds_dwordx4 v[204:205], off
	v_lshl_add_u64 v[204:205], s[0:1], 0, v[130:131]
	s_add_i32 m0, s21, 0xe000
	s_nop 0
	global_load_lds_dwordx4 v[204:205], off
	s_waitcnt lgkmcnt(8)
	s_barrier
	s_waitcnt lgkmcnt(0)
	s_setprio 1
	s_waitcnt lgkmcnt(0)
	v_mfma_f32_16x16x32_bf16 v[124:127], v[136:139], v[158:161], v[124:127]
	v_mfma_f32_16x16x32_bf16 v[120:123], v[150:153], v[158:161], v[120:123]
	v_mfma_f32_16x16x32_bf16 v[108:111], v[136:139], v[180:183], v[108:111]
	v_mfma_f32_16x16x32_bf16 v[104:107], v[150:153], v[180:183], v[104:107]
	v_mfma_f32_16x16x32_bf16 v[92:95], v[136:139], v[188:191], v[92:95]
	v_mfma_f32_16x16x32_bf16 v[88:91], v[150:153], v[188:191], v[88:91]
	v_mfma_f32_16x16x32_bf16 v[76:79], v[136:139], v[196:199], v[76:79]
	v_mfma_f32_16x16x32_bf16 v[72:75], v[150:153], v[196:199], v[72:75]
	v_mfma_f32_16x16x32_bf16 v[124:127], v[146:149], v[176:179], v[124:127]
	v_mfma_f32_16x16x32_bf16 v[120:123], v[154:157], v[176:179], v[120:123]
	v_mfma_f32_16x16x32_bf16 v[108:111], v[146:149], v[184:187], v[108:111]
	v_mfma_f32_16x16x32_bf16 v[104:107], v[154:157], v[184:187], v[104:107]
	v_mfma_f32_16x16x32_bf16 v[92:95], v[146:149], v[192:195], v[92:95]
	v_mfma_f32_16x16x32_bf16 v[88:91], v[154:157], v[192:195], v[88:91]
	v_mfma_f32_16x16x32_bf16 v[76:79], v[146:149], v[200:203], v[76:79]
	v_mfma_f32_16x16x32_bf16 v[72:75], v[154:157], v[200:203], v[72:75]
	s_setprio 0
	s_barrier
	s_add_i32 s42, s33, s20
	v_lshl_add_u64 v[216:217], s[8:9], 0, v[170:171]
	s_mov_b32 m0, s42
	ds_read_b128 v[204:207], v143
	v_xor_b32_e32 v243, 64, v143
	ds_read_b128 v[208:211], v243
	ds_read_b128 v[212:215], v143 offset:2048
	ds_read_b128 v[240:243], v243 offset:2048
	global_load_lds_dwordx4 v[216:217], off
	v_lshl_add_u64 v[244:245], s[8:9], 0, v[174:175]
	s_add_i32 m0, s42, 0x2000
	s_nop 0
	global_load_lds_dwordx4 v[244:245], off
	s_barrier
	s_waitcnt lgkmcnt(0)
	s_setprio 1
	s_waitcnt lgkmcnt(0)
	v_mfma_f32_16x16x32_bf16 v[116:119], v[204:207], v[158:161], v[116:119]
	v_mfma_f32_16x16x32_bf16 v[112:115], v[212:215], v[158:161], v[112:115]
	v_mfma_f32_16x16x32_bf16 v[100:103], v[204:207], v[180:183], v[100:103]
	v_mfma_f32_16x16x32_bf16 v[96:99], v[212:215], v[180:183], v[96:99]
	v_mfma_f32_16x16x32_bf16 v[84:87], v[204:207], v[188:191], v[84:87]
	v_mfma_f32_16x16x32_bf16 v[80:83], v[212:215], v[188:191], v[80:83]
	v_mfma_f32_16x16x32_bf16 v[68:71], v[204:207], v[196:199], v[68:71]
	v_mfma_f32_16x16x32_bf16 v[64:67], v[212:215], v[196:199], v[64:67]
	v_mfma_f32_16x16x32_bf16 v[116:119], v[208:211], v[176:179], v[116:119]
	v_mfma_f32_16x16x32_bf16 v[112:115], v[240:243], v[176:179], v[112:115]
	v_mfma_f32_16x16x32_bf16 v[100:103], v[208:211], v[184:187], v[100:103]
	v_mfma_f32_16x16x32_bf16 v[96:99], v[240:243], v[184:187], v[96:99]
	v_mfma_f32_16x16x32_bf16 v[84:87], v[208:211], v[192:195], v[84:87]
	v_mfma_f32_16x16x32_bf16 v[80:83], v[240:243], v[192:195], v[80:83]
	v_mfma_f32_16x16x32_bf16 v[68:71], v[208:211], v[200:203], v[68:71]
	v_mfma_f32_16x16x32_bf16 v[64:67], v[240:243], v[200:203], v[64:67]
	s_setprio 0
	s_mov_b32 m0, s21
	v_lshl_add_u64 v[246:247], s[16:17], 0, v[168:169]
	s_barrier
	ds_read_b128 v[158:161], v142 offset:16384
	v_xor_b32_e32 v203, 64, v142
	ds_read_b128 v[176:179], v203 offset:16384
	ds_read_b128 v[180:183], v142 offset:18432
	ds_read_b128 v[184:187], v203 offset:18432
	ds_read_b128 v[188:191], v142 offset:20480
	ds_read_b128 v[192:195], v203 offset:20480
	ds_read_b128 v[196:199], v142 offset:22528
	ds_read_b128 v[200:203], v203 offset:22528
	global_load_lds_dwordx4 v[246:247], off
	v_lshl_add_u64 v[248:249], s[16:17], 0, v[172:173]
	s_mov_b32 m0, s22
	s_nop 0
	global_load_lds_dwordx4 v[248:249], off
	s_barrier
	s_waitcnt lgkmcnt(0)
	s_setprio 1
	s_waitcnt lgkmcnt(0)
	v_mfma_f32_16x16x32_bf16 v[60:63], v[136:139], v[158:161], v[60:63]
	v_mfma_f32_16x16x32_bf16 v[56:59], v[150:153], v[158:161], v[56:59]
	v_mfma_f32_16x16x32_bf16 v[44:47], v[136:139], v[180:183], v[44:47]
	v_mfma_f32_16x16x32_bf16 v[40:43], v[150:153], v[180:183], v[40:43]
	v_mfma_f32_16x16x32_bf16 v[28:31], v[136:139], v[188:191], v[28:31]
	v_mfma_f32_16x16x32_bf16 v[24:27], v[150:153], v[188:191], v[24:27]
	v_mfma_f32_16x16x32_bf16 v[12:15], v[136:139], v[196:199], v[12:15]
	v_mfma_f32_16x16x32_bf16 v[8:11], v[150:153], v[196:199], v[8:11]
	v_mfma_f32_16x16x32_bf16 v[60:63], v[146:149], v[176:179], v[60:63]
	v_mfma_f32_16x16x32_bf16 v[56:59], v[154:157], v[176:179], v[56:59]
	v_mfma_f32_16x16x32_bf16 v[44:47], v[146:149], v[184:187], v[44:47]
	v_mfma_f32_16x16x32_bf16 v[40:43], v[154:157], v[184:187], v[40:43]
	v_mfma_f32_16x16x32_bf16 v[28:31], v[146:149], v[192:195], v[28:31]
	v_mfma_f32_16x16x32_bf16 v[24:27], v[154:157], v[192:195], v[24:27]
	v_mfma_f32_16x16x32_bf16 v[12:15], v[146:149], v[200:203], v[12:15]
	v_mfma_f32_16x16x32_bf16 v[8:11], v[154:157], v[200:203], v[8:11]
	s_setprio 0
	s_barrier
	s_add_u32 s42, s8, 0x160000
	s_addc_u32 s43, s9, 0
	s_add_i32 s44, s34, s20
	v_lshl_add_u64 v[136:137], s[42:43], 0, v[170:171]
	s_mov_b32 m0, s44
	s_nop 0
	global_load_lds_dwordx4 v[136:137], off
	v_lshl_add_u64 v[136:137], s[42:43], 0, v[174:175]
	s_add_i32 m0, s44, 0x2000
	s_nop 0
	global_load_lds_dwordx4 v[136:137], off
	s_waitcnt vmcnt(6)
	s_barrier
	s_setprio 1
	v_mfma_f32_16x16x32_bf16 v[52:55], v[204:207], v[158:161], v[52:55]
	v_mfma_f32_16x16x32_bf16 v[48:51], v[212:215], v[158:161], v[48:51]
	v_mfma_f32_16x16x32_bf16 v[36:39], v[204:207], v[180:183], v[36:39]
	v_mfma_f32_16x16x32_bf16 v[32:35], v[212:215], v[180:183], v[32:35]
	v_mfma_f32_16x16x32_bf16 v[20:23], v[204:207], v[188:191], v[20:23]
	v_mfma_f32_16x16x32_bf16 v[16:19], v[212:215], v[188:191], v[16:19]
	v_mfma_f32_16x16x32_bf16 v[4:7], v[204:207], v[196:199], v[4:7]
	v_mfma_f32_16x16x32_bf16 v[0:3], v[212:215], v[196:199], v[0:3]
	v_mfma_f32_16x16x32_bf16 v[52:55], v[208:211], v[176:179], v[52:55]
	v_mfma_f32_16x16x32_bf16 v[48:51], v[240:243], v[176:179], v[48:51]
	v_mfma_f32_16x16x32_bf16 v[36:39], v[208:211], v[184:187], v[36:39]
	v_mfma_f32_16x16x32_bf16 v[32:35], v[240:243], v[184:187], v[32:35]
	v_mfma_f32_16x16x32_bf16 v[20:23], v[208:211], v[192:195], v[20:23]
	v_mfma_f32_16x16x32_bf16 v[16:19], v[240:243], v[192:195], v[16:19]
	v_mfma_f32_16x16x32_bf16 v[4:7], v[208:211], v[200:203], v[4:7]
	v_mfma_f32_16x16x32_bf16 v[0:3], v[240:243], v[200:203], v[0:3]
	s_setprio 0
	s_add_i32 s42, 0, 0x18000
	v_add_u32_e32 v145, s42, v140
	s_barrier
	ds_read_b128 v[136:139], v145
	v_xor_b32_e32 v157, 64, v145
	ds_read_b128 v[146:149], v157
	ds_read_b128 v[150:153], v145 offset:2048
	ds_read_b128 v[154:157], v157 offset:2048
	s_add_u32 s16, s16, 0x160000
	s_addc_u32 s17, s17, 0
	s_mov_b32 m0, s23
	v_lshl_add_u64 v[204:205], s[16:17], 0, v[168:169]
	ds_read_b128 v[158:161], v142 offset:32768
	v_xor_b32_e32 v203, 64, v142
	ds_read_b128 v[176:179], v203 offset:32768
	ds_read_b128 v[180:183], v142 offset:34816
	ds_read_b128 v[184:187], v203 offset:34816
	ds_read_b128 v[188:191], v142 offset:36864
	ds_read_b128 v[192:195], v203 offset:36864
	ds_read_b128 v[196:199], v142 offset:38912
	ds_read_b128 v[200:203], v203 offset:38912
	global_load_lds_dwordx4 v[204:205], off
	v_lshl_add_u64 v[204:205], s[16:17], 0, v[172:173]
	s_mov_b32 m0, s24
	s_nop 0
	global_load_lds_dwordx4 v[204:205], off
	s_waitcnt lgkmcnt(8)
	s_barrier
	s_waitcnt lgkmcnt(0)
	s_setprio 1
	s_waitcnt lgkmcnt(0)
	v_mfma_f32_16x16x32_bf16 v[124:127], v[136:139], v[158:161], v[124:127]
	v_mfma_f32_16x16x32_bf16 v[120:123], v[150:153], v[158:161], v[120:123]
	v_mfma_f32_16x16x32_bf16 v[108:111], v[136:139], v[180:183], v[108:111]
	v_mfma_f32_16x16x32_bf16 v[104:107], v[150:153], v[180:183], v[104:107]
	v_mfma_f32_16x16x32_bf16 v[92:95], v[136:139], v[188:191], v[92:95]
	v_mfma_f32_16x16x32_bf16 v[88:91], v[150:153], v[188:191], v[88:91]
	v_mfma_f32_16x16x32_bf16 v[76:79], v[136:139], v[196:199], v[76:79]
	v_mfma_f32_16x16x32_bf16 v[72:75], v[150:153], v[196:199], v[72:75]
	v_mfma_f32_16x16x32_bf16 v[124:127], v[146:149], v[176:179], v[124:127]
	v_mfma_f32_16x16x32_bf16 v[120:123], v[154:157], v[176:179], v[120:123]
	v_mfma_f32_16x16x32_bf16 v[108:111], v[146:149], v[184:187], v[108:111]
	v_mfma_f32_16x16x32_bf16 v[104:107], v[154:157], v[184:187], v[104:107]
	v_mfma_f32_16x16x32_bf16 v[92:95], v[146:149], v[192:195], v[92:95]
	v_mfma_f32_16x16x32_bf16 v[88:91], v[154:157], v[192:195], v[88:91]
	v_mfma_f32_16x16x32_bf16 v[76:79], v[146:149], v[200:203], v[76:79]
	v_mfma_f32_16x16x32_bf16 v[72:75], v[154:157], v[200:203], v[72:75]
	s_setprio 0
	s_barrier
	s_add_i32 s16, 0, 0x1c000
	s_add_i32 s17, s42, s20
	v_add_u32_e32 v145, s16, v140
	v_lshl_add_u64 v[216:217], v[216:217], 0, s[4:5]
	s_mov_b32 m0, s17
	ds_read_b128 v[204:207], v145
	v_xor_b32_e32 v243, 64, v145
	ds_read_b128 v[208:211], v243
	ds_read_b128 v[212:215], v145 offset:2048
	ds_read_b128 v[240:243], v243 offset:2048
	global_load_lds_dwordx4 v[216:217], off
	v_lshl_add_u64 v[216:217], v[244:245], 0, s[4:5]
	s_add_i32 m0, s17, 0x2000
	s_nop 0
	global_load_lds_dwordx4 v[216:217], off
	s_barrier
	s_waitcnt lgkmcnt(0)
	s_setprio 1
	s_waitcnt lgkmcnt(0)
	v_mfma_f32_16x16x32_bf16 v[116:119], v[204:207], v[158:161], v[116:119]
	v_mfma_f32_16x16x32_bf16 v[112:115], v[212:215], v[158:161], v[112:115]
	v_mfma_f32_16x16x32_bf16 v[100:103], v[204:207], v[180:183], v[100:103]
	v_mfma_f32_16x16x32_bf16 v[96:99], v[212:215], v[180:183], v[96:99]
	v_mfma_f32_16x16x32_bf16 v[84:87], v[204:207], v[188:191], v[84:87]
	v_mfma_f32_16x16x32_bf16 v[80:83], v[212:215], v[188:191], v[80:83]
	v_mfma_f32_16x16x32_bf16 v[68:71], v[204:207], v[196:199], v[68:71]
	v_mfma_f32_16x16x32_bf16 v[64:67], v[212:215], v[196:199], v[64:67]
	v_mfma_f32_16x16x32_bf16 v[116:119], v[208:211], v[176:179], v[116:119]
	v_mfma_f32_16x16x32_bf16 v[112:115], v[240:243], v[176:179], v[112:115]
	v_mfma_f32_16x16x32_bf16 v[100:103], v[208:211], v[184:187], v[100:103]
	v_mfma_f32_16x16x32_bf16 v[96:99], v[240:243], v[184:187], v[96:99]
	v_mfma_f32_16x16x32_bf16 v[84:87], v[208:211], v[192:195], v[84:87]
	v_mfma_f32_16x16x32_bf16 v[80:83], v[240:243], v[192:195], v[80:83]
	v_mfma_f32_16x16x32_bf16 v[68:71], v[208:211], v[200:203], v[68:71]
	v_mfma_f32_16x16x32_bf16 v[64:67], v[240:243], v[200:203], v[64:67]
	s_setprio 0
	s_mov_b32 m0, s28
	v_lshl_add_u64 v[216:217], v[246:247], 0, s[4:5]
	s_barrier
	ds_read_b128 v[158:161], v142 offset:49152
	v_xor_b32_e32 v203, 64, v142
	ds_read_b128 v[176:179], v203 offset:49152
	ds_read_b128 v[180:183], v142 offset:51200
	ds_read_b128 v[184:187], v203 offset:51200
	ds_read_b128 v[188:191], v142 offset:53248
	ds_read_b128 v[192:195], v203 offset:53248
	ds_read_b128 v[196:199], v142 offset:55296
	ds_read_b128 v[200:203], v203 offset:55296
	global_load_lds_dwordx4 v[216:217], off
	v_lshl_add_u64 v[216:217], v[248:249], 0, s[4:5]
	s_mov_b32 m0, s29
	s_nop 0
	global_load_lds_dwordx4 v[216:217], off
	s_barrier
	s_waitcnt lgkmcnt(0)
	s_setprio 1
	s_waitcnt lgkmcnt(0)
	v_mfma_f32_16x16x32_bf16 v[60:63], v[136:139], v[158:161], v[60:63]
	v_mfma_f32_16x16x32_bf16 v[56:59], v[150:153], v[158:161], v[56:59]
	v_mfma_f32_16x16x32_bf16 v[44:47], v[136:139], v[180:183], v[44:47]
	v_mfma_f32_16x16x32_bf16 v[40:43], v[150:153], v[180:183], v[40:43]
	v_mfma_f32_16x16x32_bf16 v[28:31], v[136:139], v[188:191], v[28:31]
	v_mfma_f32_16x16x32_bf16 v[24:27], v[150:153], v[188:191], v[24:27]
	v_mfma_f32_16x16x32_bf16 v[12:15], v[136:139], v[196:199], v[12:15]
	v_mfma_f32_16x16x32_bf16 v[8:11], v[150:153], v[196:199], v[8:11]
	v_mfma_f32_16x16x32_bf16 v[60:63], v[146:149], v[176:179], v[60:63]
	v_mfma_f32_16x16x32_bf16 v[56:59], v[154:157], v[176:179], v[56:59]
	v_mfma_f32_16x16x32_bf16 v[44:47], v[146:149], v[184:187], v[44:47]
	v_mfma_f32_16x16x32_bf16 v[40:43], v[154:157], v[184:187], v[40:43]
	v_mfma_f32_16x16x32_bf16 v[28:31], v[146:149], v[192:195], v[28:31]
	v_mfma_f32_16x16x32_bf16 v[24:27], v[154:157], v[192:195], v[24:27]
	v_mfma_f32_16x16x32_bf16 v[12:15], v[146:149], v[200:203], v[12:15]
	v_mfma_f32_16x16x32_bf16 v[8:11], v[154:157], v[200:203], v[8:11]
	s_setprio 0
	s_barrier
	s_add_u32 s8, s8, 0x160080
	s_addc_u32 s9, s9, 0
	s_add_i32 s16, s16, s20
	v_lshl_add_u64 v[136:137], s[8:9], 0, v[170:171]
	s_mov_b32 m0, s16
	s_nop 0
	global_load_lds_dwordx4 v[136:137], off
	v_lshl_add_u64 v[136:137], s[8:9], 0, v[174:175]
	s_add_i32 m0, s16, 0x2000
	s_nop 0
	global_load_lds_dwordx4 v[136:137], off
	s_waitcnt vmcnt(6)
	s_barrier
	s_setprio 1
	v_mfma_f32_16x16x32_bf16 v[52:55], v[204:207], v[158:161], v[52:55]
	v_mfma_f32_16x16x32_bf16 v[48:51], v[212:215], v[158:161], v[48:51]
	v_mfma_f32_16x16x32_bf16 v[36:39], v[204:207], v[180:183], v[36:39]
	v_mfma_f32_16x16x32_bf16 v[32:35], v[212:215], v[180:183], v[32:35]
	v_mfma_f32_16x16x32_bf16 v[20:23], v[204:207], v[188:191], v[20:23]
	v_mfma_f32_16x16x32_bf16 v[16:19], v[212:215], v[188:191], v[16:19]
	v_mfma_f32_16x16x32_bf16 v[4:7], v[204:207], v[196:199], v[4:7]
	v_mfma_f32_16x16x32_bf16 v[0:3], v[212:215], v[196:199], v[0:3]
	v_mfma_f32_16x16x32_bf16 v[52:55], v[208:211], v[176:179], v[52:55]
	v_mfma_f32_16x16x32_bf16 v[48:51], v[240:243], v[176:179], v[48:51]
	v_mfma_f32_16x16x32_bf16 v[36:39], v[208:211], v[184:187], v[36:39]
	v_mfma_f32_16x16x32_bf16 v[32:35], v[240:243], v[184:187], v[32:35]
	v_mfma_f32_16x16x32_bf16 v[20:23], v[208:211], v[192:195], v[20:23]
	v_mfma_f32_16x16x32_bf16 v[16:19], v[240:243], v[192:195], v[16:19]
	v_mfma_f32_16x16x32_bf16 v[4:7], v[208:211], v[200:203], v[4:7]
	v_mfma_f32_16x16x32_bf16 v[0:3], v[240:243], v[200:203], v[0:3]
	s_setprio 0
	s_add_i32 s41, s41, 2
	s_add_u32 s0, s0, 0x100
	s_addc_u32 s1, s1, 0
	s_add_u32 s39, s39, 0x100
	s_addc_u32 s40, s40, 0
	s_cmpk_gt_u32 s41, 0x55
	s_barrier
	s_cbranch_scc0 .LBB0_508
	s_lshl_b32 s0, s38, 8
	v_mov_b32_e32 v136, v163
	v_mov_b32_e32 v145, v225
	s_add_i32 s0, s0, s26
	v_xor_b32_e32 v158, 32, v144
	v_add_u32_e32 v138, s0, v136
	s_lshl_b32 s0, s37, 8
	s_or_b32 s0, s0, s27
	v_ashrrev_i32_e32 v139, 31, v138
	v_lshl_add_u32 v136, v145, 3, s0
	v_lshlrev_b64 v[146:147], 12, v[138:139]
	v_ashrrev_i32_e32 v137, 31, v136
	v_lshl_add_u64 v[146:147], s[80:81], 0, v[146:147]
	v_lshl_add_u64 v[150:151], v[136:137], 1, v[146:147]
	global_load_dwordx4 v[146:149], v[150:151], off
	v_cmp_eq_u32_e32 vcc, 0, v145
	s_waitcnt vmcnt(0)
	v_lshlrev_b32_e32 v152, 16, v146
	v_and_b32_e32 v153, 0xffff0000, v146
	v_lshlrev_b32_e32 v146, 16, v147
	v_and_b32_e32 v147, 0xffff0000, v147
	v_lshlrev_b32_e32 v154, 16, v148
	v_and_b32_e32 v155, 0xffff0000, v148
	v_lshlrev_b32_e32 v148, 16, v149
	v_and_b32_e32 v149, 0xffff0000, v149
	v_pk_add_f32 v[126:127], v[126:127], v[146:147]
	v_pk_add_f32 v[152:153], v[124:125], v[152:153]
	v_pk_add_f32 v[156:157], v[122:123], v[148:149]
	v_pk_add_f32 v[154:155], v[120:121], v[154:155]
	v_cvt_pk_bf16_f32 v122, v152, v153
	v_cvt_pk_bf16_f32 v123, v126, v127
	v_and_b32_e32 v121, 64, v144
	v_cvt_pk_bf16_f32 v124, v154, v155
	v_cvt_pk_bf16_f32 v125, v156, v157
	global_load_dwordx4 v[146:149], v[150:151], off offset:256
	v_mul_f32_e32 v145, v154, v154
	v_mul_f32_e32 v154, v155, v155
	v_mul_f32_e32 v155, v156, v156
	v_fmac_f32_e32 v145, v152, v152
	v_fmac_f32_e32 v154, v153, v153
	v_mul_f32_e32 v156, v157, v157
	v_fmac_f32_e32 v155, v126, v126
	v_add_f32_e32 v126, v145, v154
	v_fmac_f32_e32 v156, v127, v127
	v_add_f32_e32 v126, v155, v126
	v_add_f32_e32 v145, v156, v126
	v_xor_b32_e32 v120, 16, v144
	v_add_u32_e32 v121, 64, v121
	v_cmp_lt_i32_e64 s[8:9], v120, v121
	global_store_dwordx4 v[150:151], v[122:125], off
	s_waitcnt vmcnt(0)
	v_lshlrev_b32_e32 v126, 16, v146
	v_and_b32_e32 v127, 0xffff0000, v146
	v_lshlrev_b32_e32 v146, 16, v147
	v_and_b32_e32 v147, 0xffff0000, v147
	v_lshlrev_b32_e32 v152, 16, v148
	v_and_b32_e32 v153, 0xffff0000, v148
	v_pk_add_f32 v[118:119], v[118:119], v[146:147]
	v_pk_add_f32 v[146:147], v[112:113], v[152:153]
	v_lshlrev_b32_e32 v148, 16, v149
	v_and_b32_e32 v149, 0xffff0000, v149
	v_pk_add_f32 v[116:117], v[116:117], v[126:127]
	v_mul_f32_e32 v112, v146, v146
	v_pk_add_f32 v[126:127], v[114:115], v[148:149]
	v_mul_f32_e32 v113, v147, v147
	v_fmac_f32_e32 v112, v116, v116
	v_mul_f32_e32 v114, v126, v126
	v_fmac_f32_e32 v113, v117, v117
	v_add_f32_e32 v112, v145, v112
	v_mul_f32_e32 v115, v127, v127
	v_fmac_f32_e32 v114, v118, v118
	v_add_f32_e32 v112, v113, v112
	v_cndmask_b32_e64 v120, v144, v120, s[8:9]
	v_fmac_f32_e32 v115, v119, v119
	v_add_f32_e32 v112, v114, v112
	v_lshlrev_b32_e32 v120, 2, v120
	v_add_f32_e32 v112, v115, v112
	ds_bpermute_b32 v113, v120, v112
	v_cmp_lt_i32_e64 s[8:9], v158, v121
	v_cvt_pk_bf16_f32 v116, v116, v117
	v_cvt_pk_bf16_f32 v117, v118, v119
	v_cvt_pk_bf16_f32 v118, v146, v147
	s_waitcnt lgkmcnt(0)
	v_add_f32_e32 v112, v112, v113
	v_cvt_pk_bf16_f32 v119, v126, v127
	v_cndmask_b32_e64 v114, v144, v158, s[8:9]
	v_lshlrev_b32_e32 v114, 2, v114
	ds_bpermute_b32 v113, v114, v112
	global_store_dwordx4 v[150:151], v[116:119], off offset:256
	s_and_saveexec_b64 s[0:1], vcc
	s_cbranch_execz .LBB0_511
	s_waitcnt lgkmcnt(0)
	v_add_f32_e32 v115, v112, v113
	v_lshl_add_u64 v[112:113], v[138:139], 2, s[14:15]
	global_atomic_add_f32 v[112:113], v115, off

.LBB0_586:
	s_add_u32 s4, s92, 0x30000
	v_cndmask_b32_e64 v0, 0, 1, s[8:9]
	s_addc_u32 s5, s93, 0
	v_cmp_ne_u32_e64 s[6:7], 1, v0
	s_andn2_b64 vcc, exec, s[8:9]
	s_cbranch_vccnz .LBB0_634
	s_add_u32 s34, s92, 0x6300000
	s_addc_u32 s35, s93, 0
	s_lshr_b32 s9, s3, 6
	s_ashr_i32 s13, s12, 31
	s_ashr_i32 s1, s0, 31
	s_lshr_b32 s8, s3, 8
	s_lshl_b32 s36, s9, 10
	s_lshl_b64 s[10:11], s[12:13], 20
	s_lshl_b64 s[16:17], s[0:1], 20
	s_add_u32 s28, s34, s16
	s_addc_u32 s29, s35, s17
	s_add_i32 s37, s36, 0
	s_add_i32 m0, s37, 0x10000
	v_lshl_or_b32 v128, v236, 12, v219
	v_and_b32_e32 v140, 63, v222
	v_lshrrev_b32_e32 v141, 3, v140
	v_lshrrev_b32_e32 v142, 6, v222
	v_lshl_add_u32 v143, v142, 3, v141
	v_and_b32_e32 v144, 7, v140
	v_and_b32_e32 v145, 6, v141
	v_xor_b32_e32 v144, v144, v145
	v_lshlrev_b32_e32 v144, 4, v144
	v_mul_u32_u24_e32 v145, 0x1000, v143
	v_add_u32_e32 v145, v145, v144
	v_mov_b32_e32 v132, v145
	v_mov_b32_e32 v128, v145
	v_add_u32_e32 v134, 0x40000, v145
	v_add_u32_e32 v130, 0x40000, v145
	v_add_u32_e32 v134, 0x40000, v145
	v_add_u32_e32 v130, 0x40000, v145
	v_and_b32_e32 v145, 31, v143
	v_and_b32_e32 v154, 12, v145
	v_lshlrev_b32_e32 v154, 1, v154
	v_lshrrev_b32_e32 v155, 4, v145
	v_lshlrev_b32_e32 v155, 2, v155
	v_and_b32_e32 v145, 3, v145
	v_or3_b32 v145, v154, v155, v145
	v_and_b32_e32 v154, 0x60, v143
	v_add_u32_e32 v145, v145, v154
	v_mul_u32_u24_e32 v145, 0x1000, v145
	v_add_u32_e32 v145, v145, v144
	v_mov_b32_e32 v164, v145
	v_add_u32_e32 v166, 0x40000, v145
	v_add_u32_e32 v166, 0x40000, v145
	v_and_b32_e32 v145, 15, v140
	v_lshrrev_b32_e32 v154, 4, v140
	v_and_b32_e32 v155, 6, v145
	v_xor_b32_e32 v154, v154, v155
	v_lshlrev_b32_e32 v154, 4, v154
	v_lshl_or_b32 v154, v145, 7, v154
	v_lshrrev_b32_e32 v155, 2, v142
	v_lshl_add_u32 v155, v155, 13, v154
	v_add_u32_e32 v150, 0x0, v155
	v_and_b32_e32 v145, 3, v142
	v_lshl_add_u32 v145, v145, 12, v154
	v_add_u32_e32 v147, 0x0, v145
	v_add_u32_e32 v149, 0x10000, v145
	v_add_u32_e32 v151, 0x14000, v145
	global_load_lds_dwordx4 v164, s[28:29]
	s_add_i32 m0, s37, 0x12000
	s_add_u32 s26, s80, s10
	global_load_lds_dwordx4 v166, s[28:29]
	s_addc_u32 s27, s81, s11
	s_mov_b32 m0, s37
	s_add_i32 s38, s37, 0x2000
	global_load_lds_dwordx4 v128, s[26:27]
	s_mov_b32 m0, s38
	s_add_u32 s10, s28, 0x80000
	global_load_lds_dwordx4 v130, s[26:27]
	s_addc_u32 s11, s29, 0
	s_add_i32 m0, s37, 0x14000
	v_mov_b32_e32 v165, 0
	global_load_lds_dwordx4 v164, s[10:11]
	s_add_i32 m0, s37, 0x16000
	v_mov_b32_e32 v167, v165
	global_load_lds_dwordx4 v166, s[10:11]
	s_add_u32 s10, s26, 0x80000
	s_addc_u32 s11, s27, 0
	s_add_i32 s39, s37, 0x4000
	s_mov_b32 m0, s39
	s_add_i32 s40, s37, 0x6000
	global_load_lds_dwordx4 v128, s[10:11]
	s_mov_b32 m0, s40
	v_mov_b32_e32 v129, v165
	global_load_lds_dwordx4 v130, s[10:11]
	v_mov_b32_e32 v131, v165
	s_mov_b32 s41, 0
	v_lshl_add_u64 v[6:7], s[28:29], 0, v[164:165]
	v_lshl_add_u64 v[4:5], s[28:29], 0, v[166:167]
	v_lshl_add_u64 v[2:3], s[26:27], 0, v[128:129]
	s_cmp_lg_u32 s8, 1
	v_lshl_add_u64 v[0:1], s[26:27], 0, v[130:131]
	s_cbranch_scc1 .LBB0_589
	s_barrier
.LBB0_589:
	s_mov_b64 s[16:17], 0x80
	s_lshl_b32 s9, s9, 5
	s_add_i32 m0, s37, 0x18000
	v_lshl_add_u64 v[6:7], v[6:7], 0, s[16:17]
	s_lshl_b32 s1, s8, 13
	s_and_b32 s13, s9, 0x60
	s_waitcnt vmcnt(4)
	s_barrier
	global_load_lds_dwordx4 v[6:7], off
	v_lshl_add_u64 v[4:5], v[4:5], 0, s[16:17]
	s_add_i32 m0, s37, 0x1a000
	s_add_i32 s42, s37, 0x8000
	s_add_i32 s43, s37, 0xa000
	global_load_lds_dwordx4 v[4:5], off
	v_lshl_add_u64 v[2:3], v[2:3], 0, s[16:17]
	s_mov_b32 m0, s42
	s_add_u32 s10, s28, 0x80080
	global_load_lds_dwordx4 v[2:3], off
	v_lshl_add_u64 v[0:1], v[0:1], 0, s[16:17]
	s_mov_b32 m0, s43
	s_addc_u32 s11, s29, 0
	global_load_lds_dwordx4 v[0:1], off
	s_add_i32 m0, s37, 0x1c000
	v_lshl_add_u64 v[0:1], s[10:11], 0, v[164:165]
	global_load_lds_dwordx4 v[0:1], off
	v_lshl_add_u64 v[0:1], s[10:11], 0, v[166:167]
	s_add_i32 m0, s37, 0x1e000
	v_lshlrev_b32_e32 v2, 12, v218
	global_load_lds_dwordx4 v[0:1], off
	v_lshlrev_b32_e32 v1, 2, v163
	v_lshl_or_b32 v0, v163, 6, v227
	v_and_b32_e32 v1, 32, v1
	v_bitop3_b32 v0, v0, s1, v1 bitop3:0xde
	v_lshlrev_b32_e32 v1, 9, v222
	v_and_b32_e32 v1, 0x70000, v1
	v_or3_b32 v1, v226, v1, v2
	v_lshlrev_b32_e32 v1, 5, v233
	s_waitcnt vmcnt(6)
	v_and_b32_e32 v1, 0xf0000, v1
	v_or3_b32 v1, v226, v1, v2
	s_add_i32 s46, 0, 0x10000
	s_add_i32 s47, 0, 0x14000
	v_mbcnt_lo_u32_b32 v0, -1, 0
	v_lshl_or_b32 v146, s8, 6, v163
	s_ashr_i32 s44, s94, 31
	s_mov_b32 s45, s94
	v_cmp_eq_u32_e64 s[8:9], 0, v225
	v_lshl_or_b32 v148, v225, 3, s13
	v_mov_b32_e32 v133, v165
	v_mov_b32_e32 v135, v165
	v_mov_b64_e32 v[136:137], 0x400
	v_mov_b64_e32 v[138:139], 0x3ff
	v_mov_b32_e32 v152, 0x3727c5ac
	v_mbcnt_hi_u32_b32 v153, -1, v0
	s_barrier
	s_branch .LBB0_592

.LBB0_599:
	ds_read_b128 v[140:143], v149
	v_xor_b32_e32 v179, 64, v149
	ds_read_b128 v[154:157], v179
	ds_read_b128 v[158:161], v149 offset:2048
	ds_read_b128 v[176:179], v179 offset:2048
	s_add_u32 s28, s26, 0xfff80080
	s_addc_u32 s29, s27, -1
	s_cmp_eq_u32 s49, 28
	s_cselect_b32 s31, s1, s29
	s_cselect_b32 s30, s13, s28
	s_cselect_b32 s29, s19, s48
	s_cselect_b32 s28, s21, s33
	v_lshl_add_u64 v[144:145], s[26:27], 0, v[132:133]
	s_add_i32 m0, s37, 0xc000
	ds_read_b128 v[180:183], v150
	v_xor_b32_e32 v211, 64, v150
	ds_read_b128 v[184:187], v211
	ds_read_b128 v[188:191], v150 offset:2048
	ds_read_b128 v[192:195], v211 offset:2048
	ds_read_b128 v[196:199], v150 offset:4096
	ds_read_b128 v[200:203], v211 offset:4096
	ds_read_b128 v[204:207], v150 offset:6144
	ds_read_b128 v[208:211], v211 offset:6144
	global_load_lds_dwordx4 v[144:145], off
	v_lshl_add_u64 v[144:145], s[26:27], 0, v[134:135]
	s_add_i32 m0, s37, 0xe000
	s_nop 0
	global_load_lds_dwordx4 v[144:145], off
	s_waitcnt lgkmcnt(8)
	s_barrier
	s_waitcnt lgkmcnt(0)
	s_setprio 1
	s_waitcnt lgkmcnt(0)
	v_mfma_f32_16x16x32_bf16 v[124:127], v[140:143], v[180:183], v[124:127]
	v_mfma_f32_16x16x32_bf16 v[120:123], v[158:161], v[180:183], v[120:123]
	v_mfma_f32_16x16x32_bf16 v[108:111], v[140:143], v[188:191], v[108:111]
	v_mfma_f32_16x16x32_bf16 v[104:107], v[158:161], v[188:191], v[104:107]
	v_mfma_f32_16x16x32_bf16 v[92:95], v[140:143], v[196:199], v[92:95]
	v_mfma_f32_16x16x32_bf16 v[88:91], v[158:161], v[196:199], v[88:91]
	v_mfma_f32_16x16x32_bf16 v[76:79], v[140:143], v[204:207], v[76:79]
	v_mfma_f32_16x16x32_bf16 v[72:75], v[158:161], v[204:207], v[72:75]
	v_mfma_f32_16x16x32_bf16 v[124:127], v[154:157], v[184:187], v[124:127]
	v_mfma_f32_16x16x32_bf16 v[120:123], v[176:179], v[184:187], v[120:123]
	v_mfma_f32_16x16x32_bf16 v[108:111], v[154:157], v[192:195], v[108:111]
	v_mfma_f32_16x16x32_bf16 v[104:107], v[176:179], v[192:195], v[104:107]
	v_mfma_f32_16x16x32_bf16 v[92:95], v[154:157], v[200:203], v[92:95]
	v_mfma_f32_16x16x32_bf16 v[88:91], v[176:179], v[200:203], v[88:91]
	v_mfma_f32_16x16x32_bf16 v[76:79], v[154:157], v[208:211], v[76:79]
	v_mfma_f32_16x16x32_bf16 v[72:75], v[176:179], v[208:211], v[72:75]
	s_setprio 0
	s_barrier
	s_add_i32 s52, s46, s36
	v_lshl_add_u64 v[144:145], s[28:29], 0, v[164:165]
	s_mov_b32 m0, s52
	ds_read_b128 v[212:215], v151
	v_xor_b32_e32 v251, 64, v151
	ds_read_b128 v[240:243], v251
	ds_read_b128 v[244:247], v151 offset:2048
	ds_read_b128 v[248:251], v251 offset:2048
	global_load_lds_dwordx4 v[144:145], off
	v_lshl_add_u64 v[216:217], s[28:29], 0, v[166:167]
	s_add_i32 m0, s52, 0x2000
	s_nop 0
	global_load_lds_dwordx4 v[216:217], off
	s_barrier
	s_waitcnt lgkmcnt(0)
	s_setprio 1
	s_waitcnt lgkmcnt(0)
	v_mfma_f32_16x16x32_bf16 v[116:119], v[212:215], v[180:183], v[116:119]
	v_mfma_f32_16x16x32_bf16 v[112:115], v[244:247], v[180:183], v[112:115]
	v_mfma_f32_16x16x32_bf16 v[100:103], v[212:215], v[188:191], v[100:103]
	v_mfma_f32_16x16x32_bf16 v[96:99], v[244:247], v[188:191], v[96:99]
	v_mfma_f32_16x16x32_bf16 v[84:87], v[212:215], v[196:199], v[84:87]
	v_mfma_f32_16x16x32_bf16 v[80:83], v[244:247], v[196:199], v[80:83]
	v_mfma_f32_16x16x32_bf16 v[68:71], v[212:215], v[204:207], v[68:71]
	v_mfma_f32_16x16x32_bf16 v[64:67], v[244:247], v[204:207], v[64:67]
	v_mfma_f32_16x16x32_bf16 v[116:119], v[240:243], v[184:187], v[116:119]
	v_mfma_f32_16x16x32_bf16 v[112:115], v[248:251], v[184:187], v[112:115]
	v_mfma_f32_16x16x32_bf16 v[100:103], v[240:243], v[192:195], v[100:103]
	v_mfma_f32_16x16x32_bf16 v[96:99], v[248:251], v[192:195], v[96:99]
	v_mfma_f32_16x16x32_bf16 v[84:87], v[240:243], v[200:203], v[84:87]
	v_mfma_f32_16x16x32_bf16 v[80:83], v[248:251], v[200:203], v[80:83]
	v_mfma_f32_16x16x32_bf16 v[68:71], v[240:243], v[208:211], v[68:71]
	v_mfma_f32_16x16x32_bf16 v[64:67], v[248:251], v[208:211], v[64:67]
	s_setprio 0
	s_mov_b32 m0, s37
	v_lshl_add_u64 v[252:253], s[30:31], 0, v[128:129]
	s_barrier
	ds_read_b128 v[180:183], v150 offset:16384
	v_xor_b32_e32 v211, 64, v150
	ds_read_b128 v[184:187], v211 offset:16384
	ds_read_b128 v[188:191], v150 offset:18432
	ds_read_b128 v[192:195], v211 offset:18432
	ds_read_b128 v[196:199], v150 offset:20480
	ds_read_b128 v[200:203], v211 offset:20480
	ds_read_b128 v[204:207], v150 offset:22528
	ds_read_b128 v[208:211], v211 offset:22528
	global_load_lds_dwordx4 v[252:253], off
	v_lshl_add_u64 v[234:235], s[30:31], 0, v[130:131]
	s_mov_b32 m0, s38
	s_nop 0
	global_load_lds_dwordx4 v[234:235], off
	s_barrier
	s_waitcnt lgkmcnt(0)
	s_setprio 1
	s_waitcnt lgkmcnt(0)
	v_mfma_f32_16x16x32_bf16 v[60:63], v[140:143], v[180:183], v[60:63]
	v_mfma_f32_16x16x32_bf16 v[56:59], v[158:161], v[180:183], v[56:59]
	v_mfma_f32_16x16x32_bf16 v[44:47], v[140:143], v[188:191], v[44:47]
	v_mfma_f32_16x16x32_bf16 v[40:43], v[158:161], v[188:191], v[40:43]
	v_mfma_f32_16x16x32_bf16 v[28:31], v[140:143], v[196:199], v[28:31]
	v_mfma_f32_16x16x32_bf16 v[24:27], v[158:161], v[196:199], v[24:27]
	v_mfma_f32_16x16x32_bf16 v[12:15], v[140:143], v[204:207], v[12:15]
	v_mfma_f32_16x16x32_bf16 v[8:11], v[158:161], v[204:207], v[8:11]
	v_mfma_f32_16x16x32_bf16 v[60:63], v[154:157], v[184:187], v[60:63]
	v_mfma_f32_16x16x32_bf16 v[56:59], v[176:179], v[184:187], v[56:59]
	v_mfma_f32_16x16x32_bf16 v[44:47], v[154:157], v[192:195], v[44:47]
	v_mfma_f32_16x16x32_bf16 v[40:43], v[176:179], v[192:195], v[40:43]
	v_mfma_f32_16x16x32_bf16 v[28:31], v[154:157], v[200:203], v[28:31]
	v_mfma_f32_16x16x32_bf16 v[24:27], v[176:179], v[200:203], v[24:27]
	v_mfma_f32_16x16x32_bf16 v[12:15], v[154:157], v[208:211], v[12:15]
	v_mfma_f32_16x16x32_bf16 v[8:11], v[176:179], v[208:211], v[8:11]
	s_setprio 0
	s_barrier
	s_add_u32 s52, s28, 0x80000
	s_addc_u32 s53, s29, 0
	s_add_i32 s54, s47, s36
	v_lshl_add_u64 v[140:141], s[52:53], 0, v[164:165]
	s_mov_b32 m0, s54
	s_nop 0
	global_load_lds_dwordx4 v[140:141], off
	v_lshl_add_u64 v[140:141], s[52:53], 0, v[166:167]
	s_add_i32 m0, s54, 0x2000
	s_nop 0
	global_load_lds_dwordx4 v[140:141], off
	s_waitcnt vmcnt(6)
	s_barrier
	s_setprio 1
	v_mfma_f32_16x16x32_bf16 v[52:55], v[212:215], v[180:183], v[52:55]
	v_mfma_f32_16x16x32_bf16 v[48:51], v[244:247], v[180:183], v[48:51]
	v_mfma_f32_16x16x32_bf16 v[36:39], v[212:215], v[188:191], v[36:39]
	v_mfma_f32_16x16x32_bf16 v[32:35], v[244:247], v[188:191], v[32:35]
	v_mfma_f32_16x16x32_bf16 v[20:23], v[212:215], v[196:199], v[20:23]
	v_mfma_f32_16x16x32_bf16 v[16:19], v[244:247], v[196:199], v[16:19]
	v_mfma_f32_16x16x32_bf16 v[4:7], v[212:215], v[204:207], v[4:7]
	v_mfma_f32_16x16x32_bf16 v[0:3], v[244:247], v[204:207], v[0:3]
	v_mfma_f32_16x16x32_bf16 v[52:55], v[240:243], v[184:187], v[52:55]
	v_mfma_f32_16x16x32_bf16 v[48:51], v[248:251], v[184:187], v[48:51]
	v_mfma_f32_16x16x32_bf16 v[36:39], v[240:243], v[192:195], v[36:39]
	v_mfma_f32_16x16x32_bf16 v[32:35], v[248:251], v[192:195], v[32:35]
	v_mfma_f32_16x16x32_bf16 v[20:23], v[240:243], v[200:203], v[20:23]
	v_mfma_f32_16x16x32_bf16 v[16:19], v[248:251], v[200:203], v[16:19]
	v_mfma_f32_16x16x32_bf16 v[4:7], v[240:243], v[208:211], v[4:7]
	v_mfma_f32_16x16x32_bf16 v[0:3], v[248:251], v[208:211], v[0:3]
	s_setprio 0
	s_add_i32 s52, 0, 0x18000
	v_add_u32_e32 v169, s52, v147
	s_barrier
	ds_read_b128 v[140:143], v169
	v_xor_b32_e32 v179, 64, v169
	ds_read_b128 v[154:157], v179
	ds_read_b128 v[158:161], v169 offset:2048
	ds_read_b128 v[176:179], v179 offset:2048
	s_add_u32 s30, s30, 0x80000
	s_addc_u32 s31, s31, 0
	s_mov_b32 m0, s39
	v_lshl_add_u64 v[212:213], s[30:31], 0, v[128:129]
	ds_read_b128 v[180:183], v150 offset:32768
	v_xor_b32_e32 v211, 64, v150
	ds_read_b128 v[184:187], v211 offset:32768
	ds_read_b128 v[188:191], v150 offset:34816
	ds_read_b128 v[192:195], v211 offset:34816
	ds_read_b128 v[196:199], v150 offset:36864
	ds_read_b128 v[200:203], v211 offset:36864
	ds_read_b128 v[204:207], v150 offset:38912
	ds_read_b128 v[208:211], v211 offset:38912
	global_load_lds_dwordx4 v[212:213], off
	v_lshl_add_u64 v[212:213], s[30:31], 0, v[130:131]
	s_mov_b32 m0, s40
	s_nop 0
	global_load_lds_dwordx4 v[212:213], off
	s_waitcnt lgkmcnt(8)
	s_barrier
	s_waitcnt lgkmcnt(0)
	s_setprio 1
	s_waitcnt lgkmcnt(0)
	v_mfma_f32_16x16x32_bf16 v[124:127], v[140:143], v[180:183], v[124:127]
	v_mfma_f32_16x16x32_bf16 v[120:123], v[158:161], v[180:183], v[120:123]
	v_mfma_f32_16x16x32_bf16 v[108:111], v[140:143], v[188:191], v[108:111]
	v_mfma_f32_16x16x32_bf16 v[104:107], v[158:161], v[188:191], v[104:107]
	v_mfma_f32_16x16x32_bf16 v[92:95], v[140:143], v[196:199], v[92:95]
	v_mfma_f32_16x16x32_bf16 v[88:91], v[158:161], v[196:199], v[88:91]
	v_mfma_f32_16x16x32_bf16 v[76:79], v[140:143], v[204:207], v[76:79]
	v_mfma_f32_16x16x32_bf16 v[72:75], v[158:161], v[204:207], v[72:75]
	v_mfma_f32_16x16x32_bf16 v[124:127], v[154:157], v[184:187], v[124:127]
	v_mfma_f32_16x16x32_bf16 v[120:123], v[176:179], v[184:187], v[120:123]
	v_mfma_f32_16x16x32_bf16 v[108:111], v[154:157], v[192:195], v[108:111]
	v_mfma_f32_16x16x32_bf16 v[104:107], v[176:179], v[192:195], v[104:107]
	v_mfma_f32_16x16x32_bf16 v[92:95], v[154:157], v[200:203], v[92:95]
	v_mfma_f32_16x16x32_bf16 v[88:91], v[176:179], v[200:203], v[88:91]
	v_mfma_f32_16x16x32_bf16 v[76:79], v[154:157], v[208:211], v[76:79]
	v_mfma_f32_16x16x32_bf16 v[72:75], v[176:179], v[208:211], v[72:75]
	s_setprio 0
	s_barrier
	s_add_i32 s30, 0, 0x1c000
	s_add_i32 s31, s52, s36
	v_add_u32_e32 v169, s30, v147
	v_lshl_add_u64 v[144:145], v[144:145], 0, s[16:17]
	s_mov_b32 m0, s31
	ds_read_b128 v[212:215], v169
	v_xor_b32_e32 v251, 64, v169
	ds_read_b128 v[240:243], v251
	ds_read_b128 v[244:247], v169 offset:2048
	ds_read_b128 v[248:251], v251 offset:2048
	global_load_lds_dwordx4 v[144:145], off
	v_lshl_add_u64 v[144:145], v[216:217], 0, s[16:17]
	s_add_i32 m0, s31, 0x2000
	s_nop 0
	global_load_lds_dwordx4 v[144:145], off
	s_barrier
	s_waitcnt lgkmcnt(0)
	s_setprio 1
	s_waitcnt lgkmcnt(0)
	v_mfma_f32_16x16x32_bf16 v[116:119], v[212:215], v[180:183], v[116:119]
	v_mfma_f32_16x16x32_bf16 v[112:115], v[244:247], v[180:183], v[112:115]
	v_mfma_f32_16x16x32_bf16 v[100:103], v[212:215], v[188:191], v[100:103]
	v_mfma_f32_16x16x32_bf16 v[96:99], v[244:247], v[188:191], v[96:99]
	v_mfma_f32_16x16x32_bf16 v[84:87], v[212:215], v[196:199], v[84:87]
	v_mfma_f32_16x16x32_bf16 v[80:83], v[244:247], v[196:199], v[80:83]
	v_mfma_f32_16x16x32_bf16 v[68:71], v[212:215], v[204:207], v[68:71]
	v_mfma_f32_16x16x32_bf16 v[64:67], v[244:247], v[204:207], v[64:67]
	v_mfma_f32_16x16x32_bf16 v[116:119], v[240:243], v[184:187], v[116:119]
	v_mfma_f32_16x16x32_bf16 v[112:115], v[248:251], v[184:187], v[112:115]
	v_mfma_f32_16x16x32_bf16 v[100:103], v[240:243], v[192:195], v[100:103]
	v_mfma_f32_16x16x32_bf16 v[96:99], v[248:251], v[192:195], v[96:99]
	v_mfma_f32_16x16x32_bf16 v[84:87], v[240:243], v[200:203], v[84:87]
	v_mfma_f32_16x16x32_bf16 v[80:83], v[248:251], v[200:203], v[80:83]
	v_mfma_f32_16x16x32_bf16 v[68:71], v[240:243], v[208:211], v[68:71]
	v_mfma_f32_16x16x32_bf16 v[64:67], v[248:251], v[208:211], v[64:67]
	s_setprio 0
	s_mov_b32 m0, s42
	v_lshl_add_u64 v[144:145], v[252:253], 0, s[16:17]
	s_barrier
	ds_read_b128 v[180:183], v150 offset:49152
	v_xor_b32_e32 v211, 64, v150
	ds_read_b128 v[184:187], v211 offset:49152
	ds_read_b128 v[188:191], v150 offset:51200
	ds_read_b128 v[192:195], v211 offset:51200
	ds_read_b128 v[196:199], v150 offset:53248
	ds_read_b128 v[200:203], v211 offset:53248
	ds_read_b128 v[204:207], v150 offset:55296
	ds_read_b128 v[208:211], v211 offset:55296
	global_load_lds_dwordx4 v[144:145], off
	v_lshl_add_u64 v[144:145], v[234:235], 0, s[16:17]
	s_mov_b32 m0, s43
	s_nop 0
	global_load_lds_dwordx4 v[144:145], off
	s_barrier
	s_waitcnt lgkmcnt(0)
	s_setprio 1
	s_waitcnt lgkmcnt(0)
	v_mfma_f32_16x16x32_bf16 v[60:63], v[140:143], v[180:183], v[60:63]
	v_mfma_f32_16x16x32_bf16 v[56:59], v[158:161], v[180:183], v[56:59]
	v_mfma_f32_16x16x32_bf16 v[44:47], v[140:143], v[188:191], v[44:47]
	v_mfma_f32_16x16x32_bf16 v[40:43], v[158:161], v[188:191], v[40:43]
	v_mfma_f32_16x16x32_bf16 v[28:31], v[140:143], v[196:199], v[28:31]
	v_mfma_f32_16x16x32_bf16 v[24:27], v[158:161], v[196:199], v[24:27]
	v_mfma_f32_16x16x32_bf16 v[12:15], v[140:143], v[204:207], v[12:15]
	v_mfma_f32_16x16x32_bf16 v[8:11], v[158:161], v[204:207], v[8:11]
	v_mfma_f32_16x16x32_bf16 v[60:63], v[154:157], v[184:187], v[60:63]
	v_mfma_f32_16x16x32_bf16 v[56:59], v[176:179], v[184:187], v[56:59]
	v_mfma_f32_16x16x32_bf16 v[44:47], v[154:157], v[192:195], v[44:47]
	v_mfma_f32_16x16x32_bf16 v[40:43], v[176:179], v[192:195], v[40:43]
	v_mfma_f32_16x16x32_bf16 v[28:31], v[154:157], v[200:203], v[28:31]
	v_mfma_f32_16x16x32_bf16 v[24:27], v[176:179], v[200:203], v[24:27]
	v_mfma_f32_16x16x32_bf16 v[12:15], v[154:157], v[208:211], v[12:15]
	v_mfma_f32_16x16x32_bf16 v[8:11], v[176:179], v[208:211], v[8:11]
	s_setprio 0
	s_barrier
	s_add_u32 s28, s28, 0x80080
	s_addc_u32 s29, s29, 0
	s_add_i32 s30, s30, s36
	v_lshl_add_u64 v[140:141], s[28:29], 0, v[164:165]
	s_mov_b32 m0, s30
	s_nop 0
	global_load_lds_dwordx4 v[140:141], off
	v_lshl_add_u64 v[140:141], s[28:29], 0, v[166:167]
	s_add_i32 m0, s30, 0x2000
	s_nop 0
	global_load_lds_dwordx4 v[140:141], off
	s_waitcnt vmcnt(6)
	s_barrier
	s_setprio 1
	v_mfma_f32_16x16x32_bf16 v[52:55], v[212:215], v[180:183], v[52:55]
	v_mfma_f32_16x16x32_bf16 v[48:51], v[244:247], v[180:183], v[48:51]
	v_mfma_f32_16x16x32_bf16 v[36:39], v[212:215], v[188:191], v[36:39]
	v_mfma_f32_16x16x32_bf16 v[32:35], v[244:247], v[188:191], v[32:35]
	v_mfma_f32_16x16x32_bf16 v[20:23], v[212:215], v[196:199], v[20:23]
	v_mfma_f32_16x16x32_bf16 v[16:19], v[244:247], v[196:199], v[16:19]
	v_mfma_f32_16x16x32_bf16 v[4:7], v[212:215], v[204:207], v[4:7]
	v_mfma_f32_16x16x32_bf16 v[0:3], v[244:247], v[204:207], v[0:3]
	v_mfma_f32_16x16x32_bf16 v[52:55], v[240:243], v[184:187], v[52:55]
	v_mfma_f32_16x16x32_bf16 v[48:51], v[248:251], v[184:187], v[48:51]
	v_mfma_f32_16x16x32_bf16 v[36:39], v[240:243], v[192:195], v[36:39]
	v_mfma_f32_16x16x32_bf16 v[32:35], v[248:251], v[192:195], v[32:35]
	v_mfma_f32_16x16x32_bf16 v[20:23], v[240:243], v[200:203], v[20:23]
	v_mfma_f32_16x16x32_bf16 v[16:19], v[248:251], v[200:203], v[16:19]
	v_mfma_f32_16x16x32_bf16 v[4:7], v[240:243], v[208:211], v[4:7]
	v_mfma_f32_16x16x32_bf16 v[0:3], v[248:251], v[208:211], v[0:3]
	s_setprio 0
	s_add_i32 s49, s49, 2
	s_add_u32 s26, s26, 0x100
	s_addc_u32 s27, s27, 0
	s_add_u32 s33, s33, 0x100
	s_addc_u32 s48, s48, 0
	s_cmp_gt_u32 s49, 29
	s_barrier
	s_cbranch_scc0 .LBB0_599
	v_lshl_add_u32 v142, s12, 8, v146
	v_ashrrev_i32_e32 v143, 31, v142
	v_lshl_add_u64 v[144:145], v[142:143], 2, s[14:15]
	global_load_dword v154, v[144:145], off
	v_lshl_or_b32 v140, s0, 8, v148
	v_lshlrev_b64 v[156:157], 13, v[142:143]
	v_ashrrev_i32_e32 v141, 31, v140
	v_lshl_add_u64 v[156:157], s[96:97], 0, v[156:157]
	v_lshl_add_u64 v[158:159], v[140:141], 1, v[156:157]
	s_cmp_gt_i32 s0, 7
	s_cselect_b64 s[26:27], -1, 0
	s_cmp_lt_i32 s0, 8
	s_waitcnt vmcnt(0)
	v_fmamk_f32 v154, v154, 0x3a000000, v152
	v_rsq_f32_e32 v154, v154
	s_nop 0
	v_pk_mul_f32 v[126:127], v[126:127], v[154:155] op_sel_hi:[1,0]
	v_pk_mul_f32 v[124:125], v[124:125], v[154:155] op_sel_hi:[1,0]
	v_pk_mul_f32 v[120:121], v[120:121], v[154:155] op_sel_hi:[1,0]
	v_pk_mul_f32 v[122:123], v[122:123], v[154:155] op_sel_hi:[1,0]
	v_pk_mul_f32 v[156:157], v[118:119], v[154:155] op_sel_hi:[1,0]
	v_pk_mul_f32 v[160:161], v[116:117], v[154:155] op_sel_hi:[1,0]
	v_pk_mul_f32 v[176:177], v[114:115], v[154:155] op_sel_hi:[1,0]
	v_pk_mul_f32 v[154:155], v[112:113], v[154:155] op_sel_hi:[1,0]
	v_mul_f32_e32 v112, 0x3d372713, v124
	v_mul_f32_e32 v113, 0x3d372713, v120
	v_mul_f32_e32 v114, 0x3d372713, v125
	v_mul_f32_e32 v115, 0x3d372713, v121
	v_mul_f32_e32 v116, 0x3d372713, v126
	v_mul_f32_e32 v118, 0x3d372713, v127
	v_mul_f32_e32 v117, 0x3d372713, v122
	v_mul_f32_e32 v119, 0x3d372713, v123
	v_mul_f32_e32 v112, v124, v112
	v_mul_f32_e32 v113, v120, v113
	v_mul_f32_e32 v114, v125, v114
	v_mul_f32_e32 v115, v121, v115
	v_mul_f32_e32 v116, v126, v116
	v_mul_f32_e32 v118, v127, v118
	v_mul_f32_e32 v117, v122, v117
	v_mul_f32_e32 v119, v123, v119
	v_fma_f32 v112, v124, v112, v124
	v_fma_f32 v113, v120, v113, v120
	v_fma_f32 v114, v125, v114, v125
	v_fma_f32 v115, v121, v115, v121
	v_fma_f32 v116, v126, v116, v126
	v_fma_f32 v118, v127, v118, v127
	v_fma_f32 v117, v122, v117, v122
	v_fma_f32 v119, v123, v119, v123
	v_mul_f32_e32 v112, 0x3f4c422a, v112
	v_mul_f32_e32 v113, 0x3f4c422a, v113
	v_mul_f32_e32 v114, 0x3f4c422a, v114
	v_mul_f32_e32 v115, 0x3f4c422a, v115
	v_mul_f32_e32 v116, 0x3f4c422a, v116
	v_mul_f32_e32 v118, 0x3f4c422a, v118
	v_mul_f32_e32 v117, 0x3f4c422a, v117
	v_mul_f32_e32 v119, 0x3f4c422a, v119
	v_mul_f32_e32 v112, 0xc038aa3b, v112
	v_mul_f32_e32 v113, 0xc038aa3b, v113
	v_mul_f32_e32 v114, 0xc038aa3b, v114
	v_mul_f32_e32 v115, 0xc038aa3b, v115
	v_mul_f32_e32 v116, 0xc038aa3b, v116
	v_mul_f32_e32 v118, 0xc038aa3b, v118
	v_mul_f32_e32 v117, 0xc038aa3b, v117
	v_mul_f32_e32 v119, 0xc038aa3b, v119
	v_exp_f32_e32 v112, v112
	v_exp_f32_e32 v113, v113
	v_exp_f32_e32 v114, v114
	v_exp_f32_e32 v115, v115
	v_exp_f32_e32 v116, v116
	v_exp_f32_e32 v118, v118
	v_exp_f32_e32 v117, v117
	v_exp_f32_e32 v119, v119
	v_add_f32_e32 v112, 1.0, v112
	v_add_f32_e32 v113, 1.0, v113
	v_add_f32_e32 v114, 1.0, v114
	v_add_f32_e32 v115, 1.0, v115
	v_add_f32_e32 v116, 1.0, v116
	v_add_f32_e32 v118, 1.0, v118
	v_add_f32_e32 v117, 1.0, v117
	v_add_f32_e32 v119, 1.0, v119
	v_rcp_f32_e32 v112, v112
	v_rcp_f32_e32 v113, v113
	v_rcp_f32_e32 v114, v114
	v_rcp_f32_e32 v171, v115
	v_rcp_f32_e32 v173, v116
	v_rcp_f32_e32 v175, v118
	v_rcp_f32_e32 v117, v117
	v_rcp_f32_e32 v178, v119
	v_mul_f32_e32 v116, v124, v112
	v_mul_f32_e32 v119, v120, v113
	v_mul_f32_e32 v115, v125, v114
	v_mul_f32_e32 v118, v121, v171
	v_mul_f32_e32 v113, v126, v173
	v_mul_f32_e32 v112, v127, v175
	v_cvt_pk_bf16_f32 v120, v116, v115
	v_cvt_pk_bf16_f32 v121, v113, v112
	v_mul_f32_e32 v117, v122, v117
	v_mul_f32_e32 v114, v123, v178
	v_cvt_pk_bf16_f32 v122, v119, v118
	v_cvt_pk_bf16_f32 v123, v117, v114
	global_store_dwordx4 v[158:159], v[120:123], off
	v_mul_f32_e32 v169, 0x3d372713, v160
	v_mul_f32_e32 v169, v160, v169
	v_mul_f32_e32 v121, 0x3d372713, v161
	v_mul_f32_e32 v121, v161, v121
	v_fma_f32 v121, v161, v121, v161
	v_mul_f32_e32 v121, 0x3f4c422a, v121
	v_mul_f32_e32 v121, 0xc038aa3b, v121
	v_mul_f32_e32 v120, 0x3d372713, v154
	v_exp_f32_e32 v121, v121
	v_mul_f32_e32 v120, v154, v120
	v_fma_f32 v169, v160, v169, v160
	v_fma_f32 v120, v154, v120, v154
	v_mul_f32_e32 v169, 0x3f4c422a, v169
	v_mul_f32_e32 v120, 0x3f4c422a, v120
	v_mul_f32_e32 v169, 0xc038aa3b, v169
	v_mul_f32_e32 v120, 0xc038aa3b, v120
	v_add_f32_e32 v121, 1.0, v121
	v_exp_f32_e32 v169, v169
	v_exp_f32_e32 v120, v120
	v_rcp_f32_e32 v123, v121
	v_mul_f32_e32 v121, 0x3d372713, v155
	v_mul_f32_e32 v121, v155, v121
	v_fma_f32 v121, v155, v121, v155
	v_mul_f32_e32 v121, 0x3f4c422a, v121
	v_add_f32_e32 v169, 1.0, v169
	v_add_f32_e32 v120, 1.0, v120
	v_mul_f32_e32 v121, 0xc038aa3b, v121
	v_rcp_f32_e32 v122, v169
	v_rcp_f32_e32 v120, v120
	v_exp_f32_e32 v124, v121
	v_mul_f32_e32 v125, 0x3d372713, v176
	v_mul_f32_e32 v125, v176, v125
	v_mul_f32_e32 v126, 0x3d372713, v157
	v_mul_f32_e32 v121, v160, v122
	v_mul_f32_e32 v122, v154, v120
	v_mul_f32_e32 v120, v161, v123
	v_add_f32_e32 v123, 1.0, v124
	v_mul_f32_e32 v124, 0x3d372713, v156
	v_fma_f32 v125, v176, v125, v176
	v_mul_f32_e32 v126, v157, v126
	v_mul_f32_e32 v127, 0x3d372713, v177
	v_mul_f32_e32 v124, v156, v124
	v_mul_f32_e32 v125, 0x3f4c422a, v125
	v_fma_f32 v126, v157, v126, v157
	v_mul_f32_e32 v127, v177, v127
	v_fma_f32 v124, v156, v124, v156
	v_mul_f32_e32 v125, 0xc038aa3b, v125
	v_mul_f32_e32 v126, 0x3f4c422a, v126
	v_fma_f32 v127, v177, v127, v177
	v_mul_f32_e32 v124, 0x3f4c422a, v124
	v_exp_f32_e32 v125, v125
	v_mul_f32_e32 v126, 0xc038aa3b, v126
	v_mul_f32_e32 v127, 0x3f4c422a, v127
	v_mul_f32_e32 v124, 0xc038aa3b, v124
	v_exp_f32_e32 v126, v126
	v_mul_f32_e32 v127, 0xc038aa3b, v127
	v_exp_f32_e32 v124, v124
	v_exp_f32_e32 v127, v127
	v_rcp_f32_e32 v123, v123
	v_add_f32_e32 v125, 1.0, v125
	v_rcp_f32_e32 v154, v125
	v_add_f32_e32 v125, 1.0, v126
	v_add_f32_e32 v124, 1.0, v124
	v_rcp_f32_e32 v126, v125
	v_add_f32_e32 v125, 1.0, v127
	v_mul_f32_e32 v123, v155, v123
	v_rcp_f32_e32 v124, v124
	v_rcp_f32_e32 v155, v125
	v_mul_f32_e32 v127, v176, v154
	v_cvt_pk_bf16_f32 v154, v121, v120
	v_mul_f32_e32 v125, v156, v124
	v_mul_f32_e32 v124, v157, v126
	v_mul_f32_e32 v126, v177, v155
	v_cvt_pk_bf16_f32 v155, v125, v124
	v_cvt_pk_bf16_f32 v156, v122, v123
	v_cvt_pk_bf16_f32 v157, v127, v126
	global_store_dwordx4 v[158:159], v[154:157], off offset:256
	s_cbranch_scc1 .LBB0_604
	v_mul_f32_e32 v119, v119, v119
	v_fmac_f32_e32 v119, v116, v116
	v_mul_f32_e32 v116, v118, v118
	v_fmac_f32_e32 v116, v115, v115
	v_add_f32_e32 v115, v119, v116
	v_mul_f32_e32 v116, v117, v117
	v_fmac_f32_e32 v116, v113, v113
	v_mul_f32_e32 v114, v114, v114
	v_add_f32_e32 v113, v116, v115
	v_fmac_f32_e32 v114, v112, v112
	v_add_f32_e32 v112, v114, v113
	v_mul_f32_e32 v113, v122, v122
	v_fmac_f32_e32 v113, v121, v121
	v_add_f32_e32 v112, v113, v112
	v_mul_f32_e32 v113, v123, v123
	v_fmac_f32_e32 v113, v120, v120
	v_add_f32_e32 v112, v113, v112
	v_mul_f32_e32 v113, v127, v127
	v_fmac_f32_e32 v113, v125, v125
	v_add_f32_e32 v112, v113, v112
	v_mul_f32_e32 v113, v126, v126
	v_fmac_f32_e32 v113, v124, v124
	v_and_b32_e32 v114, 64, v153
	v_add_f32_e32 v112, v113, v112
	v_xor_b32_e32 v113, 16, v153
	v_add_u32_e32 v114, 64, v114
	v_cmp_lt_i32_e32 vcc, v113, v114
	s_nop 1
	v_cndmask_b32_e32 v113, v153, v113, vcc
	v_lshlrev_b32_e32 v113, 2, v113
	ds_bpermute_b32 v113, v113, v112
	s_waitcnt lgkmcnt(0)
	v_add_f32_e32 v112, v112, v113
	v_xor_b32_e32 v113, 32, v153
	v_cmp_lt_i32_e32 vcc, v113, v114
	s_nop 1
	v_cndmask_b32_e32 v113, v153, v113, vcc
	v_lshlrev_b32_e32 v113, 2, v113
	ds_bpermute_b32 v113, v113, v112
	s_and_saveexec_b64 s[0:1], s[8:9]
	s_cbranch_execz .LBB0_603
	v_lshl_add_u64 v[114:115], v[142:143], 2, s[4:5]
	s_waitcnt lgkmcnt(0)
	v_add_f32_e32 v112, v112, v113
	global_atomic_add_f32 v[114:115], v112, off

.LBB0_748:
	v_readlane_b32 s6, v255, 8
	s_add_u32 s4, s92, 0x40000
	v_readlane_b32 s7, v255, 9
	s_addc_u32 s5, s93, 0
	s_and_b64 vcc, exec, s[6:7]
	s_cbranch_vccnz .LBB0_780
	s_add_u32 s26, s92, 0x7300000
	s_addc_u32 s27, s93, 0
	s_lshr_b32 s6, s3, 6
	s_ashr_i32 s9, s8, 31
	s_ashr_i32 s1, s0, 31
	s_lshr_b32 s7, s3, 8
	s_lshl_b32 s28, s6, 10
	s_lshl_b64 s[10:11], s[8:9], 21
	s_lshl_b64 s[12:13], s[0:1], 20
	s_add_u32 s22, s26, s12
	s_addc_u32 s23, s27, s13
	s_add_i32 s29, s28, 0
	s_add_i32 m0, s29, 0x10000
	v_lshl_or_b32 v128, v236, 13, v219
	v_and_b32_e32 v140, 63, v222
	v_lshrrev_b32_e32 v141, 3, v140
	v_lshrrev_b32_e32 v142, 6, v222
	v_lshl_add_u32 v143, v142, 3, v141
	v_and_b32_e32 v150, 7, v140
	v_and_b32_e32 v151, 6, v141
	v_xor_b32_e32 v150, v150, v151
	v_lshlrev_b32_e32 v150, 4, v150
	v_mul_u32_u24_e32 v151, 0x2000, v143
	v_add_u32_e32 v151, v151, v150
	v_mov_b32_e32 v132, v151
	v_mov_b32_e32 v128, v151
	v_add_u32_e32 v134, 0x80000, v151
	v_add_u32_e32 v130, 0x80000, v151
	v_add_u32_e32 v134, 0x80000, v151
	v_add_u32_e32 v130, 0x80000, v151
	v_and_b32_e32 v151, 31, v143
	v_and_b32_e32 v152, 12, v151
	v_lshlrev_b32_e32 v152, 1, v152
	v_lshrrev_b32_e32 v153, 4, v151
	v_lshlrev_b32_e32 v153, 2, v153
	v_and_b32_e32 v151, 3, v151
	v_or3_b32 v151, v152, v153, v151
	v_and_b32_e32 v152, 0x60, v143
	v_add_u32_e32 v151, v151, v152
	v_mul_u32_u24_e32 v151, 0x1000, v151
	v_add_u32_e32 v151, v151, v150
	v_mov_b32_e32 v164, v151
	v_add_u32_e32 v166, 0x40000, v151
	v_add_u32_e32 v166, 0x40000, v151
	v_and_b32_e32 v151, 15, v140
	v_lshrrev_b32_e32 v152, 4, v140
	v_and_b32_e32 v153, 6, v151
	v_xor_b32_e32 v152, v152, v153
	v_lshlrev_b32_e32 v152, 4, v152
	v_lshl_or_b32 v152, v151, 7, v152
	v_lshrrev_b32_e32 v153, 2, v142
	v_lshl_add_u32 v153, v153, 13, v152
	v_add_u32_e32 v146, 0x0, v153
	v_and_b32_e32 v151, 3, v142
	v_lshl_add_u32 v151, v151, 12, v152
	v_add_u32_e32 v144, 0x0, v151
	v_add_u32_e32 v145, 0x10000, v151
	v_add_u32_e32 v147, 0x14000, v151
	v_add_u32_e32 v149, 0x10000, v151
	global_load_lds_dwordx4 v164, s[22:23]
	s_add_i32 m0, s29, 0x12000
	s_add_u32 s20, s96, s10
	global_load_lds_dwordx4 v166, s[22:23]
	s_addc_u32 s21, s97, s11
	s_mov_b32 m0, s29
	s_add_i32 s30, s29, 0x2000
	global_load_lds_dwordx4 v128, s[20:21]
	s_mov_b32 m0, s30
	s_add_u32 s10, s22, 0x80000
	global_load_lds_dwordx4 v130, s[20:21]
	s_addc_u32 s11, s23, 0
	s_add_i32 m0, s29, 0x14000
	v_mov_b32_e32 v165, 0
	global_load_lds_dwordx4 v164, s[10:11]
	s_add_i32 m0, s29, 0x16000
	v_mov_b32_e32 v167, v165
	global_load_lds_dwordx4 v166, s[10:11]
	s_add_u32 s10, s20, 0x100000
	s_addc_u32 s11, s21, 0
	s_add_i32 s31, s29, 0x4000
	s_mov_b32 m0, s31
	s_add_i32 s33, s29, 0x6000
	global_load_lds_dwordx4 v128, s[10:11]
	s_mov_b32 m0, s33
	v_mov_b32_e32 v129, v165
	global_load_lds_dwordx4 v130, s[10:11]
	v_mov_b32_e32 v131, v165
	s_mov_b32 s34, 0
	v_lshl_add_u64 v[6:7], s[22:23], 0, v[164:165]
	v_lshl_add_u64 v[4:5], s[22:23], 0, v[166:167]
	v_lshl_add_u64 v[2:3], s[20:21], 0, v[128:129]
	s_cmp_lg_u32 s7, 1
	v_lshl_add_u64 v[0:1], s[20:21], 0, v[130:131]
	s_cbranch_scc1 .LBB0_751
	s_barrier
.LBB0_751:
	s_mov_b64 s[10:11], 0x80
	s_lshl_b32 s6, s6, 5
	s_add_i32 m0, s29, 0x18000
	v_lshl_add_u64 v[6:7], v[6:7], 0, s[10:11]
	s_lshl_b32 s35, s7, 6
	s_lshl_b32 s1, s7, 13
	s_and_b32 s36, s6, 0x60
	s_waitcnt vmcnt(4)
	s_barrier
	global_load_lds_dwordx4 v[6:7], off
	v_lshl_add_u64 v[4:5], v[4:5], 0, s[10:11]
	s_add_i32 m0, s29, 0x1a000
	s_add_i32 s37, s29, 0x8000
	s_add_i32 s38, s29, 0xa000
	global_load_lds_dwordx4 v[4:5], off
	v_lshl_add_u64 v[2:3], v[2:3], 0, s[10:11]
	s_mov_b32 m0, s37
	s_add_u32 s6, s22, 0x80080
	global_load_lds_dwordx4 v[2:3], off
	v_lshl_add_u64 v[0:1], v[0:1], 0, s[10:11]
	s_mov_b32 m0, s38
	s_addc_u32 s7, s23, 0
	global_load_lds_dwordx4 v[0:1], off
	s_add_i32 m0, s29, 0x1c000
	v_lshl_add_u64 v[0:1], s[6:7], 0, v[164:165]
	global_load_lds_dwordx4 v[0:1], off
	v_lshl_add_u64 v[0:1], s[6:7], 0, v[166:167]
	s_add_i32 m0, s29, 0x1e000
	v_lshlrev_b32_e32 v2, 13, v218
	global_load_lds_dwordx4 v[0:1], off
	v_lshlrev_b32_e32 v1, 2, v163
	v_lshl_or_b32 v0, v163, 6, v227
	v_and_b32_e32 v1, 32, v1
	v_bitop3_b32 v0, v0, s1, v1 bitop3:0xde
	v_lshlrev_b32_e32 v1, 10, v222
	v_and_b32_e32 v1, 0xe0000, v1
	v_or3_b32 v1, v226, v1, v2
	v_lshlrev_b32_e32 v1, 6, v233
	s_waitcnt vmcnt(6)
	v_and_b32_e32 v1, 0x1e0000, v1
	v_or3_b32 v1, v226, v1, v2
	s_add_i32 s41, 0, 0x10000
	s_add_i32 s42, 0, 0x14000
	v_mbcnt_lo_u32_b32 v0, -1, 0
	s_ashr_i32 s39, s94, 31
	s_mov_b32 s40, s94
	v_mov_b32_e32 v133, v165
	v_mov_b32_e32 v135, v165
	v_mov_b64_e32 v[136:137], 0x200
	v_mov_b64_e32 v[138:139], 0x1ff
	v_mbcnt_hi_u32_b32 v148, -1, v0
	s_barrier
	s_branch .LBB0_753

.LBB0_760:
	ds_read_b128 v[140:143], v145
	v_xor_b32_e32 v161, 64, v145
	ds_read_b128 v[150:153], v161
	ds_read_b128 v[154:157], v145 offset:2048
	ds_read_b128 v[158:161], v161 offset:2048
	s_add_u32 s22, s20, 0xfff00080
	s_addc_u32 s23, s21, -1
	s_cmp_eq_u32 s45, 28
	s_cselect_b32 s25, s1, s23
	s_cselect_b32 s24, s9, s22
	s_cselect_b32 s23, s13, s44
	s_cselect_b32 s22, s15, s43
	v_lshl_add_u64 v[208:209], s[20:21], 0, v[132:133]
	s_add_i32 m0, s29, 0xc000
	ds_read_b128 v[176:179], v146
	v_xor_b32_e32 v207, 64, v146
	ds_read_b128 v[180:183], v207
	ds_read_b128 v[184:187], v146 offset:2048
	ds_read_b128 v[188:191], v207 offset:2048
	ds_read_b128 v[192:195], v146 offset:4096
	ds_read_b128 v[196:199], v207 offset:4096
	ds_read_b128 v[200:203], v146 offset:6144
	ds_read_b128 v[204:207], v207 offset:6144
	global_load_lds_dwordx4 v[208:209], off
	v_lshl_add_u64 v[208:209], s[20:21], 0, v[134:135]
	s_add_i32 m0, s29, 0xe000
	s_nop 0
	global_load_lds_dwordx4 v[208:209], off
	s_waitcnt lgkmcnt(8)
	s_barrier
	s_waitcnt lgkmcnt(0)
	s_setprio 1
	s_waitcnt lgkmcnt(0)
	v_mfma_f32_16x16x32_bf16 v[124:127], v[140:143], v[176:179], v[124:127]
	v_mfma_f32_16x16x32_bf16 v[120:123], v[154:157], v[176:179], v[120:123]
	v_mfma_f32_16x16x32_bf16 v[108:111], v[140:143], v[184:187], v[108:111]
	v_mfma_f32_16x16x32_bf16 v[104:107], v[154:157], v[184:187], v[104:107]
	v_mfma_f32_16x16x32_bf16 v[92:95], v[140:143], v[192:195], v[92:95]
	v_mfma_f32_16x16x32_bf16 v[88:91], v[154:157], v[192:195], v[88:91]
	v_mfma_f32_16x16x32_bf16 v[76:79], v[140:143], v[200:203], v[76:79]
	v_mfma_f32_16x16x32_bf16 v[72:75], v[154:157], v[200:203], v[72:75]
	v_mfma_f32_16x16x32_bf16 v[124:127], v[150:153], v[180:183], v[124:127]
	v_mfma_f32_16x16x32_bf16 v[120:123], v[158:161], v[180:183], v[120:123]
	v_mfma_f32_16x16x32_bf16 v[108:111], v[150:153], v[188:191], v[108:111]
	v_mfma_f32_16x16x32_bf16 v[104:107], v[158:161], v[188:191], v[104:107]
	v_mfma_f32_16x16x32_bf16 v[92:95], v[150:153], v[196:199], v[92:95]
	v_mfma_f32_16x16x32_bf16 v[88:91], v[158:161], v[196:199], v[88:91]
	v_mfma_f32_16x16x32_bf16 v[76:79], v[150:153], v[204:207], v[76:79]
	v_mfma_f32_16x16x32_bf16 v[72:75], v[158:161], v[204:207], v[72:75]
	s_setprio 0
	s_barrier
	s_add_i32 s46, s41, s28
	v_lshl_add_u64 v[216:217], s[22:23], 0, v[164:165]
	s_mov_b32 m0, s46
	ds_read_b128 v[208:211], v147
	v_xor_b32_e32 v243, 64, v147
	ds_read_b128 v[212:215], v243
	ds_read_b128 v[236:239], v147 offset:2048
	ds_read_b128 v[240:243], v243 offset:2048
	global_load_lds_dwordx4 v[216:217], off
	v_lshl_add_u64 v[234:235], s[22:23], 0, v[166:167]
	s_add_i32 m0, s46, 0x2000
	s_nop 0
	global_load_lds_dwordx4 v[234:235], off
	s_barrier
	s_waitcnt lgkmcnt(0)
	s_setprio 1
	s_waitcnt lgkmcnt(0)
	v_mfma_f32_16x16x32_bf16 v[116:119], v[208:211], v[176:179], v[116:119]
	v_mfma_f32_16x16x32_bf16 v[112:115], v[236:239], v[176:179], v[112:115]
	v_mfma_f32_16x16x32_bf16 v[100:103], v[208:211], v[184:187], v[100:103]
	v_mfma_f32_16x16x32_bf16 v[96:99], v[236:239], v[184:187], v[96:99]
	v_mfma_f32_16x16x32_bf16 v[84:87], v[208:211], v[192:195], v[84:87]
	v_mfma_f32_16x16x32_bf16 v[80:83], v[236:239], v[192:195], v[80:83]
	v_mfma_f32_16x16x32_bf16 v[68:71], v[208:211], v[200:203], v[68:71]
	v_mfma_f32_16x16x32_bf16 v[64:67], v[236:239], v[200:203], v[64:67]
	v_mfma_f32_16x16x32_bf16 v[116:119], v[212:215], v[180:183], v[116:119]
	v_mfma_f32_16x16x32_bf16 v[112:115], v[240:243], v[180:183], v[112:115]
	v_mfma_f32_16x16x32_bf16 v[100:103], v[212:215], v[188:191], v[100:103]
	v_mfma_f32_16x16x32_bf16 v[96:99], v[240:243], v[188:191], v[96:99]
	v_mfma_f32_16x16x32_bf16 v[84:87], v[212:215], v[196:199], v[84:87]
	v_mfma_f32_16x16x32_bf16 v[80:83], v[240:243], v[196:199], v[80:83]
	v_mfma_f32_16x16x32_bf16 v[68:71], v[212:215], v[204:207], v[68:71]
	v_mfma_f32_16x16x32_bf16 v[64:67], v[240:243], v[204:207], v[64:67]
	s_setprio 0
	s_mov_b32 m0, s29
	v_lshl_add_u64 v[244:245], s[24:25], 0, v[128:129]
	s_barrier
	ds_read_b128 v[176:179], v146 offset:16384
	v_xor_b32_e32 v207, 64, v146
	ds_read_b128 v[180:183], v207 offset:16384
	ds_read_b128 v[184:187], v146 offset:18432
	ds_read_b128 v[188:191], v207 offset:18432
	ds_read_b128 v[192:195], v146 offset:20480
	ds_read_b128 v[196:199], v207 offset:20480
	ds_read_b128 v[200:203], v146 offset:22528
	ds_read_b128 v[204:207], v207 offset:22528
	global_load_lds_dwordx4 v[244:245], off
	v_lshl_add_u64 v[246:247], s[24:25], 0, v[130:131]
	s_mov_b32 m0, s30
	s_nop 0
	global_load_lds_dwordx4 v[246:247], off
	s_barrier
	s_waitcnt lgkmcnt(0)
	s_setprio 1
	s_waitcnt lgkmcnt(0)
	v_mfma_f32_16x16x32_bf16 v[60:63], v[140:143], v[176:179], v[60:63]
	v_mfma_f32_16x16x32_bf16 v[56:59], v[154:157], v[176:179], v[56:59]
	v_mfma_f32_16x16x32_bf16 v[44:47], v[140:143], v[184:187], v[44:47]
	v_mfma_f32_16x16x32_bf16 v[40:43], v[154:157], v[184:187], v[40:43]
	v_mfma_f32_16x16x32_bf16 v[28:31], v[140:143], v[192:195], v[28:31]
	v_mfma_f32_16x16x32_bf16 v[24:27], v[154:157], v[192:195], v[24:27]
	v_mfma_f32_16x16x32_bf16 v[12:15], v[140:143], v[200:203], v[12:15]
	v_mfma_f32_16x16x32_bf16 v[8:11], v[154:157], v[200:203], v[8:11]
	v_mfma_f32_16x16x32_bf16 v[60:63], v[150:153], v[180:183], v[60:63]
	v_mfma_f32_16x16x32_bf16 v[56:59], v[158:161], v[180:183], v[56:59]
	v_mfma_f32_16x16x32_bf16 v[44:47], v[150:153], v[188:191], v[44:47]
	v_mfma_f32_16x16x32_bf16 v[40:43], v[158:161], v[188:191], v[40:43]
	v_mfma_f32_16x16x32_bf16 v[28:31], v[150:153], v[196:199], v[28:31]
	v_mfma_f32_16x16x32_bf16 v[24:27], v[158:161], v[196:199], v[24:27]
	v_mfma_f32_16x16x32_bf16 v[12:15], v[150:153], v[204:207], v[12:15]
	v_mfma_f32_16x16x32_bf16 v[8:11], v[158:161], v[204:207], v[8:11]
	s_setprio 0
	s_barrier
	s_add_u32 s46, s22, 0x80000
	s_addc_u32 s47, s23, 0
	s_add_i32 s48, s42, s28
	v_lshl_add_u64 v[140:141], s[46:47], 0, v[164:165]
	s_mov_b32 m0, s48
	s_nop 0
	global_load_lds_dwordx4 v[140:141], off
	v_lshl_add_u64 v[140:141], s[46:47], 0, v[166:167]
	s_add_i32 m0, s48, 0x2000
	s_nop 0
	global_load_lds_dwordx4 v[140:141], off
	s_waitcnt vmcnt(6)
	s_barrier
	s_setprio 1
	v_mfma_f32_16x16x32_bf16 v[52:55], v[208:211], v[176:179], v[52:55]
	v_mfma_f32_16x16x32_bf16 v[48:51], v[236:239], v[176:179], v[48:51]
	v_mfma_f32_16x16x32_bf16 v[36:39], v[208:211], v[184:187], v[36:39]
	v_mfma_f32_16x16x32_bf16 v[32:35], v[236:239], v[184:187], v[32:35]
	v_mfma_f32_16x16x32_bf16 v[20:23], v[208:211], v[192:195], v[20:23]
	v_mfma_f32_16x16x32_bf16 v[16:19], v[236:239], v[192:195], v[16:19]
	v_mfma_f32_16x16x32_bf16 v[4:7], v[208:211], v[200:203], v[4:7]
	v_mfma_f32_16x16x32_bf16 v[0:3], v[236:239], v[200:203], v[0:3]
	v_mfma_f32_16x16x32_bf16 v[52:55], v[212:215], v[180:183], v[52:55]
	v_mfma_f32_16x16x32_bf16 v[48:51], v[240:243], v[180:183], v[48:51]
	v_mfma_f32_16x16x32_bf16 v[36:39], v[212:215], v[188:191], v[36:39]
	v_mfma_f32_16x16x32_bf16 v[32:35], v[240:243], v[188:191], v[32:35]
	v_mfma_f32_16x16x32_bf16 v[20:23], v[212:215], v[196:199], v[20:23]
	v_mfma_f32_16x16x32_bf16 v[16:19], v[240:243], v[196:199], v[16:19]
	v_mfma_f32_16x16x32_bf16 v[4:7], v[212:215], v[204:207], v[4:7]
	v_mfma_f32_16x16x32_bf16 v[0:3], v[240:243], v[204:207], v[0:3]
	s_setprio 0
	s_add_i32 s46, 0, 0x18000
	v_add_u32_e32 v149, s46, v144
	s_barrier
	ds_read_b128 v[140:143], v149
	v_xor_b32_e32 v161, 64, v149
	ds_read_b128 v[150:153], v161
	ds_read_b128 v[154:157], v149 offset:2048
	ds_read_b128 v[158:161], v161 offset:2048
	s_add_u32 s24, s24, 0x100000
	s_addc_u32 s25, s25, 0
	s_mov_b32 m0, s31
	v_lshl_add_u64 v[208:209], s[24:25], 0, v[128:129]
	ds_read_b128 v[176:179], v146 offset:32768
	v_xor_b32_e32 v207, 64, v146
	ds_read_b128 v[180:183], v207 offset:32768
	ds_read_b128 v[184:187], v146 offset:34816
	ds_read_b128 v[188:191], v207 offset:34816
	ds_read_b128 v[192:195], v146 offset:36864
	ds_read_b128 v[196:199], v207 offset:36864
	ds_read_b128 v[200:203], v146 offset:38912
	ds_read_b128 v[204:207], v207 offset:38912
	global_load_lds_dwordx4 v[208:209], off
	v_lshl_add_u64 v[208:209], s[24:25], 0, v[130:131]
	s_mov_b32 m0, s33
	s_nop 0
	global_load_lds_dwordx4 v[208:209], off
	s_waitcnt lgkmcnt(8)
	s_barrier
	s_waitcnt lgkmcnt(0)
	s_setprio 1
	s_waitcnt lgkmcnt(0)
	v_mfma_f32_16x16x32_bf16 v[124:127], v[140:143], v[176:179], v[124:127]
	v_mfma_f32_16x16x32_bf16 v[120:123], v[154:157], v[176:179], v[120:123]
	v_mfma_f32_16x16x32_bf16 v[108:111], v[140:143], v[184:187], v[108:111]
	v_mfma_f32_16x16x32_bf16 v[104:107], v[154:157], v[184:187], v[104:107]
	v_mfma_f32_16x16x32_bf16 v[92:95], v[140:143], v[192:195], v[92:95]
	v_mfma_f32_16x16x32_bf16 v[88:91], v[154:157], v[192:195], v[88:91]
	v_mfma_f32_16x16x32_bf16 v[76:79], v[140:143], v[200:203], v[76:79]
	v_mfma_f32_16x16x32_bf16 v[72:75], v[154:157], v[200:203], v[72:75]
	v_mfma_f32_16x16x32_bf16 v[124:127], v[150:153], v[180:183], v[124:127]
	v_mfma_f32_16x16x32_bf16 v[120:123], v[158:161], v[180:183], v[120:123]
	v_mfma_f32_16x16x32_bf16 v[108:111], v[150:153], v[188:191], v[108:111]
	v_mfma_f32_16x16x32_bf16 v[104:107], v[158:161], v[188:191], v[104:107]
	v_mfma_f32_16x16x32_bf16 v[92:95], v[150:153], v[196:199], v[92:95]
	v_mfma_f32_16x16x32_bf16 v[88:91], v[158:161], v[196:199], v[88:91]
	v_mfma_f32_16x16x32_bf16 v[76:79], v[150:153], v[204:207], v[76:79]
	v_mfma_f32_16x16x32_bf16 v[72:75], v[158:161], v[204:207], v[72:75]
	s_setprio 0
	s_barrier
	s_add_i32 s24, 0, 0x1c000
	s_add_i32 s25, s46, s28
	v_add_u32_e32 v149, s24, v144
	v_lshl_add_u64 v[216:217], v[216:217], 0, s[10:11]
	s_mov_b32 m0, s25
	ds_read_b128 v[208:211], v149
	v_xor_b32_e32 v243, 64, v149
	ds_read_b128 v[212:215], v243
	ds_read_b128 v[236:239], v149 offset:2048
	ds_read_b128 v[240:243], v243 offset:2048
	global_load_lds_dwordx4 v[216:217], off
	v_lshl_add_u64 v[216:217], v[234:235], 0, s[10:11]
	s_add_i32 m0, s25, 0x2000
	s_nop 0
	global_load_lds_dwordx4 v[216:217], off
	s_barrier
	s_waitcnt lgkmcnt(0)
	s_setprio 1
	s_waitcnt lgkmcnt(0)
	v_mfma_f32_16x16x32_bf16 v[116:119], v[208:211], v[176:179], v[116:119]
	v_mfma_f32_16x16x32_bf16 v[112:115], v[236:239], v[176:179], v[112:115]
	v_mfma_f32_16x16x32_bf16 v[100:103], v[208:211], v[184:187], v[100:103]
	v_mfma_f32_16x16x32_bf16 v[96:99], v[236:239], v[184:187], v[96:99]
	v_mfma_f32_16x16x32_bf16 v[84:87], v[208:211], v[192:195], v[84:87]
	v_mfma_f32_16x16x32_bf16 v[80:83], v[236:239], v[192:195], v[80:83]
	v_mfma_f32_16x16x32_bf16 v[68:71], v[208:211], v[200:203], v[68:71]
	v_mfma_f32_16x16x32_bf16 v[64:67], v[236:239], v[200:203], v[64:67]
	v_mfma_f32_16x16x32_bf16 v[116:119], v[212:215], v[180:183], v[116:119]
	v_mfma_f32_16x16x32_bf16 v[112:115], v[240:243], v[180:183], v[112:115]
	v_mfma_f32_16x16x32_bf16 v[100:103], v[212:215], v[188:191], v[100:103]
	v_mfma_f32_16x16x32_bf16 v[96:99], v[240:243], v[188:191], v[96:99]
	v_mfma_f32_16x16x32_bf16 v[84:87], v[212:215], v[196:199], v[84:87]
	v_mfma_f32_16x16x32_bf16 v[80:83], v[240:243], v[196:199], v[80:83]
	v_mfma_f32_16x16x32_bf16 v[68:71], v[212:215], v[204:207], v[68:71]
	v_mfma_f32_16x16x32_bf16 v[64:67], v[240:243], v[204:207], v[64:67]
	s_setprio 0
	s_mov_b32 m0, s37
	v_lshl_add_u64 v[216:217], v[244:245], 0, s[10:11]
	s_barrier
	ds_read_b128 v[176:179], v146 offset:49152
	v_xor_b32_e32 v207, 64, v146
	ds_read_b128 v[180:183], v207 offset:49152
	ds_read_b128 v[184:187], v146 offset:51200
	ds_read_b128 v[188:191], v207 offset:51200
	ds_read_b128 v[192:195], v146 offset:53248
	ds_read_b128 v[196:199], v207 offset:53248
	ds_read_b128 v[200:203], v146 offset:55296
	ds_read_b128 v[204:207], v207 offset:55296
	global_load_lds_dwordx4 v[216:217], off
	v_lshl_add_u64 v[216:217], v[246:247], 0, s[10:11]
	s_mov_b32 m0, s38
	s_nop 0
	global_load_lds_dwordx4 v[216:217], off
	s_barrier
	s_waitcnt lgkmcnt(0)
	s_setprio 1
	s_waitcnt lgkmcnt(0)
	v_mfma_f32_16x16x32_bf16 v[60:63], v[140:143], v[176:179], v[60:63]
	v_mfma_f32_16x16x32_bf16 v[56:59], v[154:157], v[176:179], v[56:59]
	v_mfma_f32_16x16x32_bf16 v[44:47], v[140:143], v[184:187], v[44:47]
	v_mfma_f32_16x16x32_bf16 v[40:43], v[154:157], v[184:187], v[40:43]
	v_mfma_f32_16x16x32_bf16 v[28:31], v[140:143], v[192:195], v[28:31]
	v_mfma_f32_16x16x32_bf16 v[24:27], v[154:157], v[192:195], v[24:27]
	v_mfma_f32_16x16x32_bf16 v[12:15], v[140:143], v[200:203], v[12:15]
	v_mfma_f32_16x16x32_bf16 v[8:11], v[154:157], v[200:203], v[8:11]
	v_mfma_f32_16x16x32_bf16 v[60:63], v[150:153], v[180:183], v[60:63]
	v_mfma_f32_16x16x32_bf16 v[56:59], v[158:161], v[180:183], v[56:59]
	v_mfma_f32_16x16x32_bf16 v[44:47], v[150:153], v[188:191], v[44:47]
	v_mfma_f32_16x16x32_bf16 v[40:43], v[158:161], v[188:191], v[40:43]
	v_mfma_f32_16x16x32_bf16 v[28:31], v[150:153], v[196:199], v[28:31]
	v_mfma_f32_16x16x32_bf16 v[24:27], v[158:161], v[196:199], v[24:27]
	v_mfma_f32_16x16x32_bf16 v[12:15], v[150:153], v[204:207], v[12:15]
	v_mfma_f32_16x16x32_bf16 v[8:11], v[158:161], v[204:207], v[8:11]
	s_setprio 0
	s_barrier
	s_add_u32 s22, s22, 0x80080
	s_addc_u32 s23, s23, 0
	s_add_i32 s24, s24, s28
	v_lshl_add_u64 v[140:141], s[22:23], 0, v[164:165]
	s_mov_b32 m0, s24
	s_nop 0
	global_load_lds_dwordx4 v[140:141], off
	v_lshl_add_u64 v[140:141], s[22:23], 0, v[166:167]
	s_add_i32 m0, s24, 0x2000
	s_nop 0
	global_load_lds_dwordx4 v[140:141], off
	s_waitcnt vmcnt(6)
	s_barrier
	s_setprio 1
	v_mfma_f32_16x16x32_bf16 v[52:55], v[208:211], v[176:179], v[52:55]
	v_mfma_f32_16x16x32_bf16 v[48:51], v[236:239], v[176:179], v[48:51]
	v_mfma_f32_16x16x32_bf16 v[36:39], v[208:211], v[184:187], v[36:39]
	v_mfma_f32_16x16x32_bf16 v[32:35], v[236:239], v[184:187], v[32:35]
	v_mfma_f32_16x16x32_bf16 v[20:23], v[208:211], v[192:195], v[20:23]
	v_mfma_f32_16x16x32_bf16 v[16:19], v[236:239], v[192:195], v[16:19]
	v_mfma_f32_16x16x32_bf16 v[4:7], v[208:211], v[200:203], v[4:7]
	v_mfma_f32_16x16x32_bf16 v[0:3], v[236:239], v[200:203], v[0:3]
	v_mfma_f32_16x16x32_bf16 v[52:55], v[212:215], v[180:183], v[52:55]
	v_mfma_f32_16x16x32_bf16 v[48:51], v[240:243], v[180:183], v[48:51]
	v_mfma_f32_16x16x32_bf16 v[36:39], v[212:215], v[188:191], v[36:39]
	v_mfma_f32_16x16x32_bf16 v[32:35], v[240:243], v[188:191], v[32:35]
	v_mfma_f32_16x16x32_bf16 v[20:23], v[212:215], v[196:199], v[20:23]
	v_mfma_f32_16x16x32_bf16 v[16:19], v[240:243], v[196:199], v[16:19]
	v_mfma_f32_16x16x32_bf16 v[4:7], v[212:215], v[204:207], v[4:7]
	v_mfma_f32_16x16x32_bf16 v[0:3], v[240:243], v[204:207], v[0:3]
	s_setprio 0
	s_add_i32 s45, s45, 2
	s_add_u32 s20, s20, 0x100
	s_addc_u32 s21, s21, 0
	s_add_u32 s43, s43, 0x100
	s_addc_u32 s44, s44, 0
	s_cmp_gt_u32 s45, 29
	s_barrier
	s_cbranch_scc0 .LBB0_760
	s_lshl_b32 s1, s8, 8
	v_mov_b32_e32 v140, v163
	v_mov_b32_e32 v149, v225
	s_add_i32 s1, s1, s35
	s_lshl_b32 s0, s0, 8
	v_add_u32_e32 v142, s1, v140
	s_or_b32 s0, s0, s36
	v_ashrrev_i32_e32 v143, 31, v142
	v_lshl_add_u32 v140, v149, 3, s0
	v_lshlrev_b64 v[150:151], 12, v[142:143]
	v_ashrrev_i32_e32 v141, 31, v140
	v_lshl_add_u64 v[150:151], s[80:81], 0, v[150:151]
	v_lshl_add_u64 v[154:155], v[140:141], 1, v[150:151]
	global_load_dwordx4 v[150:153], v[154:155], off
	v_cmp_eq_u32_e32 vcc, 0, v149
	v_xor_b32_e32 v169, 32, v148
	s_waitcnt vmcnt(0)
	v_lshlrev_b32_e32 v156, 16, v150
	v_and_b32_e32 v157, 0xffff0000, v150
	v_lshlrev_b32_e32 v150, 16, v151
	v_and_b32_e32 v151, 0xffff0000, v151
	v_lshlrev_b32_e32 v158, 16, v152
	v_and_b32_e32 v159, 0xffff0000, v152
	v_lshlrev_b32_e32 v152, 16, v153
	v_and_b32_e32 v153, 0xffff0000, v153
	v_pk_add_f32 v[126:127], v[126:127], v[150:151]
	v_pk_add_f32 v[156:157], v[124:125], v[156:157]
	v_pk_add_f32 v[160:161], v[122:123], v[152:153]
	v_pk_add_f32 v[158:159], v[120:121], v[158:159]
	v_cvt_pk_bf16_f32 v122, v156, v157
	v_cvt_pk_bf16_f32 v123, v126, v127
	v_and_b32_e32 v121, 64, v148
	v_cvt_pk_bf16_f32 v124, v158, v159
	v_cvt_pk_bf16_f32 v125, v160, v161
	global_load_dwordx4 v[150:153], v[154:155], off offset:256
	v_mul_f32_e32 v149, v158, v158
	v_mul_f32_e32 v158, v159, v159
	v_mul_f32_e32 v159, v160, v160
	v_fmac_f32_e32 v149, v156, v156
	v_fmac_f32_e32 v158, v157, v157
	v_mul_f32_e32 v160, v161, v161
	v_fmac_f32_e32 v159, v126, v126
	v_add_f32_e32 v126, v149, v158
	v_fmac_f32_e32 v160, v127, v127
	v_add_f32_e32 v126, v159, v126
	v_add_f32_e32 v149, v160, v126
	v_xor_b32_e32 v120, 16, v148
	v_add_u32_e32 v121, 64, v121
	v_cmp_lt_i32_e64 s[8:9], v120, v121
	global_store_dwordx4 v[154:155], v[122:125], off
	s_waitcnt vmcnt(0)
	v_lshlrev_b32_e32 v126, 16, v150
	v_and_b32_e32 v127, 0xffff0000, v150
	v_lshlrev_b32_e32 v150, 16, v151
	v_and_b32_e32 v151, 0xffff0000, v151
	v_lshlrev_b32_e32 v156, 16, v152
	v_and_b32_e32 v157, 0xffff0000, v152
	v_pk_add_f32 v[118:119], v[118:119], v[150:151]
	v_pk_add_f32 v[150:151], v[112:113], v[156:157]
	v_lshlrev_b32_e32 v152, 16, v153
	v_and_b32_e32 v153, 0xffff0000, v153
	v_pk_add_f32 v[116:117], v[116:117], v[126:127]
	v_mul_f32_e32 v112, v150, v150
	v_pk_add_f32 v[126:127], v[114:115], v[152:153]
	v_mul_f32_e32 v113, v151, v151
	v_fmac_f32_e32 v112, v116, v116
	v_mul_f32_e32 v114, v126, v126
	v_fmac_f32_e32 v113, v117, v117
	v_add_f32_e32 v112, v149, v112
	v_mul_f32_e32 v115, v127, v127
	v_fmac_f32_e32 v114, v118, v118
	v_add_f32_e32 v112, v113, v112
	v_cndmask_b32_e64 v120, v148, v120, s[8:9]
	v_fmac_f32_e32 v115, v119, v119
	v_add_f32_e32 v112, v114, v112
	v_lshlrev_b32_e32 v120, 2, v120
	v_add_f32_e32 v112, v115, v112
	ds_bpermute_b32 v113, v120, v112
	v_cmp_lt_i32_e64 s[8:9], v169, v121
	v_cvt_pk_bf16_f32 v116, v116, v117
	v_cvt_pk_bf16_f32 v117, v118, v119
	v_cvt_pk_bf16_f32 v118, v150, v151
	s_waitcnt lgkmcnt(0)
	v_add_f32_e32 v112, v112, v113
	v_cvt_pk_bf16_f32 v119, v126, v127
	v_cndmask_b32_e64 v114, v148, v169, s[8:9]
	v_lshlrev_b32_e32 v114, 2, v114
	ds_bpermute_b32 v113, v114, v112
	global_store_dwordx4 v[154:155], v[116:119], off offset:256
	s_and_saveexec_b64 s[0:1], vcc
	s_cbranch_execz .LBB0_763
	s_waitcnt lgkmcnt(0)
	v_add_f32_e32 v115, v112, v113
	v_lshl_add_u64 v[112:113], v[142:143], 2, s[4:5]
	global_atomic_add_f32 v[112:113], v115, off

.LBB0_832:
	s_or_b64 exec, exec, s[0:1]
	s_add_u32 s14, s82, 0x21000
	s_addc_u32 s15, s83, 0
	v_readlane_b32 s0, v255, 10
	s_add_u32 s16, s84, 0xb000
	v_readlane_b32 s1, v255, 11
	s_addc_u32 s17, s85, 0
	s_andn2_b64 vcc, exec, s[0:1]
	v_readfirstlane_b32 s3, v222
	s_waitcnt lgkmcnt(0)
	s_barrier
	s_cbranch_vccnz .LBB0_854
	s_add_u32 s44, s92, 0x7b00000
	s_addc_u32 s45, s93, 0
	s_lshr_b32 s0, s77, 29
	s_add_i32 s0, s2, s0
	s_lshr_b32 s12, s3, 6
	s_ashr_i32 s1, s0, 3
	s_and_b32 s0, s0, -8
	s_lshr_b32 s7, s3, 8
	s_lshl_b32 s46, s12, 10
	s_sub_i32 s0, s2, s0
	s_cmp_lt_i32 s0, 0
	s_movk_i32 s47, 0x161
	s_cselect_b32 s6, s47, 0x160
	s_mul_i32 s0, s6, s0
	s_add_i32 s0, s0, s1
	s_mul_hi_i32 s1, s0, 0x2e8ba2e9
	s_lshr_b32 s6, s1, 31
	s_ashr_i32 s1, s1, 5
	s_add_i32 s1, s1, s6
	s_lshl_b32 s8, s1, 2
	s_mulk_i32 s1, 0xb0
	s_sub_i32 s0, s0, s1
	s_sext_i32_i16 s1, s0
	s_bfe_u32 s1, s1, 0x2001d
	s_add_i32 s1, s0, s1
	s_sext_i32_i16 s6, s1
	s_and_b32 s1, s1, 0xfffc
	s_sub_i32 s0, s0, s1
	s_sext_i32_i16 s0, s0
	s_lshr_b32 s6, s6, 2
	s_add_i32 s0, s8, s0
	s_ashr_i32 s1, s0, 31
	s_bfe_i64 s[10:11], s[6:7], 0x100000
	s_lshl_b64 s[8:9], s[0:1], 20
	s_lshl_b64 s[10:11], s[10:11], 19
	s_add_u32 s10, s44, s10
	s_addc_u32 s11, s45, s11
	s_add_i32 s48, s46, 0
	v_and_b32_e32 v8, 0x180, v223
	s_add_i32 m0, s48, 0x10000
	v_or3_b32 v0, v220, v8, v218
	v_and_b32_e32 v9, 0x80, v254
	v_and_b32_e32 v191, 63, v222
	v_lshrrev_b32_e32 v192, 3, v191
	v_lshrrev_b32_e32 v193, 6, v222
	v_lshl_add_u32 v194, v193, 3, v192
	v_and_b32_e32 v195, 7, v191
	v_and_b32_e32 v196, 6, v192
	v_xor_b32_e32 v195, v195, v196
	v_lshlrev_b32_e32 v195, 4, v195
	v_mul_u32_u24_e32 v196, 0x1000, v194
	v_add_u32_e32 v196, v196, v195
	v_add_u32_e32 v176, 0x80000, v196
	v_mov_b32_e32 v178, v196
	v_add_u32_e32 v180, 0x40080, v196
	v_add_u32_e32 v182, 0xc0080, v196
	v_add_u32_e32 v176, 0x80000, v196
	v_add_u32_e32 v182, 0xc0080, v196
	v_and_b32_e32 v196, 31, v194
	v_and_b32_e32 v197, 12, v196
	v_lshlrev_b32_e32 v197, 1, v197
	v_lshrrev_b32_e32 v198, 4, v196
	v_lshlrev_b32_e32 v198, 2, v198
	v_and_b32_e32 v196, 3, v196
	v_or3_b32 v196, v197, v198, v196
	v_and_b32_e32 v197, 0x60, v194
	v_add_u32_e32 v196, v196, v197
	v_mul_u32_u24_e32 v196, 0x1000, v196
	v_add_u32_e32 v196, v196, v195
	v_mov_b32_e32 v164, v196
	v_add_u32_e32 v166, 0x40000, v196
	v_add_u32_e32 v166, 0x40000, v196
	v_and_b32_e32 v196, 15, v191
	v_lshrrev_b32_e32 v197, 4, v191
	v_and_b32_e32 v198, 6, v196
	v_xor_b32_e32 v197, v197, v198
	v_lshlrev_b32_e32 v197, 4, v197
	v_lshl_or_b32 v197, v196, 7, v197
	v_lshrrev_b32_e32 v198, 2, v193
	v_lshl_add_u32 v198, v198, 13, v197
	v_add_u32_e32 v173, 0x0, v198
	v_and_b32_e32 v196, 3, v193
	v_lshl_add_u32 v196, v196, 12, v197
	v_add_u32_e32 v171, 0x10000, v196
	v_add_u32_e32 v169, 0x0, v196
	v_add_u32_e32 v175, 0x14000, v196
	v_add_u32_e32 v242, 0x14000, v196
	v_mov_b32_e32 v181, 0x0
	v_mov_b32_e32 v183, 0x0
	global_load_lds_dwordx4 v164, s[10:11]
	s_add_i32 m0, s48, 0x12000
	v_or3_b32 v0, v221, v9, v218
	s_add_u32 s8, s80, s8
	global_load_lds_dwordx4 v166, s[10:11]
	s_addc_u32 s9, s81, s9
	s_mov_b32 m0, s48
	s_add_i32 s49, s48, 0x2000
	global_load_lds_dwordx4 v178, s[8:9]
	s_mov_b32 m0, s49
	s_add_u32 s18, s10, 0x1600000
	global_load_lds_dwordx4 v176, s[8:9]
	s_addc_u32 s19, s11, 0
	s_add_i32 m0, s48, 0x14000
	v_mov_b32_e32 v165, 0
	global_load_lds_dwordx4 v164, s[18:19]
	s_add_i32 m0, s48, 0x16000
	v_mov_b32_e32 v167, v165
	global_load_lds_dwordx4 v166, s[18:19]
	s_add_u32 s18, s8, 0x40000
	s_addc_u32 s19, s9, 0
	s_add_i32 s50, s48, 0x4000
	s_mov_b32 m0, s50
	s_add_i32 s51, s48, 0x6000
	global_load_lds_dwordx4 v178, s[18:19]
	s_mov_b32 m0, s51
	v_mov_b32_e32 v179, v165
	global_load_lds_dwordx4 v176, s[18:19]
	v_mov_b32_e32 v177, v165
	s_mov_b32 s52, 0
	v_lshl_add_u64 v[6:7], s[10:11], 0, v[164:165]
	v_lshl_add_u64 v[4:5], s[10:11], 0, v[166:167]
	v_lshl_add_u64 v[2:3], s[8:9], 0, v[178:179]
	s_cmp_lg_u32 s7, 1
	v_lshl_add_u64 v[0:1], s[8:9], 0, v[176:177]
	s_cbranch_scc1 .LBB0_835
	s_barrier
.LBB0_835:
	s_mov_b64 s[18:19], 0x80
	s_lshl_b32 s1, s12, 5
	s_add_i32 m0, s48, 0x18000
	v_lshl_add_u64 v[6:7], v[6:7], 0, s[18:19]
	s_and_b32 s53, s1, 0x60
	s_waitcnt vmcnt(4)
	s_barrier
	global_load_lds_dwordx4 v[6:7], off
	v_lshl_add_u64 v[4:5], v[4:5], 0, s[18:19]
	s_add_i32 m0, s48, 0x1a000
	s_add_i32 s54, s48, 0x8000
	s_add_i32 s55, s48, 0xa000
	global_load_lds_dwordx4 v[4:5], off
	v_lshl_add_u64 v[2:3], v[2:3], 0, s[18:19]
	s_mov_b32 m0, s54
	s_add_u32 s12, s10, 0x1600080
	global_load_lds_dwordx4 v[2:3], off
	v_lshl_add_u64 v[0:1], v[0:1], 0, s[18:19]
	s_mov_b32 m0, s55
	s_addc_u32 s13, s11, 0
	global_load_lds_dwordx4 v[0:1], off
	s_add_i32 m0, s48, 0x1c000
	v_lshl_add_u64 v[0:1], s[12:13], 0, v[164:165]
	global_load_lds_dwordx4 v[0:1], off
	v_lshl_add_u64 v[0:1], s[12:13], 0, v[166:167]
	s_add_i32 m0, s48, 0x1e000
	s_ashr_i32 s56, s94, 31
	global_load_lds_dwordx4 v[0:1], off
	s_lshl_b32 s58, s7, 7
	s_lshl_b32 s59, s7, 2
	s_add_u32 s20, s82, 0x2c000
	s_addc_u32 s21, s83, 0
	s_add_u32 s22, s82, 0x37000
	s_addc_u32 s23, s83, 0
	s_add_u32 s24, s82, 0x26800
	s_addc_u32 s25, s83, 0
	s_add_u32 s26, s82, 0x31800
	v_add3_u32 v0, v9, v221, v218
	s_addc_u32 s27, s83, 0
	v_lshl_or_b32 v0, v0, 12, v226
	s_sext_i32_i16 s1, s6
	v_lshl_or_b32 v2, s7, 13, v230
	s_add_u32 s28, s82, 0x3c800
	v_add_u32_e32 v0, v0, v224
	v_mov_b32_e32 v1, v165
	s_mov_b64 s[6:7], 0x40080
	s_addc_u32 s29, s83, 0
	v_add3_u32 v0, v8, v220, v218
	s_waitcnt vmcnt(6)
	s_add_u32 s30, s84, 0x10800
	v_lshl_or_b32 v0, v0, 12, v226
	s_addc_u32 s31, s85, 0
	v_add_u32_e32 v0, v0, v224
	s_add_i32 s60, 0, 0x10000
	s_add_i32 s61, 0, 0x14000
	s_mov_b32 s57, s94
	v_mov_b64_e32 v[184:185], 0xb00
	v_mov_b64_e32 v[186:187], 0xaff
	v_mov_b32_e32 v230, 0x3727c5ac
	s_mov_b32 s62, 0xb000
	s_movk_i32 s63, 0x2c00
	s_barrier
	s_branch .LBB0_837

.LBB0_840:
	ds_read_b128 v[76:79], v171
	v_xor_b32_e32 v91, 64, v171
	ds_read_b128 v[80:83], v91
	ds_read_b128 v[84:87], v171 offset:2048
	ds_read_b128 v[88:91], v91 offset:2048
	s_add_u32 s10, s8, 0x100
	s_addc_u32 s11, s9, 0
	s_cmp_eq_u32 s67, 28
	s_cselect_b32 s43, s33, s11
	s_cselect_b32 s42, s37, s10
	s_cselect_b32 s13, s35, s66
	s_cselect_b32 s12, s64, s65
	v_lshl_add_u64 v[108:109], s[8:9], 0, v[180:181]
	s_add_i32 m0, s48, 0xc000
	ds_read_b128 v[92:95], v173
	v_xor_b32_e32 v203, 64, v173
	ds_read_b128 v[96:99], v203
	ds_read_b128 v[100:103], v173 offset:2048
	ds_read_b128 v[104:107], v203 offset:2048
	ds_read_b128 v[188:191], v173 offset:4096
	ds_read_b128 v[192:195], v203 offset:4096
	ds_read_b128 v[196:199], v173 offset:6144
	ds_read_b128 v[200:203], v203 offset:6144
	global_load_lds_dwordx4 v[108:109], off
	v_lshl_add_u64 v[108:109], s[8:9], 0, v[182:183]
	s_add_i32 m0, s48, 0xe000
	s_nop 0
	global_load_lds_dwordx4 v[108:109], off
	s_waitcnt lgkmcnt(8)
	s_barrier
	s_waitcnt lgkmcnt(0)
	s_setprio 1
	s_waitcnt lgkmcnt(0)
	v_mfma_f32_16x16x32_bf16 v[158:161], v[76:79], v[92:95], v[158:161]
	v_mfma_f32_16x16x32_bf16 v[60:63], v[84:87], v[92:95], v[60:63]
	v_mfma_f32_16x16x32_bf16 v[150:153], v[76:79], v[100:103], v[150:153]
	v_mfma_f32_16x16x32_bf16 v[52:55], v[84:87], v[100:103], v[52:55]
	v_mfma_f32_16x16x32_bf16 v[146:149], v[76:79], v[188:191], v[146:149]
	v_mfma_f32_16x16x32_bf16 v[48:51], v[84:87], v[188:191], v[48:51]
	v_mfma_f32_16x16x32_bf16 v[138:141], v[76:79], v[196:199], v[138:141]
	v_mfma_f32_16x16x32_bf16 v[40:43], v[84:87], v[196:199], v[40:43]
	v_mfma_f32_16x16x32_bf16 v[158:161], v[80:83], v[96:99], v[158:161]
	v_mfma_f32_16x16x32_bf16 v[60:63], v[88:91], v[96:99], v[60:63]
	v_mfma_f32_16x16x32_bf16 v[150:153], v[80:83], v[104:107], v[150:153]
	v_mfma_f32_16x16x32_bf16 v[52:55], v[88:91], v[104:107], v[52:55]
	v_mfma_f32_16x16x32_bf16 v[146:149], v[80:83], v[192:195], v[146:149]
	v_mfma_f32_16x16x32_bf16 v[48:51], v[88:91], v[192:195], v[48:51]
	v_mfma_f32_16x16x32_bf16 v[138:141], v[80:83], v[200:203], v[138:141]
	v_mfma_f32_16x16x32_bf16 v[40:43], v[88:91], v[200:203], v[40:43]
	s_setprio 0
	s_barrier
	s_add_i32 s8, s60, s46
	v_lshl_add_u64 v[220:221], s[12:13], 0, v[164:165]
	s_mov_b32 m0, s8
	ds_read_b128 v[204:207], v175
	v_xor_b32_e32 v219, 64, v175
	ds_read_b128 v[208:211], v219
	ds_read_b128 v[212:215], v175 offset:2048
	ds_read_b128 v[216:219], v219 offset:2048
	global_load_lds_dwordx4 v[220:221], off
	v_lshl_add_u64 v[238:239], s[12:13], 0, v[166:167]
	s_add_i32 m0, s8, 0x2000
	s_nop 0
	global_load_lds_dwordx4 v[238:239], off
	s_barrier
	s_waitcnt lgkmcnt(0)
	s_setprio 1
	s_waitcnt lgkmcnt(0)
	v_mfma_f32_16x16x32_bf16 v[154:157], v[204:207], v[92:95], v[154:157]
	v_mfma_f32_16x16x32_bf16 v[56:59], v[212:215], v[92:95], v[56:59]
	v_mfma_f32_16x16x32_bf16 v[44:47], v[212:215], v[100:103], v[44:47]
	v_mfma_f32_16x16x32_bf16 v[36:39], v[212:215], v[188:191], v[36:39]
	v_mfma_f32_16x16x32_bf16 v[32:35], v[212:215], v[196:199], v[32:35]
	v_mfma_f32_16x16x32_bf16 v[154:157], v[208:211], v[96:99], v[154:157]
	v_mfma_f32_16x16x32_bf16 v[56:59], v[216:219], v[96:99], v[56:59]
	v_mfma_f32_16x16x32_bf16 v[92:95], v[204:207], v[100:103], v[142:145]
	v_mfma_f32_16x16x32_bf16 v[44:47], v[216:219], v[104:107], v[44:47]
	v_mfma_f32_16x16x32_bf16 v[96:99], v[204:207], v[188:191], v[134:137]
	v_mfma_f32_16x16x32_bf16 v[36:39], v[216:219], v[192:195], v[36:39]
	v_mfma_f32_16x16x32_bf16 v[100:103], v[204:207], v[196:199], v[130:133]
	v_mfma_f32_16x16x32_bf16 v[32:35], v[216:219], v[200:203], v[32:35]
	v_mfma_f32_16x16x32_bf16 v[92:95], v[208:211], v[104:107], v[92:95]
	v_mfma_f32_16x16x32_bf16 v[96:99], v[208:211], v[192:195], v[96:99]
	v_mfma_f32_16x16x32_bf16 v[100:103], v[208:211], v[200:203], v[100:103]
	s_setprio 0
	s_mov_b32 m0, s48
	v_lshl_add_u64 v[240:241], s[42:43], 0, v[178:179]
	s_barrier
	ds_read_b128 v[104:107], v173 offset:16384
	v_xor_b32_e32 v203, 64, v173
	ds_read_b128 v[130:133], v203 offset:16384
	ds_read_b128 v[134:137], v173 offset:18432
	ds_read_b128 v[142:145], v203 offset:18432
	ds_read_b128 v[188:191], v173 offset:20480
	ds_read_b128 v[192:195], v203 offset:20480
	ds_read_b128 v[196:199], v173 offset:22528
	ds_read_b128 v[200:203], v203 offset:22528
	global_load_lds_dwordx4 v[240:241], off
	v_lshl_add_u64 v[242:243], s[42:43], 0, v[176:177]
	s_mov_b32 m0, s49
	s_nop 0
	global_load_lds_dwordx4 v[242:243], off
	s_barrier
	s_waitcnt lgkmcnt(0)
	s_setprio 1
	s_waitcnt lgkmcnt(0)
	v_mfma_f32_16x16x32_bf16 v[126:129], v[76:79], v[104:107], v[126:129]
	v_mfma_f32_16x16x32_bf16 v[28:31], v[84:87], v[104:107], v[28:31]
	v_mfma_f32_16x16x32_bf16 v[122:125], v[76:79], v[134:137], v[122:125]
	v_mfma_f32_16x16x32_bf16 v[24:27], v[84:87], v[134:137], v[24:27]
	v_mfma_f32_16x16x32_bf16 v[114:117], v[76:79], v[188:191], v[114:117]
	v_mfma_f32_16x16x32_bf16 v[20:23], v[84:87], v[188:191], v[20:23]
	v_mfma_f32_16x16x32_bf16 v[72:75], v[76:79], v[196:199], v[72:75]
	v_mfma_f32_16x16x32_bf16 v[4:7], v[84:87], v[196:199], v[4:7]
	v_mfma_f32_16x16x32_bf16 v[126:129], v[80:83], v[130:133], v[126:129]
	v_mfma_f32_16x16x32_bf16 v[28:31], v[88:91], v[130:133], v[28:31]
	v_mfma_f32_16x16x32_bf16 v[122:125], v[80:83], v[142:145], v[122:125]
	v_mfma_f32_16x16x32_bf16 v[24:27], v[88:91], v[142:145], v[24:27]
	v_mfma_f32_16x16x32_bf16 v[114:117], v[80:83], v[192:195], v[114:117]
	v_mfma_f32_16x16x32_bf16 v[20:23], v[88:91], v[192:195], v[20:23]
	v_mfma_f32_16x16x32_bf16 v[72:75], v[80:83], v[200:203], v[72:75]
	v_mfma_f32_16x16x32_bf16 v[4:7], v[88:91], v[200:203], v[4:7]
	s_setprio 0
	s_barrier
	s_add_u32 s8, s12, 0x1600000
	s_addc_u32 s9, s13, 0
	s_add_i32 s68, s61, s46
	v_lshl_add_u64 v[76:77], s[8:9], 0, v[164:165]
	s_mov_b32 m0, s68
	s_nop 0
	global_load_lds_dwordx4 v[76:77], off
	v_lshl_add_u64 v[76:77], s[8:9], 0, v[166:167]
	s_add_i32 m0, s68, 0x2000
	s_nop 0
	global_load_lds_dwordx4 v[76:77], off
	s_waitcnt vmcnt(6)
	s_barrier
	s_setprio 1
	v_mfma_f32_16x16x32_bf16 v[16:19], v[212:215], v[104:107], v[16:19]
	v_mfma_f32_16x16x32_bf16 v[12:15], v[212:215], v[134:137], v[12:15]
	v_mfma_f32_16x16x32_bf16 v[68:71], v[204:207], v[188:191], v[68:71]
	v_mfma_f32_16x16x32_bf16 v[8:11], v[212:215], v[188:191], v[8:11]
	v_mfma_f32_16x16x32_bf16 v[64:67], v[204:207], v[196:199], v[64:67]
	v_mfma_f32_16x16x32_bf16 v[0:3], v[212:215], v[196:199], v[0:3]
	v_mfma_f32_16x16x32_bf16 v[76:79], v[204:207], v[104:107], v[118:121]
	v_mfma_f32_16x16x32_bf16 v[16:19], v[216:219], v[130:133], v[16:19]
	v_mfma_f32_16x16x32_bf16 v[80:83], v[204:207], v[134:137], v[110:113]
	v_mfma_f32_16x16x32_bf16 v[12:15], v[216:219], v[142:145], v[12:15]
	v_mfma_f32_16x16x32_bf16 v[68:71], v[208:211], v[192:195], v[68:71]
	v_mfma_f32_16x16x32_bf16 v[8:11], v[216:219], v[192:195], v[8:11]
	v_mfma_f32_16x16x32_bf16 v[64:67], v[208:211], v[200:203], v[64:67]
	v_mfma_f32_16x16x32_bf16 v[0:3], v[216:219], v[200:203], v[0:3]
	v_mfma_f32_16x16x32_bf16 v[76:79], v[208:211], v[130:133], v[76:79]
	v_mfma_f32_16x16x32_bf16 v[80:83], v[208:211], v[142:145], v[80:83]
	s_setprio 0
	s_add_i32 s68, 0, 0x18000
	v_add_u32_e32 v108, s68, v169
	s_barrier
	ds_read_b128 v[84:87], v108
	v_xor_b32_e32 v111, 64, v108
	ds_read_b128 v[88:91], v111
	ds_read_b128 v[104:107], v108 offset:2048
	ds_read_b128 v[108:111], v111 offset:2048
	s_add_u32 s8, s42, 0x40000
	s_addc_u32 s9, s43, 0
	s_mov_b32 m0, s50
	v_lshl_add_u64 v[112:113], s[8:9], 0, v[178:179]
	ds_read_b128 v[118:121], v173 offset:32768
	v_xor_b32_e32 v207, 64, v173
	ds_read_b128 v[130:133], v207 offset:32768
	ds_read_b128 v[134:137], v173 offset:34816
	ds_read_b128 v[188:191], v207 offset:34816
	ds_read_b128 v[192:195], v173 offset:36864
	ds_read_b128 v[196:199], v207 offset:36864
	ds_read_b128 v[200:203], v173 offset:38912
	ds_read_b128 v[204:207], v207 offset:38912
	global_load_lds_dwordx4 v[112:113], off
	v_lshl_add_u64 v[112:113], s[8:9], 0, v[176:177]
	s_mov_b32 m0, s51
	s_nop 0
	global_load_lds_dwordx4 v[112:113], off
	s_waitcnt lgkmcnt(8)
	s_barrier
	s_waitcnt lgkmcnt(0)
	s_setprio 1
	s_waitcnt lgkmcnt(0)
	v_mfma_f32_16x16x32_bf16 v[142:145], v[84:87], v[118:121], v[158:161]
	v_mfma_f32_16x16x32_bf16 v[158:161], v[88:91], v[130:133], v[142:145]
	v_mfma_f32_16x16x32_bf16 v[142:145], v[84:87], v[134:137], v[150:153]
	v_mfma_f32_16x16x32_bf16 v[60:63], v[104:107], v[118:121], v[60:63]
	v_mfma_f32_16x16x32_bf16 v[150:153], v[88:91], v[188:191], v[142:145]
	v_mfma_f32_16x16x32_bf16 v[52:55], v[104:107], v[134:137], v[52:55]
	v_mfma_f32_16x16x32_bf16 v[142:145], v[84:87], v[192:195], v[146:149]
	v_mfma_f32_16x16x32_bf16 v[48:51], v[104:107], v[192:195], v[48:51]
	v_mfma_f32_16x16x32_bf16 v[138:141], v[84:87], v[200:203], v[138:141]
	v_mfma_f32_16x16x32_bf16 v[40:43], v[104:107], v[200:203], v[40:43]
	v_mfma_f32_16x16x32_bf16 v[60:63], v[108:111], v[130:133], v[60:63]
	v_mfma_f32_16x16x32_bf16 v[52:55], v[108:111], v[188:191], v[52:55]
	v_mfma_f32_16x16x32_bf16 v[146:149], v[88:91], v[196:199], v[142:145]
	v_mfma_f32_16x16x32_bf16 v[48:51], v[108:111], v[196:199], v[48:51]
	v_mfma_f32_16x16x32_bf16 v[138:141], v[88:91], v[204:207], v[138:141]
	v_mfma_f32_16x16x32_bf16 v[40:43], v[108:111], v[204:207], v[40:43]
	s_setprio 0
	s_barrier
	s_add_i32 s42, 0, 0x1c000
	v_add_u32_e32 v112, s42, v169
	s_add_i32 s8, s68, s46
	ds_read_b128 v[208:211], v112
	v_xor_b32_e32 v237, 64, v112
	ds_read_b128 v[212:215], v237
	ds_read_b128 v[216:219], v112 offset:2048
	ds_read_b128 v[234:237], v237 offset:2048
	v_lshl_add_u64 v[112:113], v[220:221], 0, s[18:19]
	s_mov_b32 m0, s8
	s_nop 0
	global_load_lds_dwordx4 v[112:113], off
	v_lshl_add_u64 v[112:113], v[238:239], 0, s[18:19]
	s_add_i32 m0, s8, 0x2000
	s_nop 0
	global_load_lds_dwordx4 v[112:113], off
	s_barrier
	s_waitcnt lgkmcnt(0)
	s_setprio 1
	s_waitcnt lgkmcnt(0)
	v_mfma_f32_16x16x32_bf16 v[142:145], v[208:211], v[118:121], v[154:157]
	v_mfma_f32_16x16x32_bf16 v[92:95], v[208:211], v[134:137], v[92:95]
	v_mfma_f32_16x16x32_bf16 v[154:157], v[212:215], v[130:133], v[142:145]
	v_mfma_f32_16x16x32_bf16 v[142:145], v[212:215], v[188:191], v[92:95]
	v_mfma_f32_16x16x32_bf16 v[92:95], v[208:211], v[192:195], v[96:99]
	v_mfma_f32_16x16x32_bf16 v[56:59], v[216:219], v[118:121], v[56:59]
	v_mfma_f32_16x16x32_bf16 v[44:47], v[216:219], v[134:137], v[44:47]
	v_mfma_f32_16x16x32_bf16 v[134:137], v[212:215], v[196:199], v[92:95]
	v_mfma_f32_16x16x32_bf16 v[36:39], v[216:219], v[192:195], v[36:39]
	v_mfma_f32_16x16x32_bf16 v[92:95], v[208:211], v[200:203], v[100:103]
	v_mfma_f32_16x16x32_bf16 v[32:35], v[216:219], v[200:203], v[32:35]
	v_mfma_f32_16x16x32_bf16 v[56:59], v[234:237], v[130:133], v[56:59]
	v_mfma_f32_16x16x32_bf16 v[44:47], v[234:237], v[188:191], v[44:47]
	v_mfma_f32_16x16x32_bf16 v[36:39], v[234:237], v[196:199], v[36:39]
	v_mfma_f32_16x16x32_bf16 v[130:133], v[212:215], v[204:207], v[92:95]
	v_mfma_f32_16x16x32_bf16 v[32:35], v[234:237], v[204:207], v[32:35]
	s_setprio 0
	s_mov_b32 m0, s54
	v_lshl_add_u64 v[112:113], v[240:241], 0, s[18:19]
	s_barrier
	ds_read_b128 v[92:95], v173 offset:49152
	v_xor_b32_e32 v207, 64, v173
	ds_read_b128 v[96:99], v207 offset:49152
	ds_read_b128 v[100:103], v173 offset:51200
	ds_read_b128 v[188:191], v207 offset:51200
	ds_read_b128 v[192:195], v173 offset:53248
	ds_read_b128 v[196:199], v207 offset:53248
	ds_read_b128 v[200:203], v173 offset:55296
	ds_read_b128 v[204:207], v207 offset:55296
	global_load_lds_dwordx4 v[112:113], off
	v_lshl_add_u64 v[112:113], v[242:243], 0, s[18:19]
	s_mov_b32 m0, s55
	s_nop 0
	global_load_lds_dwordx4 v[112:113], off
	s_barrier
	s_waitcnt lgkmcnt(0)
	s_setprio 1
	s_waitcnt lgkmcnt(0)
	v_mfma_f32_16x16x32_bf16 v[118:121], v[84:87], v[92:95], v[126:129]
	v_mfma_f32_16x16x32_bf16 v[126:129], v[88:91], v[96:99], v[118:121]
	v_mfma_f32_16x16x32_bf16 v[28:31], v[104:107], v[92:95], v[28:31]
	v_mfma_f32_16x16x32_bf16 v[118:121], v[84:87], v[100:103], v[122:125]
	v_mfma_f32_16x16x32_bf16 v[24:27], v[104:107], v[100:103], v[24:27]
	v_mfma_f32_16x16x32_bf16 v[112:115], v[84:87], v[192:195], v[114:117]
	v_mfma_f32_16x16x32_bf16 v[20:23], v[104:107], v[192:195], v[20:23]
	v_mfma_f32_16x16x32_bf16 v[72:75], v[84:87], v[200:203], v[72:75]
	v_mfma_f32_16x16x32_bf16 v[4:7], v[104:107], v[200:203], v[4:7]
	v_mfma_f32_16x16x32_bf16 v[28:31], v[108:111], v[96:99], v[28:31]
	v_mfma_f32_16x16x32_bf16 v[122:125], v[88:91], v[188:191], v[118:121]
	v_mfma_f32_16x16x32_bf16 v[24:27], v[108:111], v[188:191], v[24:27]
	v_mfma_f32_16x16x32_bf16 v[114:117], v[88:91], v[196:199], v[112:115]
	v_mfma_f32_16x16x32_bf16 v[20:23], v[108:111], v[196:199], v[20:23]
	v_mfma_f32_16x16x32_bf16 v[72:75], v[88:91], v[204:207], v[72:75]
	v_mfma_f32_16x16x32_bf16 v[4:7], v[108:111], v[204:207], v[4:7]
	s_setprio 0
	s_barrier
	s_add_u32 s8, s12, 0x1600080
	s_addc_u32 s9, s13, 0
	s_add_i32 s12, s42, s46
	v_lshl_add_u64 v[84:85], s[8:9], 0, v[164:165]
	s_mov_b32 m0, s12
	s_nop 0
	global_load_lds_dwordx4 v[84:85], off
	v_lshl_add_u64 v[84:85], s[8:9], 0, v[166:167]
	s_add_i32 m0, s12, 0x2000
	s_nop 0
	global_load_lds_dwordx4 v[84:85], off
	s_waitcnt vmcnt(6)
	s_barrier
	s_setprio 1
	v_mfma_f32_16x16x32_bf16 v[76:79], v[208:211], v[92:95], v[76:79]
	v_mfma_f32_16x16x32_bf16 v[118:121], v[212:215], v[96:99], v[76:79]
	v_mfma_f32_16x16x32_bf16 v[16:19], v[216:219], v[92:95], v[16:19]
	v_mfma_f32_16x16x32_bf16 v[76:79], v[208:211], v[100:103], v[80:83]
	v_mfma_f32_16x16x32_bf16 v[12:15], v[216:219], v[100:103], v[12:15]
	v_mfma_f32_16x16x32_bf16 v[68:71], v[208:211], v[192:195], v[68:71]
	v_mfma_f32_16x16x32_bf16 v[8:11], v[216:219], v[192:195], v[8:11]
	v_mfma_f32_16x16x32_bf16 v[64:67], v[208:211], v[200:203], v[64:67]
	v_mfma_f32_16x16x32_bf16 v[0:3], v[216:219], v[200:203], v[0:3]
	v_mfma_f32_16x16x32_bf16 v[16:19], v[234:237], v[96:99], v[16:19]
	v_mfma_f32_16x16x32_bf16 v[110:113], v[212:215], v[188:191], v[76:79]
	v_mfma_f32_16x16x32_bf16 v[12:15], v[234:237], v[188:191], v[12:15]
	v_mfma_f32_16x16x32_bf16 v[68:71], v[212:215], v[196:199], v[68:71]
	v_mfma_f32_16x16x32_bf16 v[8:11], v[234:237], v[196:199], v[8:11]
	v_mfma_f32_16x16x32_bf16 v[64:67], v[212:215], v[204:207], v[64:67]
	v_mfma_f32_16x16x32_bf16 v[0:3], v[234:237], v[204:207], v[0:3]
	s_setprio 0
	s_add_i32 s67, s67, 2
	s_add_u32 s65, s65, 0x100
	s_addc_u32 s66, s66, 0
	s_cmp_gt_u32 s67, 29
	s_mov_b64 s[8:9], s[10:11]
	s_barrier
	s_cbranch_scc0 .LBB0_840
	s_lshl_b32 s8, s0, 8
	s_lshl_b32 s1, s1, 7
	v_mov_b32_e32 v80, v225
	v_mov_b32_e32 v193, v163
	s_add_i32 s8, s8, s58
	s_or_b32 s1, s1, s53
	s_lshl_b32 s0, s0, 3
	v_add_u32_e32 v190, s8, v193
	v_lshl_add_u32 v188, v80, 3, s1
	v_ashrrev_i32_e32 v191, 31, v190
	v_ashrrev_i32_e32 v189, 31, v188
	v_lshl_add_u64 v[78:79], v[190:191], 2, s[4:5]
	v_lshlrev_b64 v[90:91], 2, v[188:189]
	global_load_dword v196, v[78:79], off
	global_load_dword v192, v[78:79], off offset:64
	global_load_dword v194, v[78:79], off offset:128
	global_load_dword v200, v[78:79], off offset:192
	global_load_dword v199, v[78:79], off offset:256
	global_load_dword v77, v[78:79], off offset:320
	global_load_dword v76, v[78:79], off offset:384
	global_load_dword v191, v[78:79], off offset:448
	v_lshl_add_u64 v[78:79], s[14:15], 0, v[90:91]
	v_lshl_add_u64 v[80:81], s[20:21], 0, v[90:91]
	global_load_dwordx4 v[102:105], v[78:79], off
	global_load_dwordx4 v[94:97], v[80:81], off
	v_lshl_add_u64 v[78:79], s[22:23], 0, v[90:91]
	global_load_dwordx4 v[98:101], v[78:79], off
	v_lshl_add_u64 v[78:79], s[16:17], 0, v[90:91]
	global_load_dwordx4 v[106:109], v[78:79], off
	v_lshl_add_u64 v[78:79], s[24:25], 0, v[90:91]
	v_lshl_add_u64 v[80:81], s[26:27], 0, v[90:91]
	v_lshl_add_u64 v[82:83], s[28:29], 0, v[90:91]
	v_lshl_add_u64 v[90:91], s[30:31], 0, v[90:91]
	global_load_dwordx4 v[86:89], v[78:79], off
	s_nop 0
	global_load_dwordx4 v[78:81], v[80:81], off
	s_add_i32 s0, s0, s59
	global_load_dwordx4 v[82:85], v[82:83], off
	v_add_u32_e32 v195, s0, v193
	global_load_dwordx4 v[90:93], v[90:91], off
	v_cmp_gt_i32_e64 s[12:13], 2, v193
	s_waitcnt vmcnt(0)
	v_fmamk_f32 v196, v196, 0x3a000000, v230
	v_rsq_f32_e32 v198, v196
	v_mad_i64_i32 v[196:197], s[0:1], v195, s62, 0
	v_lshl_add_u64 v[196:197], s[70:71], 0, v[196:197]
	v_pk_mul_f32 v[160:161], v[160:161], v[198:199] op_sel_hi:[1,0]
	v_pk_mul_f32 v[158:159], v[158:159], v[198:199] op_sel_hi:[1,0]
	v_pk_mul_f32 v[156:157], v[156:157], v[198:199] op_sel_hi:[1,0]
	v_pk_mul_f32 v[154:155], v[154:155], v[198:199] op_sel_hi:[1,0]
	v_lshl_add_u64 v[196:197], v[188:189], 2, v[196:197]
	s_and_saveexec_b64 s[0:1], s[12:13]
	s_cbranch_execz .LBB0_843
	v_add_co_u32_e32 v202, vcc, 0x5000, v196
	global_store_dwordx4 v[196:197], v[158:161], off
	s_nop 0
	v_addc_co_u32_e32 v203, vcc, 0, v197, vcc
	global_store_dwordx4 v[202:203], v[154:157], off offset:2048

.LBB0_969:
	v_readlane_b32 s0, v255, 8
	v_readlane_b32 s1, v255, 9
	s_and_b64 vcc, exec, s[0:1]
	s_cbranch_vccnz .LBB0_1005
	s_add_u32 s18, s92, 0xa700000
	s_addc_u32 s19, s93, 0
	s_lshr_b32 s4, s3, 6
	s_lshr_b32 s5, s3, 8
	s_lshl_b32 s20, s4, 10
	s_mul_i32 s7, s37, 0x2c0000
	s_mul_hi_i32 s6, s37, 0x2c0000
	s_add_u32 s14, s18, s7
	s_addc_u32 s15, s19, s6
	s_add_i32 s21, s20, 0
	s_add_i32 m0, s21, 0x10000
	s_mul_i32 s0, s38, 0x2c0000
	v_and_b32_e32 v136, 63, v222
	v_lshrrev_b32_e32 v137, 3, v136
	v_lshrrev_b32_e32 v138, 6, v222
	v_lshl_add_u32 v139, v138, 3, v137
	v_and_b32_e32 v146, 7, v136
	v_and_b32_e32 v147, 6, v137
	v_xor_b32_e32 v146, v146, v147
	v_lshlrev_b32_e32 v146, 4, v146
	v_mul_u32_u24_e32 v147, 0x2c00, v139
	v_add_u32_e32 v147, v147, v146
	v_mov_b32_e32 v128, v147
	v_add_u32_e32 v130, 0xb0000, v147
	v_mov_b32_e32 v168, v147
	v_add_u32_e32 v172, 0xb0000, v147
	v_add_u32_e32 v130, 0xb0000, v147
	v_add_u32_e32 v172, 0xb0000, v147
	v_and_b32_e32 v147, 31, v139
	v_and_b32_e32 v148, 12, v147
	v_lshlrev_b32_e32 v148, 1, v148
	v_lshrrev_b32_e32 v149, 4, v147
	v_lshlrev_b32_e32 v149, 2, v149
	v_and_b32_e32 v147, 3, v147
	v_or3_b32 v147, v148, v149, v147
	v_and_b32_e32 v148, 0x60, v139
	v_add_u32_e32 v147, v147, v148
	v_mul_u32_u24_e32 v147, 0x2c00, v147
	v_add_u32_e32 v147, v147, v146
	v_mov_b32_e32 v170, v147
	v_add_u32_e32 v174, 0xb0000, v147
	v_add_u32_e32 v174, 0xb0000, v147
	v_and_b32_e32 v147, 15, v136
	v_lshrrev_b32_e32 v148, 4, v136
	v_and_b32_e32 v149, 6, v147
	v_xor_b32_e32 v148, v148, v149
	v_lshlrev_b32_e32 v148, 4, v148
	v_lshl_or_b32 v148, v147, 7, v148
	v_lshrrev_b32_e32 v149, 2, v138
	v_lshl_add_u32 v149, v149, 13, v148
	v_add_u32_e32 v142, 0x0, v149
	v_and_b32_e32 v147, 3, v138
	v_lshl_add_u32 v147, v147, 12, v148
	v_add_u32_e32 v140, 0x0, v147
	v_add_u32_e32 v141, 0x10000, v147
	v_add_u32_e32 v143, 0x14000, v147
	v_add_u32_e32 v145, 0x10000, v147
	global_load_lds_dwordx4 v170, s[14:15]
	s_add_i32 m0, s21, 0x12000
	s_mul_hi_i32 s1, s38, 0x2c0000
	s_add_u32 s0, s96, s0
	global_load_lds_dwordx4 v174, s[14:15]
	s_addc_u32 s1, s97, s1
	s_mov_b32 m0, s21
	s_add_i32 s22, s21, 0x2000
	global_load_lds_dwordx4 v168, s[0:1]
	s_mov_b32 m0, s22
	s_add_u32 s6, s14, 0x160000
	global_load_lds_dwordx4 v172, s[0:1]
	s_addc_u32 s7, s15, 0
	s_add_i32 m0, s21, 0x14000
	v_mov_b32_e32 v171, 0
	global_load_lds_dwordx4 v170, s[6:7]
	s_add_i32 m0, s21, 0x16000
	v_mov_b32_e32 v175, v171
	global_load_lds_dwordx4 v174, s[6:7]
	s_add_u32 s6, s0, 0x160000
	s_addc_u32 s7, s1, 0
	s_add_i32 s23, s21, 0x4000
	s_mov_b32 m0, s23
	s_add_i32 s24, s21, 0x6000
	global_load_lds_dwordx4 v168, s[6:7]
	s_mov_b32 m0, s24
	v_mov_b32_e32 v169, v171
	global_load_lds_dwordx4 v172, s[6:7]
	v_mov_b32_e32 v173, v171
	s_mov_b32 s25, 0
	v_lshl_add_u64 v[6:7], s[14:15], 0, v[170:171]
	v_lshl_add_u64 v[4:5], s[14:15], 0, v[174:175]
	v_lshl_add_u64 v[2:3], s[0:1], 0, v[168:169]
	s_cmp_lg_u32 s5, 1
	v_lshl_add_u64 v[0:1], s[0:1], 0, v[172:173]
	s_cbranch_scc1 .LBB0_972
	s_barrier
.LBB0_972:
	s_lshl_b32 s4, s4, 5
	s_lshl_b32 s26, s5, 6
	s_lshl_b32 s6, s5, 13
	s_and_b32 s27, s4, 0x60
	s_add_u32 s10, s92, 0x50000
	s_mov_b64 s[12:13], 0x80
	s_addc_u32 s11, s93, 0
	s_add_i32 m0, s21, 0x18000
	v_lshl_add_u64 v[6:7], v[6:7], 0, s[12:13]
	s_waitcnt vmcnt(4)
	s_barrier
	global_load_lds_dwordx4 v[6:7], off
	v_lshl_add_u64 v[4:5], v[4:5], 0, s[12:13]
	s_add_i32 m0, s21, 0x1a000
	s_add_i32 s28, s21, 0x8000
	s_add_i32 s29, s21, 0xa000
	global_load_lds_dwordx4 v[4:5], off
	v_lshl_add_u64 v[2:3], v[2:3], 0, s[12:13]
	s_mov_b32 m0, s28
	s_add_u32 s4, s14, 0x160080
	global_load_lds_dwordx4 v[2:3], off
	v_lshl_add_u64 v[0:1], v[0:1], 0, s[12:13]
	s_mov_b32 m0, s29
	s_addc_u32 s5, s15, 0
	global_load_lds_dwordx4 v[0:1], off
	s_add_i32 m0, s21, 0x1c000
	v_lshl_add_u64 v[0:1], s[4:5], 0, v[170:171]
	global_load_lds_dwordx4 v[0:1], off
	v_lshl_add_u64 v[0:1], s[4:5], 0, v[174:175]
	s_add_i32 m0, s21, 0x1e000
	global_load_lds_dwordx4 v[0:1], off
	v_lshlrev_b32_e32 v1, 2, v163
	v_lshl_or_b32 v0, v163, 6, v227
	v_and_b32_e32 v1, 32, v1
	v_bitop3_b32 v0, v0, s6, v1 bitop3:0xde
	s_waitcnt vmcnt(6)
	v_add_u16_e32 v1, v226, v224
	v_lshrrev_b16_e32 v1, 1, v1
	s_add_i32 s33, 0, 0x10000
	s_add_i32 s34, 0, 0x14000
	v_mbcnt_lo_u32_b32 v0, -1, 0
	s_ashr_i32 s30, s94, 31
	s_mov_b32 s31, s94
	v_mov_b32_e32 v129, v171
	v_mov_b32_e32 v131, v171
	v_mov_b64_e32 v[132:133], 0x200
	v_mov_b64_e32 v[134:135], 0x1ff
	v_mbcnt_hi_u32_b32 v144, -1, v0
	s_barrier
	s_branch .LBB0_974

.LBB0_985:
	ds_read_b128 v[136:139], v141
	v_xor_b32_e32 v157, 64, v141
	ds_read_b128 v[146:149], v157
	ds_read_b128 v[150:153], v141 offset:2048
	ds_read_b128 v[154:157], v157 offset:2048
	s_add_u32 s14, s0, 0xffea0080
	s_addc_u32 s15, s1, -1
	s_cmpk_eq_i32 s41, 0x54
	s_cselect_b32 s17, s5, s15
	s_cselect_b32 s16, s4, s14
	s_cselect_b32 s15, s7, s40
	s_cselect_b32 s14, s6, s39
	v_lshl_add_u64 v[200:201], s[0:1], 0, v[128:129]
	s_add_i32 m0, s21, 0xc000
	ds_read_b128 v[158:161], v142
	v_xor_b32_e32 v199, 64, v142
	ds_read_b128 v[164:167], v199
	ds_read_b128 v[176:179], v142 offset:2048
	ds_read_b128 v[180:183], v199 offset:2048
	ds_read_b128 v[184:187], v142 offset:4096
	ds_read_b128 v[188:191], v199 offset:4096
	ds_read_b128 v[192:195], v142 offset:6144
	ds_read_b128 v[196:199], v199 offset:6144
	global_load_lds_dwordx4 v[200:201], off
	v_lshl_add_u64 v[200:201], s[0:1], 0, v[130:131]
	s_add_i32 m0, s21, 0xe000
	s_nop 0
	global_load_lds_dwordx4 v[200:201], off
	s_waitcnt lgkmcnt(8)
	s_barrier
	s_waitcnt lgkmcnt(0)
	s_setprio 1
	s_waitcnt lgkmcnt(0)
	v_mfma_f32_16x16x32_bf16 v[124:127], v[136:139], v[158:161], v[124:127]
	v_mfma_f32_16x16x32_bf16 v[120:123], v[150:153], v[158:161], v[120:123]
	v_mfma_f32_16x16x32_bf16 v[108:111], v[136:139], v[176:179], v[108:111]
	v_mfma_f32_16x16x32_bf16 v[104:107], v[150:153], v[176:179], v[104:107]
	v_mfma_f32_16x16x32_bf16 v[92:95], v[136:139], v[184:187], v[92:95]
	v_mfma_f32_16x16x32_bf16 v[88:91], v[150:153], v[184:187], v[88:91]
	v_mfma_f32_16x16x32_bf16 v[76:79], v[136:139], v[192:195], v[76:79]
	v_mfma_f32_16x16x32_bf16 v[72:75], v[150:153], v[192:195], v[72:75]
	v_mfma_f32_16x16x32_bf16 v[124:127], v[146:149], v[164:167], v[124:127]
	v_mfma_f32_16x16x32_bf16 v[120:123], v[154:157], v[164:167], v[120:123]
	v_mfma_f32_16x16x32_bf16 v[108:111], v[146:149], v[180:183], v[108:111]
	v_mfma_f32_16x16x32_bf16 v[104:107], v[154:157], v[180:183], v[104:107]
	v_mfma_f32_16x16x32_bf16 v[92:95], v[146:149], v[188:191], v[92:95]
	v_mfma_f32_16x16x32_bf16 v[88:91], v[154:157], v[188:191], v[88:91]
	v_mfma_f32_16x16x32_bf16 v[76:79], v[146:149], v[196:199], v[76:79]
	v_mfma_f32_16x16x32_bf16 v[72:75], v[154:157], v[196:199], v[72:75]
	s_setprio 0
	s_barrier
	s_add_i32 s42, s33, s20
	v_lshl_add_u64 v[216:217], s[14:15], 0, v[170:171]
	s_mov_b32 m0, s42
	ds_read_b128 v[200:203], v143
	v_xor_b32_e32 v215, 64, v143
	ds_read_b128 v[204:207], v215
	ds_read_b128 v[208:211], v143 offset:2048
	ds_read_b128 v[212:215], v215 offset:2048
	global_load_lds_dwordx4 v[216:217], off
	v_lshl_add_u64 v[218:219], s[14:15], 0, v[174:175]
	s_add_i32 m0, s42, 0x2000
	s_nop 0
	global_load_lds_dwordx4 v[218:219], off
	s_barrier
	s_waitcnt lgkmcnt(0)
	s_setprio 1
	s_waitcnt lgkmcnt(0)
	v_mfma_f32_16x16x32_bf16 v[116:119], v[200:203], v[158:161], v[116:119]
	v_mfma_f32_16x16x32_bf16 v[112:115], v[208:211], v[158:161], v[112:115]
	v_mfma_f32_16x16x32_bf16 v[100:103], v[200:203], v[176:179], v[100:103]
	v_mfma_f32_16x16x32_bf16 v[96:99], v[208:211], v[176:179], v[96:99]
	v_mfma_f32_16x16x32_bf16 v[84:87], v[200:203], v[184:187], v[84:87]
	v_mfma_f32_16x16x32_bf16 v[80:83], v[208:211], v[184:187], v[80:83]
	v_mfma_f32_16x16x32_bf16 v[68:71], v[200:203], v[192:195], v[68:71]
	v_mfma_f32_16x16x32_bf16 v[64:67], v[208:211], v[192:195], v[64:67]
	v_mfma_f32_16x16x32_bf16 v[116:119], v[204:207], v[164:167], v[116:119]
	v_mfma_f32_16x16x32_bf16 v[112:115], v[212:215], v[164:167], v[112:115]
	v_mfma_f32_16x16x32_bf16 v[100:103], v[204:207], v[180:183], v[100:103]
	v_mfma_f32_16x16x32_bf16 v[96:99], v[212:215], v[180:183], v[96:99]
	v_mfma_f32_16x16x32_bf16 v[84:87], v[204:207], v[188:191], v[84:87]
	v_mfma_f32_16x16x32_bf16 v[80:83], v[212:215], v[188:191], v[80:83]
	v_mfma_f32_16x16x32_bf16 v[68:71], v[204:207], v[196:199], v[68:71]
	v_mfma_f32_16x16x32_bf16 v[64:67], v[212:215], v[196:199], v[64:67]
	s_setprio 0
	s_mov_b32 m0, s21
	v_lshl_add_u64 v[220:221], s[16:17], 0, v[168:169]
	s_barrier
	ds_read_b128 v[158:161], v142 offset:16384
	v_xor_b32_e32 v199, 64, v142
	ds_read_b128 v[164:167], v199 offset:16384
	ds_read_b128 v[176:179], v142 offset:18432
	ds_read_b128 v[180:183], v199 offset:18432
	ds_read_b128 v[184:187], v142 offset:20480
	ds_read_b128 v[188:191], v199 offset:20480
	ds_read_b128 v[192:195], v142 offset:22528
	ds_read_b128 v[196:199], v199 offset:22528
	global_load_lds_dwordx4 v[220:221], off
	v_lshl_add_u64 v[222:223], s[16:17], 0, v[172:173]
	s_mov_b32 m0, s22
	s_nop 0
	global_load_lds_dwordx4 v[222:223], off
	s_barrier
	s_waitcnt lgkmcnt(0)
	s_setprio 1
	s_waitcnt lgkmcnt(0)
	v_mfma_f32_16x16x32_bf16 v[60:63], v[136:139], v[158:161], v[60:63]
	v_mfma_f32_16x16x32_bf16 v[56:59], v[150:153], v[158:161], v[56:59]
	v_mfma_f32_16x16x32_bf16 v[44:47], v[136:139], v[176:179], v[44:47]
	v_mfma_f32_16x16x32_bf16 v[40:43], v[150:153], v[176:179], v[40:43]
	v_mfma_f32_16x16x32_bf16 v[28:31], v[136:139], v[184:187], v[28:31]
	v_mfma_f32_16x16x32_bf16 v[24:27], v[150:153], v[184:187], v[24:27]
	v_mfma_f32_16x16x32_bf16 v[12:15], v[136:139], v[192:195], v[12:15]
	v_mfma_f32_16x16x32_bf16 v[8:11], v[150:153], v[192:195], v[8:11]
	v_mfma_f32_16x16x32_bf16 v[60:63], v[146:149], v[164:167], v[60:63]
	v_mfma_f32_16x16x32_bf16 v[56:59], v[154:157], v[164:167], v[56:59]
	v_mfma_f32_16x16x32_bf16 v[44:47], v[146:149], v[180:183], v[44:47]
	v_mfma_f32_16x16x32_bf16 v[40:43], v[154:157], v[180:183], v[40:43]
	v_mfma_f32_16x16x32_bf16 v[28:31], v[146:149], v[188:191], v[28:31]
	v_mfma_f32_16x16x32_bf16 v[24:27], v[154:157], v[188:191], v[24:27]
	v_mfma_f32_16x16x32_bf16 v[12:15], v[146:149], v[196:199], v[12:15]
	v_mfma_f32_16x16x32_bf16 v[8:11], v[154:157], v[196:199], v[8:11]
	s_setprio 0
	s_barrier
	s_add_u32 s42, s14, 0x160000
	s_addc_u32 s43, s15, 0
	s_add_i32 s44, s34, s20
	v_lshl_add_u64 v[136:137], s[42:43], 0, v[170:171]
	s_mov_b32 m0, s44
	s_nop 0
	global_load_lds_dwordx4 v[136:137], off
	v_lshl_add_u64 v[136:137], s[42:43], 0, v[174:175]
	s_add_i32 m0, s44, 0x2000
	s_nop 0
	global_load_lds_dwordx4 v[136:137], off
	s_waitcnt vmcnt(6)
	s_barrier
	s_setprio 1
	v_mfma_f32_16x16x32_bf16 v[52:55], v[200:203], v[158:161], v[52:55]
	v_mfma_f32_16x16x32_bf16 v[48:51], v[208:211], v[158:161], v[48:51]
	v_mfma_f32_16x16x32_bf16 v[36:39], v[200:203], v[176:179], v[36:39]
	v_mfma_f32_16x16x32_bf16 v[32:35], v[208:211], v[176:179], v[32:35]
	v_mfma_f32_16x16x32_bf16 v[20:23], v[200:203], v[184:187], v[20:23]
	v_mfma_f32_16x16x32_bf16 v[16:19], v[208:211], v[184:187], v[16:19]
	v_mfma_f32_16x16x32_bf16 v[4:7], v[200:203], v[192:195], v[4:7]
	v_mfma_f32_16x16x32_bf16 v[0:3], v[208:211], v[192:195], v[0:3]
	v_mfma_f32_16x16x32_bf16 v[52:55], v[204:207], v[164:167], v[52:55]
	v_mfma_f32_16x16x32_bf16 v[48:51], v[212:215], v[164:167], v[48:51]
	v_mfma_f32_16x16x32_bf16 v[36:39], v[204:207], v[180:183], v[36:39]
	v_mfma_f32_16x16x32_bf16 v[32:35], v[212:215], v[180:183], v[32:35]
	v_mfma_f32_16x16x32_bf16 v[20:23], v[204:207], v[188:191], v[20:23]
	v_mfma_f32_16x16x32_bf16 v[16:19], v[212:215], v[188:191], v[16:19]
	v_mfma_f32_16x16x32_bf16 v[4:7], v[204:207], v[196:199], v[4:7]
	v_mfma_f32_16x16x32_bf16 v[0:3], v[212:215], v[196:199], v[0:3]
	s_setprio 0
	s_add_i32 s42, 0, 0x18000
	v_add_u32_e32 v145, s42, v140
	s_barrier
	ds_read_b128 v[136:139], v145
	v_xor_b32_e32 v157, 64, v145
	ds_read_b128 v[146:149], v157
	ds_read_b128 v[150:153], v145 offset:2048
	ds_read_b128 v[154:157], v157 offset:2048
	s_add_u32 s16, s16, 0x160000
	s_addc_u32 s17, s17, 0
	s_mov_b32 m0, s23
	v_lshl_add_u64 v[200:201], s[16:17], 0, v[168:169]
	ds_read_b128 v[158:161], v142 offset:32768
	v_xor_b32_e32 v199, 64, v142
	ds_read_b128 v[164:167], v199 offset:32768
	ds_read_b128 v[176:179], v142 offset:34816
	ds_read_b128 v[180:183], v199 offset:34816
	ds_read_b128 v[184:187], v142 offset:36864
	ds_read_b128 v[188:191], v199 offset:36864
	ds_read_b128 v[192:195], v142 offset:38912
	ds_read_b128 v[196:199], v199 offset:38912
	global_load_lds_dwordx4 v[200:201], off
	v_lshl_add_u64 v[200:201], s[16:17], 0, v[172:173]
	s_mov_b32 m0, s24
	s_nop 0
	global_load_lds_dwordx4 v[200:201], off
	s_waitcnt lgkmcnt(8)
	s_barrier
	s_waitcnt lgkmcnt(0)
	s_setprio 1
	s_waitcnt lgkmcnt(0)
	v_mfma_f32_16x16x32_bf16 v[124:127], v[136:139], v[158:161], v[124:127]
	v_mfma_f32_16x16x32_bf16 v[120:123], v[150:153], v[158:161], v[120:123]
	v_mfma_f32_16x16x32_bf16 v[108:111], v[136:139], v[176:179], v[108:111]
	v_mfma_f32_16x16x32_bf16 v[104:107], v[150:153], v[176:179], v[104:107]
	v_mfma_f32_16x16x32_bf16 v[92:95], v[136:139], v[184:187], v[92:95]
	v_mfma_f32_16x16x32_bf16 v[88:91], v[150:153], v[184:187], v[88:91]
	v_mfma_f32_16x16x32_bf16 v[76:79], v[136:139], v[192:195], v[76:79]
	v_mfma_f32_16x16x32_bf16 v[72:75], v[150:153], v[192:195], v[72:75]
	v_mfma_f32_16x16x32_bf16 v[124:127], v[146:149], v[164:167], v[124:127]
	v_mfma_f32_16x16x32_bf16 v[120:123], v[154:157], v[164:167], v[120:123]
	v_mfma_f32_16x16x32_bf16 v[108:111], v[146:149], v[180:183], v[108:111]
	v_mfma_f32_16x16x32_bf16 v[104:107], v[154:157], v[180:183], v[104:107]
	v_mfma_f32_16x16x32_bf16 v[92:95], v[146:149], v[188:191], v[92:95]
	v_mfma_f32_16x16x32_bf16 v[88:91], v[154:157], v[188:191], v[88:91]
	v_mfma_f32_16x16x32_bf16 v[76:79], v[146:149], v[196:199], v[76:79]
	v_mfma_f32_16x16x32_bf16 v[72:75], v[154:157], v[196:199], v[72:75]
	s_setprio 0
	s_barrier
	s_add_i32 s16, 0, 0x1c000
	s_add_i32 s17, s42, s20
	v_add_u32_e32 v145, s16, v140
	v_lshl_add_u64 v[216:217], v[216:217], 0, s[12:13]
	s_mov_b32 m0, s17
	ds_read_b128 v[200:203], v145
	v_xor_b32_e32 v215, 64, v145
	ds_read_b128 v[204:207], v215
	ds_read_b128 v[208:211], v145 offset:2048
	ds_read_b128 v[212:215], v215 offset:2048
	global_load_lds_dwordx4 v[216:217], off
	v_lshl_add_u64 v[216:217], v[218:219], 0, s[12:13]
	s_add_i32 m0, s17, 0x2000
	s_nop 0
	global_load_lds_dwordx4 v[216:217], off
	s_barrier
	s_waitcnt lgkmcnt(0)
	s_setprio 1
	s_waitcnt lgkmcnt(0)
	v_mfma_f32_16x16x32_bf16 v[116:119], v[200:203], v[158:161], v[116:119]
	v_mfma_f32_16x16x32_bf16 v[112:115], v[208:211], v[158:161], v[112:115]
	v_mfma_f32_16x16x32_bf16 v[100:103], v[200:203], v[176:179], v[100:103]
	v_mfma_f32_16x16x32_bf16 v[96:99], v[208:211], v[176:179], v[96:99]
	v_mfma_f32_16x16x32_bf16 v[84:87], v[200:203], v[184:187], v[84:87]
	v_mfma_f32_16x16x32_bf16 v[80:83], v[208:211], v[184:187], v[80:83]
	v_mfma_f32_16x16x32_bf16 v[68:71], v[200:203], v[192:195], v[68:71]
	v_mfma_f32_16x16x32_bf16 v[64:67], v[208:211], v[192:195], v[64:67]
	v_mfma_f32_16x16x32_bf16 v[116:119], v[204:207], v[164:167], v[116:119]
	v_mfma_f32_16x16x32_bf16 v[112:115], v[212:215], v[164:167], v[112:115]
	v_mfma_f32_16x16x32_bf16 v[100:103], v[204:207], v[180:183], v[100:103]
	v_mfma_f32_16x16x32_bf16 v[96:99], v[212:215], v[180:183], v[96:99]
	v_mfma_f32_16x16x32_bf16 v[84:87], v[204:207], v[188:191], v[84:87]
	v_mfma_f32_16x16x32_bf16 v[80:83], v[212:215], v[188:191], v[80:83]
	v_mfma_f32_16x16x32_bf16 v[68:71], v[204:207], v[196:199], v[68:71]
	v_mfma_f32_16x16x32_bf16 v[64:67], v[212:215], v[196:199], v[64:67]
	s_setprio 0
	s_mov_b32 m0, s28
	v_lshl_add_u64 v[216:217], v[220:221], 0, s[12:13]
	s_barrier
	ds_read_b128 v[158:161], v142 offset:49152
	v_xor_b32_e32 v199, 64, v142
	ds_read_b128 v[164:167], v199 offset:49152
	ds_read_b128 v[176:179], v142 offset:51200
	ds_read_b128 v[180:183], v199 offset:51200
	ds_read_b128 v[184:187], v142 offset:53248
	ds_read_b128 v[188:191], v199 offset:53248
	ds_read_b128 v[192:195], v142 offset:55296
	ds_read_b128 v[196:199], v199 offset:55296
	global_load_lds_dwordx4 v[216:217], off
	v_lshl_add_u64 v[216:217], v[222:223], 0, s[12:13]
	s_mov_b32 m0, s29
	s_nop 0
	global_load_lds_dwordx4 v[216:217], off
	s_barrier
	s_waitcnt lgkmcnt(0)
	s_setprio 1
	s_waitcnt lgkmcnt(0)
	v_mfma_f32_16x16x32_bf16 v[60:63], v[136:139], v[158:161], v[60:63]
	v_mfma_f32_16x16x32_bf16 v[56:59], v[150:153], v[158:161], v[56:59]
	v_mfma_f32_16x16x32_bf16 v[44:47], v[136:139], v[176:179], v[44:47]
	v_mfma_f32_16x16x32_bf16 v[40:43], v[150:153], v[176:179], v[40:43]
	v_mfma_f32_16x16x32_bf16 v[28:31], v[136:139], v[184:187], v[28:31]
	v_mfma_f32_16x16x32_bf16 v[24:27], v[150:153], v[184:187], v[24:27]
	v_mfma_f32_16x16x32_bf16 v[12:15], v[136:139], v[192:195], v[12:15]
	v_mfma_f32_16x16x32_bf16 v[8:11], v[150:153], v[192:195], v[8:11]
	v_mfma_f32_16x16x32_bf16 v[60:63], v[146:149], v[164:167], v[60:63]
	v_mfma_f32_16x16x32_bf16 v[56:59], v[154:157], v[164:167], v[56:59]
	v_mfma_f32_16x16x32_bf16 v[44:47], v[146:149], v[180:183], v[44:47]
	v_mfma_f32_16x16x32_bf16 v[40:43], v[154:157], v[180:183], v[40:43]
	v_mfma_f32_16x16x32_bf16 v[28:31], v[146:149], v[188:191], v[28:31]
	v_mfma_f32_16x16x32_bf16 v[24:27], v[154:157], v[188:191], v[24:27]
	v_mfma_f32_16x16x32_bf16 v[12:15], v[146:149], v[196:199], v[12:15]
	v_mfma_f32_16x16x32_bf16 v[8:11], v[154:157], v[196:199], v[8:11]
	s_setprio 0
	s_barrier
	s_add_u32 s14, s14, 0x160080
	s_addc_u32 s15, s15, 0
	s_add_i32 s16, s16, s20
	v_lshl_add_u64 v[136:137], s[14:15], 0, v[170:171]
	s_mov_b32 m0, s16
	s_nop 0
	global_load_lds_dwordx4 v[136:137], off
	v_lshl_add_u64 v[136:137], s[14:15], 0, v[174:175]
	s_add_i32 m0, s16, 0x2000
	s_nop 0
	global_load_lds_dwordx4 v[136:137], off
	s_waitcnt vmcnt(6)
	s_barrier
	s_setprio 1
	v_mfma_f32_16x16x32_bf16 v[52:55], v[200:203], v[158:161], v[52:55]
	v_mfma_f32_16x16x32_bf16 v[48:51], v[208:211], v[158:161], v[48:51]
	v_mfma_f32_16x16x32_bf16 v[36:39], v[200:203], v[176:179], v[36:39]
	v_mfma_f32_16x16x32_bf16 v[32:35], v[208:211], v[176:179], v[32:35]
	v_mfma_f32_16x16x32_bf16 v[20:23], v[200:203], v[184:187], v[20:23]
	v_mfma_f32_16x16x32_bf16 v[16:19], v[208:211], v[184:187], v[16:19]
	v_mfma_f32_16x16x32_bf16 v[4:7], v[200:203], v[192:195], v[4:7]
	v_mfma_f32_16x16x32_bf16 v[0:3], v[208:211], v[192:195], v[0:3]
	v_mfma_f32_16x16x32_bf16 v[52:55], v[204:207], v[164:167], v[52:55]
	v_mfma_f32_16x16x32_bf16 v[48:51], v[212:215], v[164:167], v[48:51]
	v_mfma_f32_16x16x32_bf16 v[36:39], v[204:207], v[180:183], v[36:39]
	v_mfma_f32_16x16x32_bf16 v[32:35], v[212:215], v[180:183], v[32:35]
	v_mfma_f32_16x16x32_bf16 v[20:23], v[204:207], v[188:191], v[20:23]
	v_mfma_f32_16x16x32_bf16 v[16:19], v[212:215], v[188:191], v[16:19]
	v_mfma_f32_16x16x32_bf16 v[4:7], v[204:207], v[196:199], v[4:7]
	v_mfma_f32_16x16x32_bf16 v[0:3], v[212:215], v[196:199], v[0:3]
	s_setprio 0
	s_add_i32 s41, s41, 2
	s_add_u32 s0, s0, 0x100
	s_addc_u32 s1, s1, 0
	s_add_u32 s39, s39, 0x100
	s_addc_u32 s40, s40, 0
	s_cmpk_gt_u32 s41, 0x55
	s_barrier
	s_cbranch_scc0 .LBB0_985
	s_lshl_b32 s0, s38, 8
	v_mov_b32_e32 v136, v163
	v_mov_b32_e32 v145, v225
	s_add_i32 s0, s0, s26
	s_nop 0
	v_add_u32_e32 v138, s0, v136
	s_lshl_b32 s0, s37, 8
	s_or_b32 s0, s0, s27
	v_lshl_add_u32 v136, v145, 3, s0
	v_ashrrev_i32_e32 v139, 31, v138
	v_ashrrev_i32_e32 v137, 31, v136
	v_lshlrev_b64 v[146:147], 11, v[138:139]
	v_lshl_add_u64 v[150:151], v[146:147], 0, v[136:137]
	v_lshl_add_u64 v[152:153], v[150:151], 1, s[80:81]
	global_load_dwordx4 v[146:149], v[152:153], off
	v_lshl_add_u64 v[154:155], v[150:151], 2, s[90:91]
	s_waitcnt vmcnt(0)
	v_lshlrev_b32_e32 v150, 16, v146
	v_and_b32_e32 v151, 0xffff0000, v146
	v_lshlrev_b32_e32 v146, 16, v147
	v_and_b32_e32 v147, 0xffff0000, v147
	v_lshlrev_b32_e32 v156, 16, v148
	v_and_b32_e32 v157, 0xffff0000, v148
	v_lshlrev_b32_e32 v148, 16, v149
	v_and_b32_e32 v149, 0xffff0000, v149
	v_pk_add_f32 v[126:127], v[126:127], v[146:147]
	v_pk_add_f32 v[124:125], v[124:125], v[150:151]
	v_pk_add_f32 v[148:149], v[122:123], v[148:149]
	v_pk_add_f32 v[146:147], v[120:121], v[156:157]
	global_store_dwordx4 v[154:155], v[124:127], off
	global_store_dwordx4 v[154:155], v[146:149], off offset:16
	global_load_dwordx4 v[150:153], v[152:153], off offset:256
	v_mul_f32_e32 v122, v146, v146
	v_mul_f32_e32 v123, v147, v147
	v_mul_f32_e32 v146, v148, v148
	v_fmac_f32_e32 v122, v124, v124
	v_fmac_f32_e32 v123, v125, v125
	v_mul_f32_e32 v147, v149, v149
	v_fmac_f32_e32 v146, v126, v126
	v_add_f32_e32 v122, v122, v123
	v_fmac_f32_e32 v147, v127, v127
	v_add_f32_e32 v122, v146, v122
	v_add_f32_e32 v148, v147, v122
	v_and_b32_e32 v121, 64, v144
	v_xor_b32_e32 v120, 16, v144
	v_add_u32_e32 v121, 64, v121
	v_cmp_lt_i32_e32 vcc, v120, v121
	s_waitcnt vmcnt(0)
	v_lshlrev_b32_e32 v122, 16, v150
	v_and_b32_e32 v123, 0xffff0000, v150
	v_lshlrev_b32_e32 v126, 16, v152
	v_and_b32_e32 v127, 0xffff0000, v152
	v_pk_add_f32 v[116:117], v[116:117], v[122:123]
	v_pk_add_f32 v[122:123], v[112:113], v[126:127]
	v_lshlrev_b32_e32 v124, 16, v151
	v_and_b32_e32 v125, 0xffff0000, v151
	v_lshlrev_b32_e32 v146, 16, v153
	v_and_b32_e32 v147, 0xffff0000, v153
	v_mul_f32_e32 v112, v122, v122
	v_pk_add_f32 v[118:119], v[118:119], v[124:125]
	v_pk_add_f32 v[124:125], v[114:115], v[146:147]
	v_mul_f32_e32 v113, v123, v123
	v_fmac_f32_e32 v112, v116, v116
	v_mul_f32_e32 v114, v124, v124
	v_fmac_f32_e32 v113, v117, v117
	v_add_f32_e32 v112, v148, v112
	v_mul_f32_e32 v115, v125, v125
	v_fmac_f32_e32 v114, v118, v118
	v_add_f32_e32 v112, v113, v112
	v_cndmask_b32_e32 v120, v144, v120, vcc
	v_add_f32_e32 v112, v114, v112
	v_fmac_f32_e32 v115, v119, v119
	v_lshlrev_b32_e32 v120, 2, v120
	v_add_f32_e32 v112, v115, v112
	ds_bpermute_b32 v113, v120, v112
	v_xor_b32_e32 v114, 32, v144
	v_cmp_lt_i32_e32 vcc, v114, v121
	global_store_dwordx4 v[154:155], v[116:119], off offset:512
	global_store_dwordx4 v[154:155], v[122:125], off offset:528
	v_cndmask_b32_e32 v114, v144, v114, vcc
	v_lshlrev_b32_e32 v114, 2, v114
	s_waitcnt lgkmcnt(0)
	v_add_f32_e32 v112, v112, v113
	ds_bpermute_b32 v113, v114, v112
	v_cmp_eq_u32_e32 vcc, 0, v145
	s_and_saveexec_b64 s[0:1], vcc
	s_cbranch_execz .LBB0_988
	v_lshl_add_u64 v[116:117], v[138:139], 2, s[10:11]
	s_waitcnt lgkmcnt(0)
	v_add_f32_e32 v112, v112, v113
	global_atomic_add_f32 v[116:117], v112, off
